# v35 + GEMM K-loops without any s_setprio toggling (all four GEMM mainloops run at flat priority)
# speedup vs baseline: 1.0101x; 1.0022x over previous
; template <class Epi, class Sched, bool ALIGN_EPI = false, bool SP2 = false>
; __device__ __forceinline__ void gemm_phase(PG8_LAS unsigned char* lds, const Gemm g, const Sched& S, const Epi& E) {
;     ...
;     for (;;) {
;         const bool has_next = S.next(ui + 1, nxt);
;         const char* nA = has_next ? (const char*)g.A + (size_t)nxt.pm * tstep : cA; const char* nB = has_next ? (const char*)g.Bt + (size_t)nxt.pn * tstep : cB;
;         for (int t = 0; t < nt; t += 2) {
;             const bool last = (t == nt - 2);
;             const char* a1 = cA + (size_t)(t + 1) * kstep;
;             const char* a2 = last ? nA : cA + (size_t)(t + 2) * kstep; const char* b2 = last ? nB : cB + (size_t)(t + 2) * kstep;
;             const char* a3 = a2 + kstep; const char* b3 = b2 + kstep;
;             if (last && has_next) S.a_ready(nxt);
;             if constexpr (SP2) {
.LBB0_235:
	v_readfirstlane_b32 s100, v232
	s_nop 3
	s_lshr_b32 s100, s100, 6
	s_cmp_ge_u32 s100, 4
	s_cbranch_scc0 .Lgprio_skip0

; #define PG8_STAGE(bufoff, gbase, voff) do { _Pragma("unroll") for (int _i = 0; _i < 2; ++_i) \
;         __builtin_amdgcn_global_load_lds((const unsigned*)((const char*)(gbase) + (voff)[_i]), (PG8_LAS unsigned*)(lds + (bufoff) + ldsw + _i * 8192), 16, 0, 0); } while (0)
; #define PG8_LDA(dst, b, h) do { _Pragma("unroll") for (int m = 0; m < 4; ++m) _Pragma("unroll") for (int k = 0; k < 2; ++k) dst[m][k] = *(const PG8_LAS bf16x8*)(lds + PG8_SA(b, h) + aoff + m * 2048 + k * 1024); } while (0)
; #define PG8_LDB(dst, b, h) do { _Pragma("unroll") for (int n = 0; n < 2; ++n) _Pragma("unroll") for (int k = 0; k < 2; ++k) dst[n][k] = *(const PG8_LAS bf16x8*)(lds + PG8_SB(b, h) + boff + n * 2048 + k * 1024); } while (0)
; #define PG8_MMA(ai, bj, At, Bt) do { __builtin_amdgcn_s_setprio(1); _Pragma("unroll") for (int m = 0; m < 4; ++m) _Pragma("unroll") for (int n = 0; n < 2; ++n) _Pragma("unroll") for (int k = 0; k < 2; ++k) \
;         acc[ai][bj][m][n] = __builtin_amdgcn_mfma_f32_16x16x32_bf16(Bt[n][k], At[m][k], acc[ai][bj][m][n], 0, 0, 0); __builtin_amdgcn_s_setprio(0); } while (0)
; #define PG8_WAIT_V(n) asm volatile("s_waitcnt vmcnt(" #n ")" ::: "memory")
; #define PG8_WAIT_L(n) asm volatile("s_waitcnt lgkmcnt(" #n ")" ::: "memory")
; #define PG8_BAR __builtin_amdgcn_s_barrier()
; #define PG8_SCHED __builtin_amdgcn_sched_barrier(0)
; template <class Epi, class Sched, bool ALIGN_EPI = false, bool SP2 = false>
; __device__ __forceinline__ void gemm_phase(PG8_LAS unsigned char* lds, const Gemm g, const Sched& S, const Epi& E) {
;     ...
;             PG8_LDB(B0, 0, 0); PG8_LDB(B1, 0, 1); PG8_SCHED; PG8_LDA(At, 0, 0); PG8_STAGE(PG8_SA(1, 1), a1 + hstep, voffA);
;             PG8_WAIT_V(8); PG8_WAIT_L(0); PG8_BAR; PG8_MMA(0, 0, At, B0); PG8_MMA(0, 1, At, B1); PG8_BAR; PG8_SCHED;
;             PG8_LDA(At, 0, 1); PG8_STAGE(PG8_SB(0, 0), b2, voffB); PG8_STAGE(PG8_SB(0, 1), b2 + hstep, voffB); PG8_STAGE(PG8_SA(0, 0), a2, voffA);
;             PG8_WAIT_V(8); PG8_WAIT_L(0); PG8_BAR; PG8_MMA(1, 0, At, B0); PG8_MMA(1, 1, At, B1); PG8_BAR; PG8_SCHED;
.LBB0_238:
	s_add_u32 s20, s18, 0xfffc0080
	s_addc_u32 s21, s19, -1
	s_add_i32 s44, 0, 0x10000
	s_cmp_eq_u32 s43, 12
	s_cselect_b32 s23, s13, s21
	s_cselect_b32 s22, s39, s20
	s_cselect_b32 s21, s11, s42
	s_cselect_b32 s20, s40, s41
	s_add_i32 s46, 0, 0x14000
	v_add_u32_e32 v154, s44, v143
	v_add_u32_e32 v170, s46, v143
	ds_read_b128 v[138:141], v154
	ds_read_b128 v[146:149], v154 offset:1024
	ds_read_b128 v[150:153], v154 offset:2048
	ds_read_b128 v[154:157], v154 offset:3072
	ds_read_b128 v[158:161], v170
	ds_read_b128 v[162:165], v170 offset:1024
	ds_read_b128 v[166:169], v170 offset:2048
	ds_read_b128 v[170:173], v170 offset:3072
	v_lshl_add_u64 v[190:191], s[18:19], 0, v[134:135]
	s_add_i32 m0, s29, 0xc000
	ds_read_b128 v[174:177], v145
	ds_read_b128 v[178:181], v145 offset:1024
	ds_read_b128 v[182:185], v145 offset:2048
	ds_read_b128 v[186:189], v145 offset:3072
	ds_read_b128 v[206:209], v145 offset:4096
	ds_read_b128 v[210:213], v145 offset:5120
	ds_read_b128 v[214:217], v145 offset:6144
	ds_read_b128 v[218:221], v145 offset:7168
	global_load_lds_dwordx4 v[190:191], off
	v_lshl_add_u64 v[190:191], s[18:19], 0, v[136:137]
	s_add_i32 m0, s29, 0xe000
	s_nop 0
	global_load_lds_dwordx4 v[190:191], off
	s_waitcnt vmcnt(8)
	s_waitcnt lgkmcnt(0)
	s_barrier
	s_waitcnt lgkmcnt(0)
	v_mfma_f32_16x16x32_bf16 v[124:127], v[138:141], v[174:177], v[124:127]
	v_mfma_f32_16x16x32_bf16 v[120:123], v[150:153], v[174:177], v[120:123]
	v_mfma_f32_16x16x32_bf16 v[116:119], v[138:141], v[182:185], v[116:119]
	v_mfma_f32_16x16x32_bf16 v[108:111], v[150:153], v[182:185], v[108:111]
	v_mfma_f32_16x16x32_bf16 v[100:103], v[138:141], v[206:209], v[100:103]
	v_mfma_f32_16x16x32_bf16 v[92:95], v[150:153], v[206:209], v[92:95]
	v_mfma_f32_16x16x32_bf16 v[84:87], v[138:141], v[214:217], v[84:87]
	v_mfma_f32_16x16x32_bf16 v[76:79], v[150:153], v[214:217], v[76:79]
	v_mfma_f32_16x16x32_bf16 v[124:127], v[146:149], v[178:181], v[124:127]
	v_mfma_f32_16x16x32_bf16 v[120:123], v[154:157], v[178:181], v[120:123]
	v_mfma_f32_16x16x32_bf16 v[116:119], v[146:149], v[186:189], v[116:119]
	v_mfma_f32_16x16x32_bf16 v[108:111], v[154:157], v[186:189], v[108:111]
	v_mfma_f32_16x16x32_bf16 v[100:103], v[146:149], v[210:213], v[100:103]
	v_mfma_f32_16x16x32_bf16 v[92:95], v[154:157], v[210:213], v[92:95]
	v_mfma_f32_16x16x32_bf16 v[84:87], v[146:149], v[218:221], v[84:87]
	v_mfma_f32_16x16x32_bf16 v[76:79], v[154:157], v[218:221], v[76:79]
	v_mfma_f32_16x16x32_bf16 v[112:115], v[158:161], v[174:177], v[112:115]
	v_mfma_f32_16x16x32_bf16 v[104:107], v[166:169], v[174:177], v[104:107]
	v_mfma_f32_16x16x32_bf16 v[96:99], v[158:161], v[182:185], v[96:99]
	v_mfma_f32_16x16x32_bf16 v[88:91], v[166:169], v[182:185], v[88:91]
	v_mfma_f32_16x16x32_bf16 v[80:83], v[158:161], v[206:209], v[80:83]
	v_mfma_f32_16x16x32_bf16 v[72:75], v[166:169], v[206:209], v[72:75]
	v_mfma_f32_16x16x32_bf16 v[68:71], v[158:161], v[214:217], v[68:71]
	v_mfma_f32_16x16x32_bf16 v[64:67], v[166:169], v[214:217], v[64:67]
	v_mfma_f32_16x16x32_bf16 v[112:115], v[162:165], v[178:181], v[112:115]
	v_mfma_f32_16x16x32_bf16 v[104:107], v[170:173], v[178:181], v[104:107]
	v_mfma_f32_16x16x32_bf16 v[96:99], v[162:165], v[186:189], v[96:99]
	v_mfma_f32_16x16x32_bf16 v[88:91], v[170:173], v[186:189], v[88:91]
	v_mfma_f32_16x16x32_bf16 v[80:83], v[162:165], v[210:213], v[80:83]
	v_mfma_f32_16x16x32_bf16 v[72:75], v[170:173], v[210:213], v[72:75]
	v_mfma_f32_16x16x32_bf16 v[68:71], v[162:165], v[218:221], v[68:71]
	v_mfma_f32_16x16x32_bf16 v[64:67], v[170:173], v[218:221], v[64:67]
	s_barrier
	s_add_i32 s44, s44, s28
	v_lshl_add_u64 v[190:191], s[20:21], 0, v[192:193]
	s_mov_b32 m0, s44
	ds_read_b128 v[174:177], v145 offset:16384
	ds_read_b128 v[178:181], v145 offset:17408
	ds_read_b128 v[182:185], v145 offset:18432
	ds_read_b128 v[186:189], v145 offset:19456
	ds_read_b128 v[206:209], v145 offset:20480
	ds_read_b128 v[210:213], v145 offset:21504
	ds_read_b128 v[214:217], v145 offset:22528
	ds_read_b128 v[218:221], v145 offset:23552
	global_load_lds_dwordx4 v[190:191], off
	s_add_i32 m0, s44, 0x2000
	s_add_u32 s44, s20, 0x40000
	v_lshl_add_u64 v[222:223], s[20:21], 0, v[128:129]
	s_addc_u32 s45, s21, 0
	s_add_i32 s46, s46, s28
	global_load_lds_dwordx4 v[222:223], off
	v_lshl_add_u64 v[224:225], s[44:45], 0, v[192:193]
	s_mov_b32 m0, s46
	v_lshl_add_u64 v[226:227], s[22:23], 0, v[130:131]
	global_load_lds_dwordx4 v[224:225], off
	v_lshl_add_u64 v[224:225], s[44:45], 0, v[128:129]
	s_add_i32 m0, s46, 0x2000
	s_nop 0
	global_load_lds_dwordx4 v[224:225], off
	v_lshl_add_u64 v[224:225], s[22:23], 0, v[132:133]
	s_mov_b32 m0, s29
	s_nop 0
	global_load_lds_dwordx4 v[224:225], off
	s_mov_b32 m0, s30
	s_nop 0
	global_load_lds_dwordx4 v[226:227], off
	s_waitcnt vmcnt(8)
	s_waitcnt lgkmcnt(0)
	s_barrier
; #define PG8_STAGE(bufoff, gbase, voff) do { _Pragma("unroll") for (int _i = 0; _i < 2; ++_i) \
;         __builtin_amdgcn_global_load_lds((const unsigned*)((const char*)(gbase) + (voff)[_i]), (PG8_LAS unsigned*)(lds + (bufoff) + ldsw + _i * 8192), 16, 0, 0); } while (0)
; #define PG8_LDA(dst, b, h) do { _Pragma("unroll") for (int m = 0; m < 4; ++m) _Pragma("unroll") for (int k = 0; k < 2; ++k) dst[m][k] = *(const PG8_LAS bf16x8*)(lds + PG8_SA(b, h) + aoff + m * 2048 + k * 1024); } while (0)
; #define PG8_LDB(dst, b, h) do { _Pragma("unroll") for (int n = 0; n < 2; ++n) _Pragma("unroll") for (int k = 0; k < 2; ++k) dst[n][k] = *(const PG8_LAS bf16x8*)(lds + PG8_SB(b, h) + boff + n * 2048 + k * 1024); } while (0)
; #define PG8_MMA(ai, bj, At, Bt) do { __builtin_amdgcn_s_setprio(1); _Pragma("unroll") for (int m = 0; m < 4; ++m) _Pragma("unroll") for (int n = 0; n < 2; ++n) _Pragma("unroll") for (int k = 0; k < 2; ++k) \
;         acc[ai][bj][m][n] = __builtin_amdgcn_mfma_f32_16x16x32_bf16(Bt[n][k], At[m][k], acc[ai][bj][m][n], 0, 0, 0); __builtin_amdgcn_s_setprio(0); } while (0)
; #define PG8_WAIT_V(n) asm volatile("s_waitcnt vmcnt(" #n ")" ::: "memory")
; #define PG8_WAIT_L(n) asm volatile("s_waitcnt lgkmcnt(" #n ")" ::: "memory")
; #define PG8_BAR __builtin_amdgcn_s_barrier()
; #define PG8_SCHED __builtin_amdgcn_sched_barrier(0)
; template <class Epi, class Sched, bool ALIGN_EPI = false, bool SP2 = false>
; __device__ __forceinline__ void gemm_phase(PG8_LAS unsigned char* lds, const Gemm g, const Sched& S, const Epi& E) {
;     ...
;             PG8_WAIT_V(8); PG8_WAIT_L(0); PG8_BAR; PG8_MMA(1, 0, At, B0); PG8_MMA(1, 1, At, B1); PG8_BAR; PG8_SCHED;
;             PG8_LDB(B0, 1, 0); PG8_LDB(B1, 1, 1); PG8_SCHED; PG8_LDA(At, 1, 0); PG8_STAGE(PG8_SA(0, 1), a2 + hstep, voffA);
;             PG8_WAIT_V(8); PG8_WAIT_L(0); PG8_BAR; PG8_MMA(0, 0, At, B0); PG8_MMA(0, 1, At, B1); PG8_BAR; PG8_SCHED;
	s_waitcnt lgkmcnt(0)
	v_mfma_f32_16x16x32_bf16 v[60:63], v[138:141], v[174:177], v[60:63]
	v_mfma_f32_16x16x32_bf16 v[56:59], v[150:153], v[174:177], v[56:59]
	v_mfma_f32_16x16x32_bf16 v[52:55], v[138:141], v[182:185], v[52:55]
	v_mfma_f32_16x16x32_bf16 v[44:47], v[150:153], v[182:185], v[44:47]
	v_mfma_f32_16x16x32_bf16 v[36:39], v[138:141], v[206:209], v[36:39]
	v_mfma_f32_16x16x32_bf16 v[28:31], v[150:153], v[206:209], v[28:31]
	v_mfma_f32_16x16x32_bf16 v[20:23], v[138:141], v[214:217], v[20:23]
	v_mfma_f32_16x16x32_bf16 v[12:15], v[150:153], v[214:217], v[12:15]
	v_mfma_f32_16x16x32_bf16 v[60:63], v[146:149], v[178:181], v[60:63]
	v_mfma_f32_16x16x32_bf16 v[56:59], v[154:157], v[178:181], v[56:59]
	v_mfma_f32_16x16x32_bf16 v[52:55], v[146:149], v[186:189], v[52:55]
	v_mfma_f32_16x16x32_bf16 v[44:47], v[154:157], v[186:189], v[44:47]
	v_mfma_f32_16x16x32_bf16 v[36:39], v[146:149], v[210:213], v[36:39]
	v_mfma_f32_16x16x32_bf16 v[28:31], v[154:157], v[210:213], v[28:31]
	v_mfma_f32_16x16x32_bf16 v[20:23], v[146:149], v[218:221], v[20:23]
	v_mfma_f32_16x16x32_bf16 v[12:15], v[154:157], v[218:221], v[12:15]
	v_mfma_f32_16x16x32_bf16 v[48:51], v[158:161], v[174:177], v[48:51]
	v_mfma_f32_16x16x32_bf16 v[40:43], v[166:169], v[174:177], v[40:43]
	v_mfma_f32_16x16x32_bf16 v[32:35], v[158:161], v[182:185], v[32:35]
	v_mfma_f32_16x16x32_bf16 v[24:27], v[166:169], v[182:185], v[24:27]
	v_mfma_f32_16x16x32_bf16 v[16:19], v[158:161], v[206:209], v[16:19]
	v_mfma_f32_16x16x32_bf16 v[8:11], v[166:169], v[206:209], v[8:11]
	v_mfma_f32_16x16x32_bf16 v[4:7], v[158:161], v[214:217], v[4:7]
	v_mfma_f32_16x16x32_bf16 v[0:3], v[166:169], v[214:217], v[0:3]
	v_mfma_f32_16x16x32_bf16 v[48:51], v[162:165], v[178:181], v[48:51]
	v_mfma_f32_16x16x32_bf16 v[40:43], v[170:173], v[178:181], v[40:43]
	v_mfma_f32_16x16x32_bf16 v[32:35], v[162:165], v[186:189], v[32:35]
	v_mfma_f32_16x16x32_bf16 v[24:27], v[170:173], v[186:189], v[24:27]
	v_mfma_f32_16x16x32_bf16 v[16:19], v[162:165], v[210:213], v[16:19]
	v_mfma_f32_16x16x32_bf16 v[8:11], v[170:173], v[210:213], v[8:11]
	v_mfma_f32_16x16x32_bf16 v[4:7], v[162:165], v[218:221], v[4:7]
	v_mfma_f32_16x16x32_bf16 v[0:3], v[170:173], v[218:221], v[0:3]
	s_barrier
	s_add_i32 s44, 0, 0x18000
	s_add_i32 s45, 0, 0x1c000
	v_add_u32_e32 v154, s44, v143
	v_add_u32_e32 v170, s45, v143
	ds_read_b128 v[138:141], v154
	ds_read_b128 v[146:149], v154 offset:1024
	ds_read_b128 v[150:153], v154 offset:2048
	ds_read_b128 v[154:157], v154 offset:3072
	ds_read_b128 v[158:161], v170
	ds_read_b128 v[162:165], v170 offset:1024
	ds_read_b128 v[166:169], v170 offset:2048
	ds_read_b128 v[170:173], v170 offset:3072
	s_add_u32 s22, s22, 0x40000
	s_addc_u32 s23, s23, 0
	s_mov_b32 m0, s31
	v_lshl_add_u64 v[228:229], s[22:23], 0, v[132:133]
	ds_read_b128 v[174:177], v145 offset:32768
	ds_read_b128 v[178:181], v145 offset:33792
	ds_read_b128 v[182:185], v145 offset:34816
	ds_read_b128 v[186:189], v145 offset:35840
	ds_read_b128 v[206:209], v145 offset:36864
	ds_read_b128 v[210:213], v145 offset:37888
	ds_read_b128 v[214:217], v145 offset:38912
	ds_read_b128 v[218:221], v145 offset:39936
	global_load_lds_dwordx4 v[228:229], off
	v_lshl_add_u64 v[228:229], s[22:23], 0, v[130:131]
	s_mov_b32 m0, s33
	s_nop 0
	global_load_lds_dwordx4 v[228:229], off
	s_waitcnt vmcnt(8)
	s_waitcnt lgkmcnt(0)
	s_barrier
	s_waitcnt lgkmcnt(0)
	v_mfma_f32_16x16x32_bf16 v[124:127], v[138:141], v[174:177], v[124:127]
	v_mfma_f32_16x16x32_bf16 v[120:123], v[150:153], v[174:177], v[120:123]
	v_mfma_f32_16x16x32_bf16 v[116:119], v[138:141], v[182:185], v[116:119]
	v_mfma_f32_16x16x32_bf16 v[108:111], v[150:153], v[182:185], v[108:111]
	v_mfma_f32_16x16x32_bf16 v[100:103], v[138:141], v[206:209], v[100:103]
	v_mfma_f32_16x16x32_bf16 v[92:95], v[150:153], v[206:209], v[92:95]
	v_mfma_f32_16x16x32_bf16 v[84:87], v[138:141], v[214:217], v[84:87]
	v_mfma_f32_16x16x32_bf16 v[76:79], v[150:153], v[214:217], v[76:79]
	v_mfma_f32_16x16x32_bf16 v[124:127], v[146:149], v[178:181], v[124:127]
	v_mfma_f32_16x16x32_bf16 v[120:123], v[154:157], v[178:181], v[120:123]
	v_mfma_f32_16x16x32_bf16 v[116:119], v[146:149], v[186:189], v[116:119]
	v_mfma_f32_16x16x32_bf16 v[108:111], v[154:157], v[186:189], v[108:111]
	v_mfma_f32_16x16x32_bf16 v[100:103], v[146:149], v[210:213], v[100:103]
	v_mfma_f32_16x16x32_bf16 v[92:95], v[154:157], v[210:213], v[92:95]
	v_mfma_f32_16x16x32_bf16 v[84:87], v[146:149], v[218:221], v[84:87]
	v_mfma_f32_16x16x32_bf16 v[76:79], v[154:157], v[218:221], v[76:79]
	v_mfma_f32_16x16x32_bf16 v[112:115], v[158:161], v[174:177], v[112:115]
	v_mfma_f32_16x16x32_bf16 v[104:107], v[166:169], v[174:177], v[104:107]
	v_mfma_f32_16x16x32_bf16 v[96:99], v[158:161], v[182:185], v[96:99]
	v_mfma_f32_16x16x32_bf16 v[88:91], v[166:169], v[182:185], v[88:91]
	v_mfma_f32_16x16x32_bf16 v[80:83], v[158:161], v[206:209], v[80:83]
	v_mfma_f32_16x16x32_bf16 v[72:75], v[166:169], v[206:209], v[72:75]
	v_mfma_f32_16x16x32_bf16 v[68:71], v[158:161], v[214:217], v[68:71]
	v_mfma_f32_16x16x32_bf16 v[64:67], v[166:169], v[214:217], v[64:67]
	v_mfma_f32_16x16x32_bf16 v[112:115], v[162:165], v[178:181], v[112:115]
	v_mfma_f32_16x16x32_bf16 v[104:107], v[170:173], v[178:181], v[104:107]
	v_mfma_f32_16x16x32_bf16 v[96:99], v[162:165], v[186:189], v[96:99]
	v_mfma_f32_16x16x32_bf16 v[88:91], v[170:173], v[186:189], v[88:91]
	v_mfma_f32_16x16x32_bf16 v[80:83], v[162:165], v[210:213], v[80:83]
	v_mfma_f32_16x16x32_bf16 v[72:75], v[170:173], v[210:213], v[72:75]
	v_mfma_f32_16x16x32_bf16 v[68:71], v[162:165], v[218:221], v[68:71]
	v_mfma_f32_16x16x32_bf16 v[64:67], v[170:173], v[218:221], v[64:67]
	s_barrier
; #define PG8_STAGE(bufoff, gbase, voff) do { _Pragma("unroll") for (int _i = 0; _i < 2; ++_i) \
;         __builtin_amdgcn_global_load_lds((const unsigned*)((const char*)(gbase) + (voff)[_i]), (PG8_LAS unsigned*)(lds + (bufoff) + ldsw + _i * 8192), 16, 0, 0); } while (0)
; #define PG8_LDA(dst, b, h) do { _Pragma("unroll") for (int m = 0; m < 4; ++m) _Pragma("unroll") for (int k = 0; k < 2; ++k) dst[m][k] = *(const PG8_LAS bf16x8*)(lds + PG8_SA(b, h) + aoff + m * 2048 + k * 1024); } while (0)
; #define PG8_LDB(dst, b, h) do { _Pragma("unroll") for (int n = 0; n < 2; ++n) _Pragma("unroll") for (int k = 0; k < 2; ++k) dst[n][k] = *(const PG8_LAS bf16x8*)(lds + PG8_SB(b, h) + boff + n * 2048 + k * 1024); } while (0)
; template <class Epi, class Sched, bool ALIGN_EPI = false, bool SP2 = false>
; __device__ __forceinline__ void gemm_phase(PG8_LAS unsigned char* lds, const Gemm g, const Sched& S, const Epi& E) {
;     ...
;         for (int t = 0; t < nt; t += 2) {
;             const bool last = (t == nt - 2);
;             const char* a1 = cA + (size_t)(t + 1) * kstep;
;             const char* a2 = last ? nA : cA + (size_t)(t + 2) * kstep; const char* b2 = last ? nB : cB + (size_t)(t + 2) * kstep;
;             const char* a3 = a2 + kstep; const char* b3 = b2 + kstep;
;             if (last && has_next) S.a_ready(nxt);
;             if constexpr (SP2) {
;             PG8_LDB(B0, 0, 0); PG8_LDB(B1, 0, 1); PG8_SCHED; PG8_LDA(At, 0, 0); PG8_STAGE(PG8_SA(1, 1), a1 + hstep, voffA);
;             PG8_WAIT_V(8); PG8_WAIT_L(0); PG8_BAR; PG8_MMA(0, 0, At, B0); PG8_MMA(0, 1, At, B1); PG8_BAR; PG8_SCHED;
;             PG8_LDA(At, 0, 1); PG8_STAGE(PG8_SB(0, 0), b2, voffB); PG8_STAGE(PG8_SB(0, 1), b2 + hstep, voffB); PG8_STAGE(PG8_SA(0, 0), a2, voffA);
;             PG8_WAIT_V(8); PG8_WAIT_L(0); PG8_BAR; PG8_MMA(1, 0, At, B0); PG8_MMA(1, 1, At, B1); PG8_BAR; PG8_SCHED;
;             PG8_LDB(B0, 1, 0); PG8_LDB(B1, 1, 1); PG8_SCHED; PG8_LDA(At, 1, 0); PG8_STAGE(PG8_SA(0, 1), a2 + hstep, voffA);
;             PG8_WAIT_V(8); PG8_WAIT_L(0); PG8_BAR; PG8_MMA(0, 0, At, B0); PG8_MMA(0, 1, At, B1); PG8_BAR; PG8_SCHED;
;             PG8_LDA(At, 1, 1); PG8_STAGE(PG8_SB(1, 0), b3, voffB); PG8_STAGE(PG8_SB(1, 1), b3 + hstep, voffB); PG8_STAGE(PG8_SA(1, 0), a3, voffA);
;             PG8_WAIT_V(8); PG8_WAIT_L(0); PG8_BAR; PG8_MMA(1, 0, At, B0); PG8_MMA(1, 1, At, B1); PG8_BAR; PG8_SCHED;
	s_add_i32 s22, s44, s28
	v_lshl_add_u64 v[190:191], v[190:191], 0, s[72:73]
	s_mov_b32 m0, s22
	ds_read_b128 v[174:177], v145 offset:49152
	ds_read_b128 v[178:181], v145 offset:50176
	ds_read_b128 v[182:185], v145 offset:51200
	ds_read_b128 v[186:189], v145 offset:52224
	ds_read_b128 v[206:209], v145 offset:53248
	ds_read_b128 v[210:213], v145 offset:54272
	ds_read_b128 v[214:217], v145 offset:55296
	ds_read_b128 v[218:221], v145 offset:56320
	global_load_lds_dwordx4 v[190:191], off
	s_add_i32 m0, s22, 0x2000
	s_add_u32 s20, s20, 0x40080
	v_lshl_add_u64 v[190:191], v[222:223], 0, s[72:73]
	s_addc_u32 s21, s21, 0
	s_add_i32 s22, s45, s28
	global_load_lds_dwordx4 v[190:191], off
	v_lshl_add_u64 v[190:191], s[20:21], 0, v[192:193]
	s_mov_b32 m0, s22
	s_nop 0
	global_load_lds_dwordx4 v[190:191], off
	v_lshl_add_u64 v[190:191], s[20:21], 0, v[128:129]
	s_add_i32 m0, s22, 0x2000
	s_nop 0
	global_load_lds_dwordx4 v[190:191], off
	v_lshl_add_u64 v[190:191], v[224:225], 0, s[72:73]
	s_mov_b32 m0, s34
	s_nop 0
	global_load_lds_dwordx4 v[190:191], off
	v_lshl_add_u64 v[190:191], v[226:227], 0, s[72:73]
	s_mov_b32 m0, s35
	s_nop 0
	global_load_lds_dwordx4 v[190:191], off
	s_waitcnt vmcnt(8)
	s_waitcnt lgkmcnt(0)
	s_barrier
	s_waitcnt lgkmcnt(0)
	v_mfma_f32_16x16x32_bf16 v[60:63], v[138:141], v[174:177], v[60:63]
	v_mfma_f32_16x16x32_bf16 v[56:59], v[150:153], v[174:177], v[56:59]
	v_mfma_f32_16x16x32_bf16 v[52:55], v[138:141], v[182:185], v[52:55]
	v_mfma_f32_16x16x32_bf16 v[44:47], v[150:153], v[182:185], v[44:47]
	v_mfma_f32_16x16x32_bf16 v[36:39], v[138:141], v[206:209], v[36:39]
	v_mfma_f32_16x16x32_bf16 v[28:31], v[150:153], v[206:209], v[28:31]
	v_mfma_f32_16x16x32_bf16 v[20:23], v[138:141], v[214:217], v[20:23]
	v_mfma_f32_16x16x32_bf16 v[12:15], v[150:153], v[214:217], v[12:15]
	v_mfma_f32_16x16x32_bf16 v[60:63], v[146:149], v[178:181], v[60:63]
	v_mfma_f32_16x16x32_bf16 v[56:59], v[154:157], v[178:181], v[56:59]
	v_mfma_f32_16x16x32_bf16 v[52:55], v[146:149], v[186:189], v[52:55]
	v_mfma_f32_16x16x32_bf16 v[44:47], v[154:157], v[186:189], v[44:47]
	v_mfma_f32_16x16x32_bf16 v[36:39], v[146:149], v[210:213], v[36:39]
	v_mfma_f32_16x16x32_bf16 v[28:31], v[154:157], v[210:213], v[28:31]
	v_mfma_f32_16x16x32_bf16 v[20:23], v[146:149], v[218:221], v[20:23]
	v_mfma_f32_16x16x32_bf16 v[12:15], v[154:157], v[218:221], v[12:15]
	v_mfma_f32_16x16x32_bf16 v[48:51], v[158:161], v[174:177], v[48:51]
	v_mfma_f32_16x16x32_bf16 v[40:43], v[166:169], v[174:177], v[40:43]
	v_mfma_f32_16x16x32_bf16 v[32:35], v[158:161], v[182:185], v[32:35]
	v_mfma_f32_16x16x32_bf16 v[24:27], v[166:169], v[182:185], v[24:27]
	v_mfma_f32_16x16x32_bf16 v[16:19], v[158:161], v[206:209], v[16:19]
	v_mfma_f32_16x16x32_bf16 v[8:11], v[166:169], v[206:209], v[8:11]
	v_mfma_f32_16x16x32_bf16 v[4:7], v[158:161], v[214:217], v[4:7]
	v_mfma_f32_16x16x32_bf16 v[0:3], v[166:169], v[214:217], v[0:3]
	v_mfma_f32_16x16x32_bf16 v[48:51], v[162:165], v[178:181], v[48:51]
	v_mfma_f32_16x16x32_bf16 v[40:43], v[170:173], v[178:181], v[40:43]
	v_mfma_f32_16x16x32_bf16 v[32:35], v[162:165], v[186:189], v[32:35]
	v_mfma_f32_16x16x32_bf16 v[24:27], v[170:173], v[186:189], v[24:27]
	v_mfma_f32_16x16x32_bf16 v[16:19], v[162:165], v[210:213], v[16:19]
	v_mfma_f32_16x16x32_bf16 v[8:11], v[170:173], v[210:213], v[8:11]
	v_mfma_f32_16x16x32_bf16 v[4:7], v[162:165], v[218:221], v[4:7]
	v_mfma_f32_16x16x32_bf16 v[0:3], v[170:173], v[218:221], v[0:3]
	s_barrier
	s_add_i32 s43, s43, 2
	s_add_u32 s18, s18, 0x100
	s_addc_u32 s19, s19, 0
	s_add_u32 s41, s41, 0x100
	s_addc_u32 s42, s42, 0
	s_cmp_gt_u32 s43, 13
	s_cbranch_scc0 .LBB0_238
	s_and_b64 vcc, exec, s[8:9]
	s_cbranch_vccz .LBB0_241
	s_barrier
; __device__ __forceinline__ unsigned cvt_pk_bf16(float lo, float hi) { unsigned r; asm volatile("v_cvt_pk_bf16_f32 %0, %1, %2" : "=v"(r) : "v"(lo), "v"(hi)); return r; }
;     DI void operator()(const pg8::f32x4 (&acc)[2][2][4][2], const pg8::Unit& u, int wr, int wc, int fr, int fq) const {
;         const int row0 = u.pm * 256 + wr * 64 + fr, col0 = u.pn * 256 + wc * 32 + 8 * fq;
; #pragma unroll
;         for (int ai = 0; ai < 2; ++ai)
; #pragma unroll
;             for (int m = 0; m < 4; ++m) { bf16* rowp = O + (size_t)(row0 + ai * 128 + m * 16) * ldc + col0;
; #pragma unroll
;                 for (int bj = 0; bj < 2; ++bj) { const pg8::f32x4 v0 = acc[ai][bj][m][0], v1 = acc[ai][bj][m][1];
;                     v4u w; w.x = pg8::cvt_pk_bf16(v0[0], v0[1]); w.y = pg8::cvt_pk_bf16(v0[2], v0[3]); w.z = pg8::cvt_pk_bf16(v1[0], v1[1]); w.w = pg8::cvt_pk_bf16(v1[2], v1[3]);
;                     *(v4u*)(rowp + bj * 128) = w; } }
; __device__ __forceinline__ void xcd_barrier(const XcdBarrier& b) {
;     asm volatile("s_waitcnt vmcnt(0)" ::: "memory");
;     __syncthreads();
;     if (threadIdx.x == 0) {
;         unsigned* bar = b.bar;
;         __builtin_amdgcn_s_waitcnt(0);
;         unsigned nloc = b.st[0], nx = b.st[1];
;         if (nloc == 0u) { xcd_barrier_complete(bar, b.x, nloc, nx); b.st[0] = nloc; b.st[1] = nx; }
.LBB0_241:
	v_lshl_or_b32 v140, s37, 8, v144
	v_lshl_add_u32 v148, s38, 8, v142
	v_ashrrev_i32_e32 v141, 31, v140
	v_mov_b64_e32 v[138:139], s[4:5]
	s_movk_i32 s11, 0x1c00
	v_mad_i64_i32 v[146:147], s[18:19], v148, s11, v[138:139]
	v_lshlrev_b64 v[140:141], 1, v[140:141]
	v_lshl_add_u64 v[146:147], v[146:147], 0, v[140:141]
	v_cvt_pk_bf16_f32 v124, v124, v125
	v_cvt_pk_bf16_f32 v125, v126, v127
	v_cvt_pk_bf16_f32 v126, v120, v121
	v_cvt_pk_bf16_f32 v127, v122, v123
	global_store_dwordx4 v[146:147], v[124:127], off
	v_cvt_pk_bf16_f32 v112, v112, v113
	v_cvt_pk_bf16_f32 v113, v114, v115
	v_cvt_pk_bf16_f32 v114, v104, v105
	v_or_b32_e32 v104, 16, v148
	v_mad_i64_i32 v[104:105], s[18:19], v104, s11, v[138:139]
	v_cvt_pk_bf16_f32 v115, v106, v107
	global_store_dwordx4 v[146:147], v[112:115], off offset:256
	s_andn2_b64 vcc, exec, s[0:1]
	s_mov_b64 s[0:1], -1
	v_lshl_add_u64 v[112:113], v[104:105], 0, v[140:141]
	v_cvt_pk_bf16_f32 v104, v116, v117
	v_cvt_pk_bf16_f32 v105, v118, v119
	v_cvt_pk_bf16_f32 v106, v108, v109
	v_cvt_pk_bf16_f32 v107, v110, v111
	global_store_dwordx4 v[112:113], v[104:107], off
	v_cvt_pk_bf16_f32 v96, v96, v97
	v_cvt_pk_bf16_f32 v97, v98, v99
	v_cvt_pk_bf16_f32 v98, v88, v89
	v_or_b32_e32 v88, 32, v148
	v_mad_i64_i32 v[88:89], s[18:19], v88, s11, v[138:139]
	v_cvt_pk_bf16_f32 v99, v90, v91
	global_store_dwordx4 v[112:113], v[96:99], off offset:256
	s_nop 1
	v_lshl_add_u64 v[96:97], v[88:89], 0, v[140:141]
	v_cvt_pk_bf16_f32 v88, v100, v101
	v_cvt_pk_bf16_f32 v89, v102, v103
	v_cvt_pk_bf16_f32 v90, v92, v93
	v_cvt_pk_bf16_f32 v91, v94, v95
	global_store_dwordx4 v[96:97], v[88:91], off
	v_cvt_pk_bf16_f32 v80, v80, v81
	v_cvt_pk_bf16_f32 v81, v82, v83
	v_cvt_pk_bf16_f32 v82, v72, v73
	v_or_b32_e32 v72, 48, v148
	v_mad_i64_i32 v[72:73], s[18:19], v72, s11, v[138:139]
	v_cvt_pk_bf16_f32 v83, v74, v75
	global_store_dwordx4 v[96:97], v[80:83], off offset:256
	s_nop 1
	v_lshl_add_u64 v[80:81], v[72:73], 0, v[140:141]
	v_cvt_pk_bf16_f32 v72, v84, v85
	v_cvt_pk_bf16_f32 v73, v86, v87
	v_cvt_pk_bf16_f32 v74, v76, v77
	v_cvt_pk_bf16_f32 v75, v78, v79
	global_store_dwordx4 v[80:81], v[72:75], off
	v_cvt_pk_bf16_f32 v68, v68, v69
	v_cvt_pk_bf16_f32 v69, v70, v71
	v_cvt_pk_bf16_f32 v70, v64, v65
	v_add_u32_e32 v64, 0x80, v148
	v_mad_i64_i32 v[64:65], s[18:19], v64, s11, v[138:139]
	v_lshl_add_u64 v[64:65], v[64:65], 0, v[140:141]
	v_cvt_pk_bf16_f32 v71, v66, v67
	global_store_dwordx4 v[80:81], v[68:71], off offset:256
	v_cvt_pk_bf16_f32 v60, v60, v61
	v_cvt_pk_bf16_f32 v61, v62, v63
	v_cvt_pk_bf16_f32 v62, v56, v57
	v_cvt_pk_bf16_f32 v63, v58, v59
	global_store_dwordx4 v[64:65], v[60:63], off
	v_cvt_pk_bf16_f32 v48, v48, v49
	v_cvt_pk_bf16_f32 v49, v50, v51
	v_cvt_pk_bf16_f32 v50, v40, v41
	v_add_u32_e32 v40, 0x90, v148
	v_mad_i64_i32 v[40:41], s[18:19], v40, s11, v[138:139]
	v_cvt_pk_bf16_f32 v51, v42, v43
	global_store_dwordx4 v[64:65], v[48:51], off offset:256
	s_nop 1
	v_lshl_add_u64 v[48:49], v[40:41], 0, v[140:141]
	v_cvt_pk_bf16_f32 v40, v52, v53
	v_cvt_pk_bf16_f32 v41, v54, v55
	v_cvt_pk_bf16_f32 v42, v44, v45
	v_cvt_pk_bf16_f32 v43, v46, v47
	global_store_dwordx4 v[48:49], v[40:43], off
	v_cvt_pk_bf16_f32 v32, v32, v33
	v_cvt_pk_bf16_f32 v33, v34, v35
	v_cvt_pk_bf16_f32 v34, v24, v25
	v_add_u32_e32 v24, 0xa0, v148
	v_mad_i64_i32 v[24:25], s[18:19], v24, s11, v[138:139]
	v_cvt_pk_bf16_f32 v35, v26, v27
	global_store_dwordx4 v[48:49], v[32:35], off offset:256
	s_nop 1
	v_lshl_add_u64 v[32:33], v[24:25], 0, v[140:141]
	v_cvt_pk_bf16_f32 v24, v36, v37
	v_cvt_pk_bf16_f32 v25, v38, v39
	v_cvt_pk_bf16_f32 v26, v28, v29
	v_cvt_pk_bf16_f32 v27, v30, v31
	global_store_dwordx4 v[32:33], v[24:27], off
	v_cvt_pk_bf16_f32 v16, v16, v17
	v_cvt_pk_bf16_f32 v17, v18, v19
	v_cvt_pk_bf16_f32 v18, v8, v9
	v_add_u32_e32 v8, 0xb0, v148
	v_mad_i64_i32 v[8:9], s[18:19], v8, s11, v[138:139]
	v_cvt_pk_bf16_f32 v19, v10, v11
	global_store_dwordx4 v[32:33], v[16:19], off offset:256
	s_nop 1
	v_lshl_add_u64 v[16:17], v[8:9], 0, v[140:141]
	v_cvt_pk_bf16_f32 v8, v20, v21
	v_cvt_pk_bf16_f32 v9, v22, v23
	v_cvt_pk_bf16_f32 v10, v12, v13
	v_cvt_pk_bf16_f32 v11, v14, v15
	global_store_dwordx4 v[16:17], v[8:11], off
	v_cvt_pk_bf16_f32 v4, v4, v5
	v_cvt_pk_bf16_f32 v5, v6, v7
	v_cvt_pk_bf16_f32 v6, v0, v1
	v_cvt_pk_bf16_f32 v7, v2, v3
	global_store_dwordx4 v[16:17], v[4:7], off offset:256
	s_cbranch_vccnz .LBB0_234
	s_andn2_b64 vcc, exec, s[2:3]
	s_cbranch_vccnz .LBB0_233
	s_barrier
	s_branch .LBB0_233
.LBB0_244:
	s_setprio 0
	s_waitcnt vmcnt(0)
	s_barrier
.LBB0_245:
	s_waitcnt vmcnt(0)
	s_waitcnt vmcnt(0)
	s_barrier
	s_mov_b64 s[0:1], exec
	v_readlane_b32 s2, v252, 4
	v_readlane_b32 s3, v252, 5
	s_and_b64 s[2:3], s[0:1], s[2:3]
	s_mov_b64 exec, s[2:3]
	s_cbranch_execz .LBB0_297
	v_readlane_b32 s2, v254, 4
	s_waitcnt vmcnt(0) expcnt(0) lgkmcnt(0)
	s_nop 0
	v_mov_b32_e32 v0, s2
	ds_read_b32 v2, v0
	v_readlane_b32 s2, v254, 5
	s_waitcnt lgkmcnt(0)
	v_cmp_ne_u32_e32 vcc, 0, v2
	v_mov_b32_e32 v0, s2
	ds_read_b32 v0, v0
	s_cbranch_vccnz .LBB0_261
	s_mov_b32 s10, 1
	s_branch .LBB0_249

; #define PG8_STAGE(bufoff, gbase, voff) do { _Pragma("unroll") for (int _i = 0; _i < 2; ++_i) \
;         __builtin_amdgcn_global_load_lds((const unsigned*)((const char*)(gbase) + (voff)[_i]), (PG8_LAS unsigned*)(lds + (bufoff) + ldsw + _i * 8192), 16, 0, 0); } while (0)
; #define PG8_LDA(dst, b, h) do { _Pragma("unroll") for (int m = 0; m < 4; ++m) _Pragma("unroll") for (int k = 0; k < 2; ++k) dst[m][k] = *(const PG8_LAS bf16x8*)(lds + PG8_SA(b, h) + aoff + m * 2048 + k * 1024); } while (0)
; #define PG8_LDB(dst, b, h) do { _Pragma("unroll") for (int n = 0; n < 2; ++n) _Pragma("unroll") for (int k = 0; k < 2; ++k) dst[n][k] = *(const PG8_LAS bf16x8*)(lds + PG8_SB(b, h) + boff + n * 2048 + k * 1024); } while (0)
; #define PG8_MMA(ai, bj, At, Bt) do { __builtin_amdgcn_s_setprio(1); _Pragma("unroll") for (int m = 0; m < 4; ++m) _Pragma("unroll") for (int n = 0; n < 2; ++n) _Pragma("unroll") for (int k = 0; k < 2; ++k) \
;         acc[ai][bj][m][n] = __builtin_amdgcn_mfma_f32_16x16x32_bf16(Bt[n][k], At[m][k], acc[ai][bj][m][n], 0, 0, 0); __builtin_amdgcn_s_setprio(0); } while (0)
; #define PG8_WAIT_V(n) asm volatile("s_waitcnt vmcnt(" #n ")" ::: "memory")
; #define PG8_WAIT_L(n) asm volatile("s_waitcnt lgkmcnt(" #n ")" ::: "memory")
; #define PG8_BAR __builtin_amdgcn_s_barrier()
; #define PG8_SCHED __builtin_amdgcn_sched_barrier(0)
; template <class Epi, class Sched, bool ALIGN_EPI = false, bool SP2 = false>
; __device__ __forceinline__ void gemm_phase(PG8_LAS unsigned char* lds, const Gemm g, const Sched& S, const Epi& E) {
;     ...
;             PG8_LDB(B0, 0, 0); PG8_LDB(B1, 0, 1); PG8_SCHED; PG8_LDA(At, 0, 0); PG8_STAGE(PG8_SA(1, 1), a1 + hstep, voffA);
;             PG8_WAIT_V(8); PG8_WAIT_L(0); PG8_BAR; PG8_MMA(0, 0, At, B0); PG8_MMA(0, 1, At, B1); PG8_BAR; PG8_SCHED;
;             PG8_LDA(At, 0, 1); PG8_STAGE(PG8_SB(0, 0), b2, voffB); PG8_STAGE(PG8_SB(0, 1), b2 + hstep, voffB); PG8_STAGE(PG8_SA(0, 0), a2, voffA);
;             PG8_WAIT_V(8); PG8_WAIT_L(0); PG8_BAR; PG8_MMA(1, 0, At, B0); PG8_MMA(1, 1, At, B1); PG8_BAR; PG8_SCHED;
.LBB0_1051:
	s_add_u32 s18, s16, 0xfffc0080
	s_addc_u32 s19, s17, -1
	s_add_i32 s46, 0, 0x10000
	s_cmp_eq_u32 s45, 12
	s_cselect_b32 s21, s11, s19
	s_cselect_b32 s20, s37, s18
	s_cselect_b32 s19, s9, s44
	s_cselect_b32 s18, s38, s39
	s_add_i32 s48, 0, 0x14000
	v_add_u32_e32 v150, s46, v159
	v_add_u32_e32 v170, s48, v159
	ds_read_b128 v[128:131], v150
	ds_read_b128 v[132:135], v150 offset:1024
	ds_read_b128 v[136:139], v150 offset:2048
	ds_read_b128 v[150:153], v150 offset:3072
	ds_read_b128 v[154:157], v170
	ds_read_b128 v[162:165], v170 offset:1024
	ds_read_b128 v[166:169], v170 offset:2048
	ds_read_b128 v[170:173], v170 offset:3072
	v_lshl_add_u64 v[190:191], s[16:17], 0, v[146:147]
	s_add_i32 m0, s27, 0xc000
	ds_read_b128 v[174:177], v161
	ds_read_b128 v[178:181], v161 offset:1024
	ds_read_b128 v[182:185], v161 offset:2048
	ds_read_b128 v[186:189], v161 offset:3072
	ds_read_b128 v[206:209], v161 offset:4096
	ds_read_b128 v[210:213], v161 offset:5120
	ds_read_b128 v[214:217], v161 offset:6144
	ds_read_b128 v[218:221], v161 offset:7168
	global_load_lds_dwordx4 v[190:191], off
	v_lshl_add_u64 v[190:191], s[16:17], 0, v[148:149]
	s_add_i32 m0, s27, 0xe000
	s_nop 0
	global_load_lds_dwordx4 v[190:191], off
	s_waitcnt vmcnt(8)
	s_waitcnt lgkmcnt(0)
	s_barrier
	s_waitcnt lgkmcnt(0)
	v_mfma_f32_16x16x32_bf16 v[124:127], v[128:131], v[174:177], v[124:127]
	v_mfma_f32_16x16x32_bf16 v[120:123], v[136:139], v[174:177], v[120:123]
	v_mfma_f32_16x16x32_bf16 v[116:119], v[128:131], v[182:185], v[116:119]
	v_mfma_f32_16x16x32_bf16 v[104:107], v[136:139], v[182:185], v[104:107]
	v_mfma_f32_16x16x32_bf16 v[100:103], v[128:131], v[206:209], v[100:103]
	v_mfma_f32_16x16x32_bf16 v[88:91], v[136:139], v[206:209], v[88:91]
	v_mfma_f32_16x16x32_bf16 v[84:87], v[128:131], v[214:217], v[84:87]
	v_mfma_f32_16x16x32_bf16 v[72:75], v[136:139], v[214:217], v[72:75]
	v_mfma_f32_16x16x32_bf16 v[124:127], v[132:135], v[178:181], v[124:127]
	v_mfma_f32_16x16x32_bf16 v[120:123], v[150:153], v[178:181], v[120:123]
	v_mfma_f32_16x16x32_bf16 v[116:119], v[132:135], v[186:189], v[116:119]
	v_mfma_f32_16x16x32_bf16 v[104:107], v[150:153], v[186:189], v[104:107]
	v_mfma_f32_16x16x32_bf16 v[100:103], v[132:135], v[210:213], v[100:103]
	v_mfma_f32_16x16x32_bf16 v[88:91], v[150:153], v[210:213], v[88:91]
	v_mfma_f32_16x16x32_bf16 v[84:87], v[132:135], v[218:221], v[84:87]
	v_mfma_f32_16x16x32_bf16 v[72:75], v[150:153], v[218:221], v[72:75]
	v_mfma_f32_16x16x32_bf16 v[112:115], v[154:157], v[174:177], v[112:115]
	v_mfma_f32_16x16x32_bf16 v[108:111], v[166:169], v[174:177], v[108:111]
	v_mfma_f32_16x16x32_bf16 v[96:99], v[154:157], v[182:185], v[96:99]
	v_mfma_f32_16x16x32_bf16 v[92:95], v[166:169], v[182:185], v[92:95]
	v_mfma_f32_16x16x32_bf16 v[80:83], v[154:157], v[206:209], v[80:83]
	v_mfma_f32_16x16x32_bf16 v[76:79], v[166:169], v[206:209], v[76:79]
	v_mfma_f32_16x16x32_bf16 v[68:71], v[154:157], v[214:217], v[68:71]
	v_mfma_f32_16x16x32_bf16 v[64:67], v[166:169], v[214:217], v[64:67]
	v_mfma_f32_16x16x32_bf16 v[112:115], v[162:165], v[178:181], v[112:115]
	v_mfma_f32_16x16x32_bf16 v[108:111], v[170:173], v[178:181], v[108:111]
	v_mfma_f32_16x16x32_bf16 v[96:99], v[162:165], v[186:189], v[96:99]
	v_mfma_f32_16x16x32_bf16 v[92:95], v[170:173], v[186:189], v[92:95]
	v_mfma_f32_16x16x32_bf16 v[80:83], v[162:165], v[210:213], v[80:83]
	v_mfma_f32_16x16x32_bf16 v[76:79], v[170:173], v[210:213], v[76:79]
	v_mfma_f32_16x16x32_bf16 v[68:71], v[162:165], v[218:221], v[68:71]
	v_mfma_f32_16x16x32_bf16 v[64:67], v[170:173], v[218:221], v[64:67]
	s_barrier
	s_add_i32 s46, s46, s26
	v_lshl_add_u64 v[190:191], s[18:19], 0, v[192:193]
	s_mov_b32 m0, s46
	ds_read_b128 v[174:177], v161 offset:16384
	ds_read_b128 v[178:181], v161 offset:17408
	ds_read_b128 v[182:185], v161 offset:18432
	ds_read_b128 v[186:189], v161 offset:19456
	ds_read_b128 v[206:209], v161 offset:20480
	ds_read_b128 v[210:213], v161 offset:21504
	ds_read_b128 v[214:217], v161 offset:22528
	ds_read_b128 v[218:221], v161 offset:23552
	global_load_lds_dwordx4 v[190:191], off
	s_add_i32 m0, s46, 0x2000
	s_add_u32 s46, s18, 0x40000
	v_lshl_add_u64 v[222:223], s[18:19], 0, v[140:141]
	s_addc_u32 s47, s19, 0
	s_add_i32 s48, s48, s26
	global_load_lds_dwordx4 v[222:223], off
	v_lshl_add_u64 v[224:225], s[46:47], 0, v[192:193]
	s_mov_b32 m0, s48
	v_lshl_add_u64 v[226:227], s[20:21], 0, v[142:143]
	global_load_lds_dwordx4 v[224:225], off
	v_lshl_add_u64 v[224:225], s[46:47], 0, v[140:141]
	s_add_i32 m0, s48, 0x2000
	s_nop 0
	global_load_lds_dwordx4 v[224:225], off
	v_lshl_add_u64 v[224:225], s[20:21], 0, v[144:145]
	s_mov_b32 m0, s27
	s_nop 0
	global_load_lds_dwordx4 v[224:225], off
	s_mov_b32 m0, s28
	s_nop 0
	global_load_lds_dwordx4 v[226:227], off
	s_waitcnt vmcnt(8)
	s_waitcnt lgkmcnt(0)
	s_barrier
; #define PG8_STAGE(bufoff, gbase, voff) do { _Pragma("unroll") for (int _i = 0; _i < 2; ++_i) \
;         __builtin_amdgcn_global_load_lds((const unsigned*)((const char*)(gbase) + (voff)[_i]), (PG8_LAS unsigned*)(lds + (bufoff) + ldsw + _i * 8192), 16, 0, 0); } while (0)
; #define PG8_LDA(dst, b, h) do { _Pragma("unroll") for (int m = 0; m < 4; ++m) _Pragma("unroll") for (int k = 0; k < 2; ++k) dst[m][k] = *(const PG8_LAS bf16x8*)(lds + PG8_SA(b, h) + aoff + m * 2048 + k * 1024); } while (0)
; #define PG8_LDB(dst, b, h) do { _Pragma("unroll") for (int n = 0; n < 2; ++n) _Pragma("unroll") for (int k = 0; k < 2; ++k) dst[n][k] = *(const PG8_LAS bf16x8*)(lds + PG8_SB(b, h) + boff + n * 2048 + k * 1024); } while (0)
; #define PG8_MMA(ai, bj, At, Bt) do { __builtin_amdgcn_s_setprio(1); _Pragma("unroll") for (int m = 0; m < 4; ++m) _Pragma("unroll") for (int n = 0; n < 2; ++n) _Pragma("unroll") for (int k = 0; k < 2; ++k) \
;         acc[ai][bj][m][n] = __builtin_amdgcn_mfma_f32_16x16x32_bf16(Bt[n][k], At[m][k], acc[ai][bj][m][n], 0, 0, 0); __builtin_amdgcn_s_setprio(0); } while (0)
; #define PG8_WAIT_V(n) asm volatile("s_waitcnt vmcnt(" #n ")" ::: "memory")
; #define PG8_WAIT_L(n) asm volatile("s_waitcnt lgkmcnt(" #n ")" ::: "memory")
; #define PG8_BAR __builtin_amdgcn_s_barrier()
; #define PG8_SCHED __builtin_amdgcn_sched_barrier(0)
; template <class Epi, class Sched, bool ALIGN_EPI = false, bool SP2 = false>
; __device__ __forceinline__ void gemm_phase(PG8_LAS unsigned char* lds, const Gemm g, const Sched& S, const Epi& E) {
;     ...
;             PG8_WAIT_V(8); PG8_WAIT_L(0); PG8_BAR; PG8_MMA(1, 0, At, B0); PG8_MMA(1, 1, At, B1); PG8_BAR; PG8_SCHED;
;             PG8_LDB(B0, 1, 0); PG8_LDB(B1, 1, 1); PG8_SCHED; PG8_LDA(At, 1, 0); PG8_STAGE(PG8_SA(0, 1), a2 + hstep, voffA);
;             PG8_WAIT_V(8); PG8_WAIT_L(0); PG8_BAR; PG8_MMA(0, 0, At, B0); PG8_MMA(0, 1, At, B1); PG8_BAR; PG8_SCHED;
	s_waitcnt lgkmcnt(0)
	v_mfma_f32_16x16x32_bf16 v[60:63], v[128:131], v[174:177], v[60:63]
	v_mfma_f32_16x16x32_bf16 v[56:59], v[136:139], v[174:177], v[56:59]
	v_mfma_f32_16x16x32_bf16 v[52:55], v[128:131], v[182:185], v[52:55]
	v_mfma_f32_16x16x32_bf16 v[40:43], v[136:139], v[182:185], v[40:43]
	v_mfma_f32_16x16x32_bf16 v[36:39], v[128:131], v[206:209], v[36:39]
	v_mfma_f32_16x16x32_bf16 v[24:27], v[136:139], v[206:209], v[24:27]
	v_mfma_f32_16x16x32_bf16 v[20:23], v[128:131], v[214:217], v[20:23]
	v_mfma_f32_16x16x32_bf16 v[8:11], v[136:139], v[214:217], v[8:11]
	v_mfma_f32_16x16x32_bf16 v[60:63], v[132:135], v[178:181], v[60:63]
	v_mfma_f32_16x16x32_bf16 v[56:59], v[150:153], v[178:181], v[56:59]
	v_mfma_f32_16x16x32_bf16 v[52:55], v[132:135], v[186:189], v[52:55]
	v_mfma_f32_16x16x32_bf16 v[40:43], v[150:153], v[186:189], v[40:43]
	v_mfma_f32_16x16x32_bf16 v[36:39], v[132:135], v[210:213], v[36:39]
	v_mfma_f32_16x16x32_bf16 v[24:27], v[150:153], v[210:213], v[24:27]
	v_mfma_f32_16x16x32_bf16 v[20:23], v[132:135], v[218:221], v[20:23]
	v_mfma_f32_16x16x32_bf16 v[8:11], v[150:153], v[218:221], v[8:11]
	v_mfma_f32_16x16x32_bf16 v[48:51], v[154:157], v[174:177], v[48:51]
	v_mfma_f32_16x16x32_bf16 v[44:47], v[166:169], v[174:177], v[44:47]
	v_mfma_f32_16x16x32_bf16 v[32:35], v[154:157], v[182:185], v[32:35]
	v_mfma_f32_16x16x32_bf16 v[28:31], v[166:169], v[182:185], v[28:31]
	v_mfma_f32_16x16x32_bf16 v[16:19], v[154:157], v[206:209], v[16:19]
	v_mfma_f32_16x16x32_bf16 v[12:15], v[166:169], v[206:209], v[12:15]
	v_mfma_f32_16x16x32_bf16 v[4:7], v[154:157], v[214:217], v[4:7]
	v_mfma_f32_16x16x32_bf16 v[0:3], v[166:169], v[214:217], v[0:3]
	v_mfma_f32_16x16x32_bf16 v[48:51], v[162:165], v[178:181], v[48:51]
	v_mfma_f32_16x16x32_bf16 v[44:47], v[170:173], v[178:181], v[44:47]
	v_mfma_f32_16x16x32_bf16 v[32:35], v[162:165], v[186:189], v[32:35]
	v_mfma_f32_16x16x32_bf16 v[28:31], v[170:173], v[186:189], v[28:31]
	v_mfma_f32_16x16x32_bf16 v[16:19], v[162:165], v[210:213], v[16:19]
	v_mfma_f32_16x16x32_bf16 v[12:15], v[170:173], v[210:213], v[12:15]
	v_mfma_f32_16x16x32_bf16 v[4:7], v[162:165], v[218:221], v[4:7]
	v_mfma_f32_16x16x32_bf16 v[0:3], v[170:173], v[218:221], v[0:3]
	s_barrier
	s_add_i32 s46, 0, 0x18000
	s_add_i32 s47, 0, 0x1c000
	v_add_u32_e32 v150, s46, v159
	v_add_u32_e32 v170, s47, v159
	ds_read_b128 v[128:131], v150
	ds_read_b128 v[132:135], v150 offset:1024
	ds_read_b128 v[136:139], v150 offset:2048
	ds_read_b128 v[150:153], v150 offset:3072
	ds_read_b128 v[154:157], v170
	ds_read_b128 v[162:165], v170 offset:1024
	ds_read_b128 v[166:169], v170 offset:2048
	ds_read_b128 v[170:173], v170 offset:3072
	s_add_u32 s20, s20, 0x40000
	s_addc_u32 s21, s21, 0
	s_mov_b32 m0, s29
	v_lshl_add_u64 v[228:229], s[20:21], 0, v[144:145]
	ds_read_b128 v[174:177], v161 offset:32768
	ds_read_b128 v[178:181], v161 offset:33792
	ds_read_b128 v[182:185], v161 offset:34816
	ds_read_b128 v[186:189], v161 offset:35840
	ds_read_b128 v[206:209], v161 offset:36864
	ds_read_b128 v[210:213], v161 offset:37888
	ds_read_b128 v[214:217], v161 offset:38912
	ds_read_b128 v[218:221], v161 offset:39936
	global_load_lds_dwordx4 v[228:229], off
	v_lshl_add_u64 v[228:229], s[20:21], 0, v[142:143]
	s_mov_b32 m0, s30
	s_nop 0
	global_load_lds_dwordx4 v[228:229], off
	s_waitcnt vmcnt(8)
	s_waitcnt lgkmcnt(0)
	s_barrier
	s_waitcnt lgkmcnt(0)
	v_mfma_f32_16x16x32_bf16 v[124:127], v[128:131], v[174:177], v[124:127]
	v_mfma_f32_16x16x32_bf16 v[120:123], v[136:139], v[174:177], v[120:123]
	v_mfma_f32_16x16x32_bf16 v[116:119], v[128:131], v[182:185], v[116:119]
	v_mfma_f32_16x16x32_bf16 v[104:107], v[136:139], v[182:185], v[104:107]
	v_mfma_f32_16x16x32_bf16 v[100:103], v[128:131], v[206:209], v[100:103]
	v_mfma_f32_16x16x32_bf16 v[88:91], v[136:139], v[206:209], v[88:91]
	v_mfma_f32_16x16x32_bf16 v[84:87], v[128:131], v[214:217], v[84:87]
	v_mfma_f32_16x16x32_bf16 v[72:75], v[136:139], v[214:217], v[72:75]
	v_mfma_f32_16x16x32_bf16 v[124:127], v[132:135], v[178:181], v[124:127]
	v_mfma_f32_16x16x32_bf16 v[120:123], v[150:153], v[178:181], v[120:123]
	v_mfma_f32_16x16x32_bf16 v[116:119], v[132:135], v[186:189], v[116:119]
	v_mfma_f32_16x16x32_bf16 v[104:107], v[150:153], v[186:189], v[104:107]
	v_mfma_f32_16x16x32_bf16 v[100:103], v[132:135], v[210:213], v[100:103]
	v_mfma_f32_16x16x32_bf16 v[88:91], v[150:153], v[210:213], v[88:91]
	v_mfma_f32_16x16x32_bf16 v[84:87], v[132:135], v[218:221], v[84:87]
	v_mfma_f32_16x16x32_bf16 v[72:75], v[150:153], v[218:221], v[72:75]
	v_mfma_f32_16x16x32_bf16 v[112:115], v[154:157], v[174:177], v[112:115]
	v_mfma_f32_16x16x32_bf16 v[108:111], v[166:169], v[174:177], v[108:111]
	v_mfma_f32_16x16x32_bf16 v[96:99], v[154:157], v[182:185], v[96:99]
	v_mfma_f32_16x16x32_bf16 v[92:95], v[166:169], v[182:185], v[92:95]
	v_mfma_f32_16x16x32_bf16 v[80:83], v[154:157], v[206:209], v[80:83]
	v_mfma_f32_16x16x32_bf16 v[76:79], v[166:169], v[206:209], v[76:79]
	v_mfma_f32_16x16x32_bf16 v[68:71], v[154:157], v[214:217], v[68:71]
	v_mfma_f32_16x16x32_bf16 v[64:67], v[166:169], v[214:217], v[64:67]
	v_mfma_f32_16x16x32_bf16 v[112:115], v[162:165], v[178:181], v[112:115]
	v_mfma_f32_16x16x32_bf16 v[108:111], v[170:173], v[178:181], v[108:111]
	v_mfma_f32_16x16x32_bf16 v[96:99], v[162:165], v[186:189], v[96:99]
	v_mfma_f32_16x16x32_bf16 v[92:95], v[170:173], v[186:189], v[92:95]
	v_mfma_f32_16x16x32_bf16 v[80:83], v[162:165], v[210:213], v[80:83]
	v_mfma_f32_16x16x32_bf16 v[76:79], v[170:173], v[210:213], v[76:79]
	v_mfma_f32_16x16x32_bf16 v[68:71], v[162:165], v[218:221], v[68:71]
	v_mfma_f32_16x16x32_bf16 v[64:67], v[170:173], v[218:221], v[64:67]
	s_barrier
; #define PG8_STAGE(bufoff, gbase, voff) do { _Pragma("unroll") for (int _i = 0; _i < 2; ++_i) \
;         __builtin_amdgcn_global_load_lds((const unsigned*)((const char*)(gbase) + (voff)[_i]), (PG8_LAS unsigned*)(lds + (bufoff) + ldsw + _i * 8192), 16, 0, 0); } while (0)
; #define PG8_LDA(dst, b, h) do { _Pragma("unroll") for (int m = 0; m < 4; ++m) _Pragma("unroll") for (int k = 0; k < 2; ++k) dst[m][k] = *(const PG8_LAS bf16x8*)(lds + PG8_SA(b, h) + aoff + m * 2048 + k * 1024); } while (0)
; #define PG8_MMA(ai, bj, At, Bt) do { __builtin_amdgcn_s_setprio(1); _Pragma("unroll") for (int m = 0; m < 4; ++m) _Pragma("unroll") for (int n = 0; n < 2; ++n) _Pragma("unroll") for (int k = 0; k < 2; ++k) \
;         acc[ai][bj][m][n] = __builtin_amdgcn_mfma_f32_16x16x32_bf16(Bt[n][k], At[m][k], acc[ai][bj][m][n], 0, 0, 0); __builtin_amdgcn_s_setprio(0); } while (0)
; #define PG8_WAIT_V(n) asm volatile("s_waitcnt vmcnt(" #n ")" ::: "memory")
; #define PG8_WAIT_L(n) asm volatile("s_waitcnt lgkmcnt(" #n ")" ::: "memory")
; #define PG8_BAR __builtin_amdgcn_s_barrier()
; #define PG8_SCHED __builtin_amdgcn_sched_barrier(0)
; template <class Epi, class Sched, bool ALIGN_EPI = false, bool SP2 = false>
; __device__ __forceinline__ void gemm_phase(PG8_LAS unsigned char* lds, const Gemm g, const Sched& S, const Epi& E) {
;     ...
;             PG8_LDA(At, 1, 1); PG8_STAGE(PG8_SB(1, 0), b3, voffB); PG8_STAGE(PG8_SB(1, 1), b3 + hstep, voffB); PG8_STAGE(PG8_SA(1, 0), a3, voffA);
;             PG8_WAIT_V(8); PG8_WAIT_L(0); PG8_BAR; PG8_MMA(1, 0, At, B0); PG8_MMA(1, 1, At, B1); PG8_BAR; PG8_SCHED;
;     DI void operator()(const pg8::f32x4 (&acc)[2][2][4][2], const pg8::Unit& u, int wr, int wc, int fr, int fq) const {
;         const int row0 = u.pm * 256 + wr * 64 + fr, col0 = u.pn * 256 + wc * 32 + 8 * fq;
; #pragma unroll
;         for (int ai = 0; ai < 2; ++ai) {
;             f32x4 rv[4][2][2];
; #pragma unroll
;             for (int m = 0; m < 4; ++m) { const size_t off = (size_t)(row0 + ai * 128 + m * 16) * D + col0;
; #pragma unroll
;                 for (int bj = 0; bj < 2; ++bj)
; #pragma unroll
;                     for (int n = 0; n < 2; ++n) rv[m][bj][n] = *(const f32x4*)(res + off + bj * 128 + 4 * n); }
	s_add_i32 s20, s46, s26
	v_lshl_add_u64 v[190:191], v[190:191], 0, s[72:73]
	s_mov_b32 m0, s20
	ds_read_b128 v[174:177], v161 offset:49152
	ds_read_b128 v[178:181], v161 offset:50176
	ds_read_b128 v[182:185], v161 offset:51200
	ds_read_b128 v[186:189], v161 offset:52224
	ds_read_b128 v[206:209], v161 offset:53248
	ds_read_b128 v[210:213], v161 offset:54272
	ds_read_b128 v[214:217], v161 offset:55296
	ds_read_b128 v[218:221], v161 offset:56320
	global_load_lds_dwordx4 v[190:191], off
	s_add_i32 m0, s20, 0x2000
	s_add_u32 s18, s18, 0x40080
	v_lshl_add_u64 v[190:191], v[222:223], 0, s[72:73]
	s_addc_u32 s19, s19, 0
	s_add_i32 s20, s47, s26
	global_load_lds_dwordx4 v[190:191], off
	v_lshl_add_u64 v[190:191], s[18:19], 0, v[192:193]
	s_mov_b32 m0, s20
	s_nop 0
	global_load_lds_dwordx4 v[190:191], off
	v_lshl_add_u64 v[190:191], s[18:19], 0, v[140:141]
	s_add_i32 m0, s20, 0x2000
	s_nop 0
	global_load_lds_dwordx4 v[190:191], off
	v_lshl_add_u64 v[190:191], v[224:225], 0, s[72:73]
	s_mov_b32 m0, s31
	s_nop 0
	global_load_lds_dwordx4 v[190:191], off
	v_lshl_add_u64 v[190:191], v[226:227], 0, s[72:73]
	s_mov_b32 m0, s33
	s_nop 0
	global_load_lds_dwordx4 v[190:191], off
	s_waitcnt vmcnt(8)
	s_waitcnt lgkmcnt(0)
	s_barrier
	s_waitcnt lgkmcnt(0)
	v_mfma_f32_16x16x32_bf16 v[60:63], v[128:131], v[174:177], v[60:63]
	v_mfma_f32_16x16x32_bf16 v[56:59], v[136:139], v[174:177], v[56:59]
	v_mfma_f32_16x16x32_bf16 v[52:55], v[128:131], v[182:185], v[52:55]
	v_mfma_f32_16x16x32_bf16 v[40:43], v[136:139], v[182:185], v[40:43]
	v_mfma_f32_16x16x32_bf16 v[36:39], v[128:131], v[206:209], v[36:39]
	v_mfma_f32_16x16x32_bf16 v[24:27], v[136:139], v[206:209], v[24:27]
	v_mfma_f32_16x16x32_bf16 v[20:23], v[128:131], v[214:217], v[20:23]
	v_mfma_f32_16x16x32_bf16 v[8:11], v[136:139], v[214:217], v[8:11]
	v_mfma_f32_16x16x32_bf16 v[60:63], v[132:135], v[178:181], v[60:63]
	v_mfma_f32_16x16x32_bf16 v[56:59], v[150:153], v[178:181], v[56:59]
	v_mfma_f32_16x16x32_bf16 v[52:55], v[132:135], v[186:189], v[52:55]
	v_mfma_f32_16x16x32_bf16 v[40:43], v[150:153], v[186:189], v[40:43]
	v_mfma_f32_16x16x32_bf16 v[36:39], v[132:135], v[210:213], v[36:39]
	v_mfma_f32_16x16x32_bf16 v[24:27], v[150:153], v[210:213], v[24:27]
	v_mfma_f32_16x16x32_bf16 v[20:23], v[132:135], v[218:221], v[20:23]
	v_mfma_f32_16x16x32_bf16 v[8:11], v[150:153], v[218:221], v[8:11]
	v_mfma_f32_16x16x32_bf16 v[48:51], v[154:157], v[174:177], v[48:51]
	v_mfma_f32_16x16x32_bf16 v[44:47], v[166:169], v[174:177], v[44:47]
	v_mfma_f32_16x16x32_bf16 v[32:35], v[154:157], v[182:185], v[32:35]
	v_mfma_f32_16x16x32_bf16 v[28:31], v[166:169], v[182:185], v[28:31]
	v_mfma_f32_16x16x32_bf16 v[16:19], v[154:157], v[206:209], v[16:19]
	v_mfma_f32_16x16x32_bf16 v[12:15], v[166:169], v[206:209], v[12:15]
	v_mfma_f32_16x16x32_bf16 v[4:7], v[154:157], v[214:217], v[4:7]
	v_mfma_f32_16x16x32_bf16 v[0:3], v[166:169], v[214:217], v[0:3]
	v_mfma_f32_16x16x32_bf16 v[48:51], v[162:165], v[178:181], v[48:51]
	v_mfma_f32_16x16x32_bf16 v[44:47], v[170:173], v[178:181], v[44:47]
	v_mfma_f32_16x16x32_bf16 v[32:35], v[162:165], v[186:189], v[32:35]
	v_mfma_f32_16x16x32_bf16 v[28:31], v[170:173], v[186:189], v[28:31]
	v_mfma_f32_16x16x32_bf16 v[16:19], v[162:165], v[210:213], v[16:19]
	v_mfma_f32_16x16x32_bf16 v[12:15], v[170:173], v[210:213], v[12:15]
	v_mfma_f32_16x16x32_bf16 v[4:7], v[162:165], v[218:221], v[4:7]
	v_mfma_f32_16x16x32_bf16 v[0:3], v[170:173], v[218:221], v[0:3]
	s_barrier
	s_add_i32 s45, s45, 2
	s_add_u32 s16, s16, 0x100
	s_addc_u32 s17, s17, 0
	s_add_u32 s39, s39, 0x100
	s_addc_u32 s44, s44, 0
	s_cmp_gt_u32 s45, 13
	s_cbranch_scc0 .LBB0_1051
	s_and_b64 vcc, exec, s[6:7]
	s_cbranch_vccz .LBB0_1054
	s_barrier
.LBB0_1054:
	v_lshl_or_b32 v130, s35, 8, v160
	v_lshl_add_u32 v128, s36, 8, v158
	v_ashrrev_i32_e32 v131, 31, v130
	v_lshlrev_b64 v[150:151], 2, v[130:131]
	v_ashrrev_i32_e32 v129, 31, v128
	v_lshl_add_u64 v[152:153], s[2:3], 0, v[150:151]
	v_lshlrev_b64 v[154:155], 12, v[128:129]
	v_lshl_add_u64 v[130:131], v[152:153], 0, v[154:155]
	global_load_dwordx4 v[162:165], v[130:131], off offset:16
	global_load_dwordx4 v[166:169], v[130:131], off
	global_load_dwordx4 v[170:173], v[130:131], off offset:528
	global_load_dwordx4 v[174:177], v[130:131], off offset:512
	v_or_b32_e32 v130, 16, v128
	v_ashrrev_i32_e32 v131, 31, v130
	v_lshlrev_b64 v[190:191], 12, v[130:131]
	v_lshl_add_u64 v[130:131], v[152:153], 0, v[190:191]
	global_load_dwordx4 v[178:181], v[130:131], off offset:16
	global_load_dwordx4 v[182:185], v[130:131], off
	global_load_dwordx4 v[186:189], v[130:131], off offset:528
	global_load_dwordx4 v[206:209], v[130:131], off offset:512
	v_or_b32_e32 v130, 32, v128
	v_ashrrev_i32_e32 v131, 31, v130
	v_lshlrev_b64 v[230:231], 12, v[130:131]
	v_or_b32_e32 v128, 48, v128
	v_lshl_add_u64 v[130:131], v[152:153], 0, v[230:231]
	v_ashrrev_i32_e32 v129, 31, v128
	global_load_dwordx4 v[210:213], v[130:131], off offset:16
	global_load_dwordx4 v[214:217], v[130:131], off
	global_load_dwordx4 v[218:221], v[130:131], off offset:528
	global_load_dwordx4 v[222:225], v[130:131], off offset:512
	v_lshlrev_b64 v[156:157], 12, v[128:129]
	v_lshl_add_u64 v[132:133], v[152:153], 0, v[156:157]
	global_load_dwordx4 v[136:139], v[132:133], off offset:16
	global_load_dwordx4 v[226:229], v[132:133], off
	global_load_dwordx4 v[128:131], v[132:133], off offset:528
	s_nop 0
	global_load_dwordx4 v[132:135], v[132:133], off offset:512
	s_mov_b32 s18, 0x3fb504f3
	s_mov_b64 s[16:17], 0x80000
	s_andn2_b64 vcc, exec, s[42:43]
	s_waitcnt vmcnt(0)
;     DI void operator()(const pg8::f32x4 (&acc)[2][2][4][2], const pg8::Unit& u, int wr, int wc, int fr, int fq) const {
;     ...
;             for (int m = 0; m < 4; ++m) { const size_t off = (size_t)(row0 + ai * 128 + m * 16) * D + col0;
; #pragma unroll
;                 for (int bj = 0; bj < 2; ++bj)
; #pragma unroll
;                     for (int n = 0; n < 2; ++n) rv[m][bj][n] = *(const f32x4*)(res + off + bj * 128 + 4 * n); }
; #pragma unroll
;             for (int m = 0; m < 4; ++m) { const size_t off = (size_t)(row0 + ai * 128 + m * 16) * D + col0;
; #pragma unroll
;                 for (int bj = 0; bj < 2; ++bj)
; #pragma unroll
;                     for (int n = 0; n < 2; ++n) { const f32x4 r = rv[m][bj][n]; const pg8::f32x4 a = acc[ai][bj][m][n];
;                         f32x4 o; o[0] = ALPHA * r[0] + a[0]; o[1] = ALPHA * r[1] + a[1]; o[2] = ALPHA * r[2] + a[2]; o[3] = ALPHA * r[3] + a[3];
;                         *(f32x4*)(out + off + bj * 128 + 4 * n) = o; } }
	v_pk_fma_f32 v[122:123], v[164:165], s[18:19], v[122:123] op_sel_hi:[1,0,1]
	v_pk_fma_f32 v[124:125], v[166:167], s[18:19], v[124:125] op_sel_hi:[1,0,1]
	v_lshl_add_u64 v[166:167], s[0:1], 0, v[154:155]
	v_lshl_add_u64 v[166:167], v[166:167], 0, v[150:151]
	v_pk_fma_f32 v[114:115], v[176:177], s[18:19], v[114:115] op_sel_hi:[1,0,1]
	v_pk_fma_f32 v[112:113], v[174:175], s[18:19], v[112:113] op_sel_hi:[1,0,1]
	global_store_dwordx4 v[166:167], v[112:115], off offset:512
	v_pk_fma_f32 v[110:111], v[172:173], s[18:19], v[110:111] op_sel_hi:[1,0,1]
	v_pk_fma_f32 v[98:99], v[208:209], s[18:19], v[98:99] op_sel_hi:[1,0,1]
	v_lshl_add_u64 v[112:113], s[0:1], 0, v[190:191]
	v_lshl_add_u64 v[112:113], v[112:113], 0, v[150:151]
	v_pk_fma_f32 v[96:97], v[206:207], s[18:19], v[96:97] op_sel_hi:[1,0,1]
	global_store_dwordx4 v[112:113], v[96:99], off offset:512
	v_pk_fma_f32 v[108:109], v[170:171], s[18:19], v[108:109] op_sel_hi:[1,0,1]
	v_pk_fma_f32 v[94:95], v[188:189], s[18:19], v[94:95] op_sel_hi:[1,0,1]
	v_lshl_add_u64 v[96:97], s[0:1], 0, v[230:231]
	v_lshl_add_u64 v[96:97], v[96:97], 0, v[150:151]
	v_pk_fma_f32 v[82:83], v[224:225], s[18:19], v[82:83] op_sel_hi:[1,0,1]
	v_pk_fma_f32 v[80:81], v[222:223], s[18:19], v[80:81] op_sel_hi:[1,0,1]
	v_pk_fma_f32 v[92:93], v[186:187], s[18:19], v[92:93] op_sel_hi:[1,0,1]
	global_store_dwordx4 v[96:97], v[80:83], off offset:512
	v_pk_fma_f32 v[78:79], v[220:221], s[18:19], v[78:79] op_sel_hi:[1,0,1]
	v_pk_fma_f32 v[76:77], v[218:219], s[18:19], v[76:77] op_sel_hi:[1,0,1]
	v_lshl_add_u64 v[80:81], s[0:1], 0, v[156:157]
	v_pk_fma_f32 v[126:127], v[168:169], s[18:19], v[126:127] op_sel_hi:[1,0,1]
	v_pk_fma_f32 v[120:121], v[162:163], s[18:19], v[120:121] op_sel_hi:[1,0,1]
	global_store_dwordx4 v[166:167], v[108:111], off offset:528
	v_pk_fma_f32 v[106:107], v[180:181], s[18:19], v[106:107] op_sel_hi:[1,0,1]
	v_pk_fma_f32 v[104:105], v[178:179], s[18:19], v[104:105] op_sel_hi:[1,0,1]
	v_pk_fma_f32 v[110:111], v[184:185], s[18:19], v[118:119] op_sel_hi:[1,0,1]
	v_pk_fma_f32 v[108:109], v[182:183], s[18:19], v[116:117] op_sel_hi:[1,0,1]
	global_store_dwordx4 v[112:113], v[92:95], off offset:528
	v_pk_fma_f32 v[90:91], v[212:213], s[18:19], v[90:91] op_sel_hi:[1,0,1]
	v_pk_fma_f32 v[88:89], v[210:211], s[18:19], v[88:89] op_sel_hi:[1,0,1]
	v_pk_fma_f32 v[94:95], v[216:217], s[18:19], v[102:103] op_sel_hi:[1,0,1]
	v_pk_fma_f32 v[92:93], v[214:215], s[18:19], v[100:101] op_sel_hi:[1,0,1]
	global_store_dwordx4 v[96:97], v[76:79], off offset:528
	v_lshl_add_u64 v[80:81], v[80:81], 0, v[150:151]
	v_pk_fma_f32 v[74:75], v[138:139], s[18:19], v[74:75] op_sel_hi:[1,0,1]
	v_pk_fma_f32 v[78:79], v[228:229], s[18:19], v[86:87] op_sel_hi:[1,0,1]
	v_pk_fma_f32 v[76:77], v[226:227], s[18:19], v[84:85] op_sel_hi:[1,0,1]
	v_pk_fma_f32 v[72:73], v[136:137], s[18:19], v[72:73] op_sel_hi:[1,0,1]
	v_pk_fma_f32 v[70:71], v[134:135], s[18:19], v[70:71] op_sel_hi:[1,0,1]
	v_pk_fma_f32 v[68:69], v[132:133], s[18:19], v[68:69] op_sel_hi:[1,0,1]
	v_pk_fma_f32 v[66:67], v[130:131], s[18:19], v[66:67] op_sel_hi:[1,0,1]
	v_pk_fma_f32 v[64:65], v[128:129], s[18:19], v[64:65] op_sel_hi:[1,0,1]
	v_lshl_add_u64 v[132:133], v[154:155], 0, s[16:17]
	global_store_dwordx4 v[166:167], v[124:127], off
	global_store_dwordx4 v[166:167], v[120:123], off offset:16
	global_store_dwordx4 v[112:113], v[108:111], off
	global_store_dwordx4 v[112:113], v[104:107], off offset:16
	global_store_dwordx4 v[96:97], v[92:95], off
	global_store_dwordx4 v[96:97], v[88:91], off offset:16
	global_store_dwordx4 v[80:81], v[76:79], off
	global_store_dwordx4 v[80:81], v[72:75], off offset:16
	global_store_dwordx4 v[80:81], v[68:71], off offset:512
	global_store_dwordx4 v[80:81], v[64:67], off offset:528
	s_mov_b64 s[16:17], 0x90000
	v_lshl_add_u64 v[134:135], v[154:155], 0, s[16:17]
	v_lshl_add_u64 v[64:65], v[152:153], 0, v[132:133]
	global_load_dwordx4 v[88:91], v[64:65], off offset:16
	global_load_dwordx4 v[92:95], v[64:65], off
	global_load_dwordx4 v[96:99], v[64:65], off offset:528
	global_load_dwordx4 v[100:103], v[64:65], off offset:512
	v_lshl_add_u64 v[64:65], v[152:153], 0, v[134:135]
	s_mov_b64 s[16:17], 0xa0000
	global_load_dwordx4 v[104:107], v[64:65], off offset:16
	global_load_dwordx4 v[108:111], v[64:65], off
	global_load_dwordx4 v[112:115], v[64:65], off offset:528
	global_load_dwordx4 v[116:119], v[64:65], off offset:512
	v_lshl_add_u64 v[86:87], v[154:155], 0, s[16:17]
	v_lshl_add_u64 v[64:65], v[152:153], 0, v[86:87]
	s_mov_b64 s[16:17], 0xb0000
	global_load_dwordx4 v[76:79], v[64:65], off offset:16
	global_load_dwordx4 v[120:123], v[64:65], off
	global_load_dwordx4 v[80:83], v[64:65], off offset:528
	global_load_dwordx4 v[124:127], v[64:65], off offset:512
	v_lshl_add_u64 v[84:85], v[154:155], 0, s[16:17]
	v_lshl_add_u64 v[72:73], v[152:153], 0, v[84:85]
	global_load_dwordx4 v[68:71], v[72:73], off offset:16
	global_load_dwordx4 v[128:131], v[72:73], off
	global_load_dwordx4 v[64:67], v[72:73], off offset:528
	s_nop 0
	global_load_dwordx4 v[72:75], v[72:73], off offset:512
	s_mov_b64 s[16:17], -1
	s_waitcnt vmcnt(15)
;     DI void operator()(const pg8::f32x4 (&acc)[2][2][4][2], const pg8::Unit& u, int wr, int wc, int fr, int fq) const {
;     ...
;             for (int m = 0; m < 4; ++m) { const size_t off = (size_t)(row0 + ai * 128 + m * 16) * D + col0;
; #pragma unroll
;                 for (int bj = 0; bj < 2; ++bj)
; #pragma unroll
;                     for (int n = 0; n < 2; ++n) { const f32x4 r = rv[m][bj][n]; const pg8::f32x4 a = acc[ai][bj][m][n];
;                         f32x4 o; o[0] = ALPHA * r[0] + a[0]; o[1] = ALPHA * r[1] + a[1]; o[2] = ALPHA * r[2] + a[2]; o[3] = ALPHA * r[3] + a[3];
;                         *(f32x4*)(out + off + bj * 128 + 4 * n) = o; } }
	v_pk_fma_f32 v[58:59], v[90:91], s[18:19], v[58:59] op_sel_hi:[1,0,1]
	s_waitcnt vmcnt(14)
	v_pk_fma_f32 v[60:61], v[92:93], s[18:19], v[60:61] op_sel_hi:[1,0,1]
	v_lshl_add_u64 v[92:93], s[0:1], 0, v[132:133]
	v_lshl_add_u64 v[92:93], v[92:93], 0, v[150:151]
	s_waitcnt vmcnt(12)
	v_pk_fma_f32 v[50:51], v[102:103], s[18:19], v[50:51] op_sel_hi:[1,0,1]
	v_pk_fma_f32 v[48:49], v[100:101], s[18:19], v[48:49] op_sel_hi:[1,0,1]
	global_store_dwordx4 v[92:93], v[48:51], off offset:512
	s_waitcnt vmcnt(9)
	v_pk_fma_f32 v[34:35], v[118:119], s[18:19], v[34:35] op_sel_hi:[1,0,1]
	v_pk_fma_f32 v[32:33], v[116:117], s[18:19], v[32:33] op_sel_hi:[1,0,1]
	v_lshl_add_u64 v[48:49], s[0:1], 0, v[134:135]
	v_lshl_add_u64 v[48:49], v[48:49], 0, v[150:151]
	global_store_dwordx4 v[48:49], v[32:35], off offset:512
	s_waitcnt vmcnt(6)
	v_pk_fma_f32 v[18:19], v[126:127], s[18:19], v[18:19] op_sel_hi:[1,0,1]
	v_pk_fma_f32 v[16:17], v[124:125], s[18:19], v[16:17] op_sel_hi:[1,0,1]
	v_lshl_add_u64 v[32:33], s[0:1], 0, v[86:87]
	v_lshl_add_u64 v[32:33], v[32:33], 0, v[150:151]
	v_pk_fma_f32 v[46:47], v[98:99], s[18:19], v[46:47] op_sel_hi:[1,0,1]
	v_pk_fma_f32 v[44:45], v[96:97], s[18:19], v[44:45] op_sel_hi:[1,0,1]
	v_pk_fma_f32 v[30:31], v[114:115], s[18:19], v[30:31] op_sel_hi:[1,0,1]
	v_pk_fma_f32 v[28:29], v[112:113], s[18:19], v[28:29] op_sel_hi:[1,0,1]
	global_store_dwordx4 v[32:33], v[16:19], off offset:512
	v_pk_fma_f32 v[14:15], v[82:83], s[18:19], v[14:15] op_sel_hi:[1,0,1]
	v_pk_fma_f32 v[12:13], v[80:81], s[18:19], v[12:13] op_sel_hi:[1,0,1]
	v_lshl_add_u64 v[16:17], s[0:1], 0, v[84:85]
	v_pk_fma_f32 v[62:63], v[94:95], s[18:19], v[62:63] op_sel_hi:[1,0,1]
	v_pk_fma_f32 v[56:57], v[88:89], s[18:19], v[56:57] op_sel_hi:[1,0,1]
	global_store_dwordx4 v[92:93], v[44:47], off offset:528
	v_pk_fma_f32 v[42:43], v[106:107], s[18:19], v[42:43] op_sel_hi:[1,0,1]
	v_pk_fma_f32 v[40:41], v[104:105], s[18:19], v[40:41] op_sel_hi:[1,0,1]
	v_pk_fma_f32 v[46:47], v[110:111], s[18:19], v[54:55] op_sel_hi:[1,0,1]
	v_pk_fma_f32 v[44:45], v[108:109], s[18:19], v[52:53] op_sel_hi:[1,0,1]
	global_store_dwordx4 v[48:49], v[28:31], off offset:528
	v_pk_fma_f32 v[26:27], v[78:79], s[18:19], v[26:27] op_sel_hi:[1,0,1]
	v_pk_fma_f32 v[24:25], v[76:77], s[18:19], v[24:25] op_sel_hi:[1,0,1]
	v_pk_fma_f32 v[30:31], v[122:123], s[18:19], v[38:39] op_sel_hi:[1,0,1]
	v_pk_fma_f32 v[28:29], v[120:121], s[18:19], v[36:37] op_sel_hi:[1,0,1]
	global_store_dwordx4 v[32:33], v[12:15], off offset:528
	v_lshl_add_u64 v[16:17], v[16:17], 0, v[150:151]
	s_waitcnt vmcnt(9)
	v_pk_fma_f32 v[10:11], v[70:71], s[18:19], v[10:11] op_sel_hi:[1,0,1]
	s_waitcnt vmcnt(8)
	v_pk_fma_f32 v[14:15], v[130:131], s[18:19], v[22:23] op_sel_hi:[1,0,1]
	v_pk_fma_f32 v[12:13], v[128:129], s[18:19], v[20:21] op_sel_hi:[1,0,1]
	v_pk_fma_f32 v[8:9], v[68:69], s[18:19], v[8:9] op_sel_hi:[1,0,1]
	s_waitcnt vmcnt(6)
	v_pk_fma_f32 v[6:7], v[74:75], s[18:19], v[6:7] op_sel_hi:[1,0,1]
	v_pk_fma_f32 v[4:5], v[72:73], s[18:19], v[4:5] op_sel_hi:[1,0,1]
	v_pk_fma_f32 v[2:3], v[66:67], s[18:19], v[2:3] op_sel_hi:[1,0,1]
	v_pk_fma_f32 v[0:1], v[64:65], s[18:19], v[0:1] op_sel_hi:[1,0,1]
	global_store_dwordx4 v[92:93], v[60:63], off
	global_store_dwordx4 v[92:93], v[56:59], off offset:16
	global_store_dwordx4 v[48:49], v[44:47], off
	global_store_dwordx4 v[48:49], v[40:43], off offset:16
	global_store_dwordx4 v[32:33], v[28:31], off
	global_store_dwordx4 v[32:33], v[24:27], off offset:16
	global_store_dwordx4 v[16:17], v[12:15], off
	global_store_dwordx4 v[16:17], v[8:11], off offset:16
	global_store_dwordx4 v[16:17], v[4:7], off offset:512
	global_store_dwordx4 v[16:17], v[0:3], off offset:528
	s_cbranch_vccnz .LBB0_1043
	s_andn2_b64 vcc, exec, s[4:5]
	s_cbranch_vccnz .LBB0_1042
	s_barrier
	s_branch .LBB0_1042
.LBB0_1057:
	s_setprio 0
	s_waitcnt vmcnt(0)
	s_barrier
.LBB0_1058:
	s_waitcnt vmcnt(0)
	s_barrier
	s_mov_b64 s[0:1], exec
	v_readlane_b32 s2, v252, 4
	v_readlane_b32 s3, v252, 5
	s_and_b64 s[2:3], s[0:1], s[2:3]
	s_mov_b64 exec, s[2:3]
	s_cbranch_execz .LBB0_1110
	v_readlane_b32 s2, v254, 4
	s_waitcnt vmcnt(0) expcnt(0) lgkmcnt(0)
	s_nop 0
	v_mov_b32_e32 v0, s2
	ds_read_b32 v2, v0
	v_readlane_b32 s2, v254, 5
	s_waitcnt lgkmcnt(0)
	v_cmp_ne_u32_e32 vcc, 0, v2
	v_mov_b32_e32 v0, s2
	ds_read_b32 v0, v0
	s_cbranch_vccnz .LBB0_1074
	s_mov_b32 s8, 1
	s_branch .LBB0_1062

; #define PG8_STAGE(bufoff, gbase, voff) do { _Pragma("unroll") for (int _i = 0; _i < 2; ++_i) \
;         __builtin_amdgcn_global_load_lds((const unsigned*)((const char*)(gbase) + (voff)[_i]), (PG8_LAS unsigned*)(lds + (bufoff) + ldsw + _i * 8192), 16, 0, 0); } while (0)
; #define PG8_LDA(dst, b, h) do { _Pragma("unroll") for (int m = 0; m < 4; ++m) _Pragma("unroll") for (int k = 0; k < 2; ++k) dst[m][k] = *(const PG8_LAS bf16x8*)(lds + PG8_SA(b, h) + aoff + m * 2048 + k * 1024); } while (0)
; #define PG8_LDB(dst, b, h) do { _Pragma("unroll") for (int n = 0; n < 2; ++n) _Pragma("unroll") for (int k = 0; k < 2; ++k) dst[n][k] = *(const PG8_LAS bf16x8*)(lds + PG8_SB(b, h) + boff + n * 2048 + k * 1024); } while (0)
; #define PG8_MMA(ai, bj, At, Bt) do { __builtin_amdgcn_s_setprio(1); _Pragma("unroll") for (int m = 0; m < 4; ++m) _Pragma("unroll") for (int n = 0; n < 2; ++n) _Pragma("unroll") for (int k = 0; k < 2; ++k) \
;         acc[ai][bj][m][n] = __builtin_amdgcn_mfma_f32_16x16x32_bf16(Bt[n][k], At[m][k], acc[ai][bj][m][n], 0, 0, 0); __builtin_amdgcn_s_setprio(0); } while (0)
; #define PG8_WAIT_V(n) asm volatile("s_waitcnt vmcnt(" #n ")" ::: "memory")
; #define PG8_WAIT_L(n) asm volatile("s_waitcnt lgkmcnt(" #n ")" ::: "memory")
; #define PG8_BAR __builtin_amdgcn_s_barrier()
; #define PG8_SCHED __builtin_amdgcn_sched_barrier(0)
; template <class Epi, class Sched, bool ALIGN_EPI = false, bool SP2 = false>
; __device__ __forceinline__ void gemm_phase(PG8_LAS unsigned char* lds, const Gemm g, const Sched& S, const Epi& E) {
;     ...
;             PG8_LDB(B0, 0, 0); PG8_LDB(B1, 0, 1); PG8_SCHED; PG8_LDA(At, 0, 0); PG8_STAGE(PG8_SA(1, 1), a1 + hstep, voffA);
;             PG8_WAIT_V(8); PG8_WAIT_L(0); PG8_BAR; PG8_MMA(0, 0, At, B0); PG8_MMA(0, 1, At, B1); PG8_BAR; PG8_SCHED;
;             PG8_LDA(At, 0, 1); PG8_STAGE(PG8_SB(0, 0), b2, voffB); PG8_STAGE(PG8_SB(0, 1), b2 + hstep, voffB); PG8_STAGE(PG8_SA(0, 0), a2, voffA);
;             PG8_WAIT_V(8); PG8_WAIT_L(0); PG8_BAR; PG8_MMA(1, 0, At, B0); PG8_MMA(1, 1, At, B1); PG8_BAR; PG8_SCHED;
.LBB0_1176:
	s_add_u32 s16, s14, 0xfffc0080
	s_addc_u32 s17, s15, -1
	s_add_i32 s44, 0, 0x10000
	s_cmp_eq_u32 s39, 12
	s_cselect_b32 s19, s9, s17
	s_cselect_b32 s18, s35, s16
	v_add_u32_e32 v138, s44, v141
	s_cselect_b32 s17, s7, s38
	s_cselect_b32 s16, s36, s37
	s_add_i32 s46, 0, 0x14000
	ds_read_b128 v[144:147], v138
	ds_read_b128 v[148:151], v138 offset:1024
	ds_read_b128 v[152:155], v138 offset:2048
	ds_read_b128 v[156:159], v138 offset:3072
	v_add_u32_e32 v138, s46, v141
	ds_read_b128 v[160:163], v138
	ds_read_b128 v[164:167], v138 offset:1024
	ds_read_b128 v[168:171], v138 offset:2048
	ds_read_b128 v[172:175], v138 offset:3072
	v_lshl_add_u64 v[138:139], s[14:15], 0, v[134:135]
	s_add_i32 m0, s25, 0xc000
	ds_read_b128 v[176:179], v143
	ds_read_b128 v[180:183], v143 offset:1024
	ds_read_b128 v[184:187], v143 offset:2048
	ds_read_b128 v[188:191], v143 offset:3072
	ds_read_b128 v[206:209], v143 offset:4096
	ds_read_b128 v[210:213], v143 offset:5120
	ds_read_b128 v[214:217], v143 offset:6144
	ds_read_b128 v[218:221], v143 offset:7168
	global_load_lds_dwordx4 v[138:139], off
	v_lshl_add_u64 v[138:139], s[14:15], 0, v[136:137]
	s_add_i32 m0, s25, 0xe000
	s_nop 0
	global_load_lds_dwordx4 v[138:139], off
	s_waitcnt vmcnt(8)
	s_waitcnt lgkmcnt(0)
	s_barrier
	s_waitcnt lgkmcnt(0)
	v_mfma_f32_16x16x32_bf16 v[124:127], v[144:147], v[176:179], v[124:127]
	v_mfma_f32_16x16x32_bf16 v[116:119], v[152:155], v[176:179], v[116:119]
	v_mfma_f32_16x16x32_bf16 v[108:111], v[144:147], v[184:187], v[108:111]
	v_mfma_f32_16x16x32_bf16 v[100:103], v[152:155], v[184:187], v[100:103]
	v_mfma_f32_16x16x32_bf16 v[92:95], v[144:147], v[206:209], v[92:95]
	v_mfma_f32_16x16x32_bf16 v[84:87], v[152:155], v[206:209], v[84:87]
	v_mfma_f32_16x16x32_bf16 v[76:79], v[144:147], v[214:217], v[76:79]
	v_mfma_f32_16x16x32_bf16 v[68:71], v[152:155], v[214:217], v[68:71]
	v_mfma_f32_16x16x32_bf16 v[124:127], v[148:151], v[180:183], v[124:127]
	v_mfma_f32_16x16x32_bf16 v[116:119], v[156:159], v[180:183], v[116:119]
	v_mfma_f32_16x16x32_bf16 v[108:111], v[148:151], v[188:191], v[108:111]
	v_mfma_f32_16x16x32_bf16 v[100:103], v[156:159], v[188:191], v[100:103]
	v_mfma_f32_16x16x32_bf16 v[92:95], v[148:151], v[210:213], v[92:95]
	v_mfma_f32_16x16x32_bf16 v[84:87], v[156:159], v[210:213], v[84:87]
	v_mfma_f32_16x16x32_bf16 v[76:79], v[148:151], v[218:221], v[76:79]
	v_mfma_f32_16x16x32_bf16 v[68:71], v[156:159], v[218:221], v[68:71]
	v_mfma_f32_16x16x32_bf16 v[120:123], v[160:163], v[176:179], v[120:123]
	v_mfma_f32_16x16x32_bf16 v[112:115], v[168:171], v[176:179], v[112:115]
	v_mfma_f32_16x16x32_bf16 v[104:107], v[160:163], v[184:187], v[104:107]
	v_mfma_f32_16x16x32_bf16 v[96:99], v[168:171], v[184:187], v[96:99]
	v_mfma_f32_16x16x32_bf16 v[88:91], v[160:163], v[206:209], v[88:91]
	v_mfma_f32_16x16x32_bf16 v[80:83], v[168:171], v[206:209], v[80:83]
	v_mfma_f32_16x16x32_bf16 v[72:75], v[160:163], v[214:217], v[72:75]
	v_mfma_f32_16x16x32_bf16 v[64:67], v[168:171], v[214:217], v[64:67]
	v_mfma_f32_16x16x32_bf16 v[120:123], v[164:167], v[180:183], v[120:123]
	v_mfma_f32_16x16x32_bf16 v[112:115], v[172:175], v[180:183], v[112:115]
	v_mfma_f32_16x16x32_bf16 v[104:107], v[164:167], v[188:191], v[104:107]
	v_mfma_f32_16x16x32_bf16 v[96:99], v[172:175], v[188:191], v[96:99]
	v_mfma_f32_16x16x32_bf16 v[88:91], v[164:167], v[210:213], v[88:91]
	v_mfma_f32_16x16x32_bf16 v[80:83], v[172:175], v[210:213], v[80:83]
	v_mfma_f32_16x16x32_bf16 v[72:75], v[164:167], v[218:221], v[72:75]
	v_mfma_f32_16x16x32_bf16 v[64:67], v[172:175], v[218:221], v[64:67]
	s_barrier
	s_add_i32 s44, s44, s24
	v_lshl_add_u64 v[138:139], s[16:17], 0, v[192:193]
	s_mov_b32 m0, s44
	ds_read_b128 v[176:179], v143 offset:16384
	ds_read_b128 v[180:183], v143 offset:17408
	ds_read_b128 v[184:187], v143 offset:18432
	ds_read_b128 v[188:191], v143 offset:19456
	ds_read_b128 v[206:209], v143 offset:20480
	ds_read_b128 v[210:213], v143 offset:21504
	ds_read_b128 v[214:217], v143 offset:22528
	ds_read_b128 v[218:221], v143 offset:23552
	global_load_lds_dwordx4 v[138:139], off
	s_add_i32 m0, s44, 0x2000
	s_add_u32 s44, s16, 0x40000
	v_lshl_add_u64 v[222:223], s[16:17], 0, v[128:129]
	s_addc_u32 s45, s17, 0
	s_add_i32 s46, s46, s24
	global_load_lds_dwordx4 v[222:223], off
	v_lshl_add_u64 v[224:225], s[44:45], 0, v[192:193]
	s_mov_b32 m0, s46
	v_lshl_add_u64 v[226:227], s[18:19], 0, v[130:131]
	global_load_lds_dwordx4 v[224:225], off
	v_lshl_add_u64 v[224:225], s[44:45], 0, v[128:129]
	s_add_i32 m0, s46, 0x2000
	s_nop 0
	global_load_lds_dwordx4 v[224:225], off
	v_lshl_add_u64 v[224:225], s[18:19], 0, v[132:133]
	s_mov_b32 m0, s25
	s_nop 0
	global_load_lds_dwordx4 v[224:225], off
	s_mov_b32 m0, s26
	s_nop 0
	global_load_lds_dwordx4 v[226:227], off
	s_waitcnt vmcnt(8)
	s_waitcnt lgkmcnt(0)
	s_barrier
; #define PG8_STAGE(bufoff, gbase, voff) do { _Pragma("unroll") for (int _i = 0; _i < 2; ++_i) \
;         __builtin_amdgcn_global_load_lds((const unsigned*)((const char*)(gbase) + (voff)[_i]), (PG8_LAS unsigned*)(lds + (bufoff) + ldsw + _i * 8192), 16, 0, 0); } while (0)
; #define PG8_LDA(dst, b, h) do { _Pragma("unroll") for (int m = 0; m < 4; ++m) _Pragma("unroll") for (int k = 0; k < 2; ++k) dst[m][k] = *(const PG8_LAS bf16x8*)(lds + PG8_SA(b, h) + aoff + m * 2048 + k * 1024); } while (0)
; #define PG8_LDB(dst, b, h) do { _Pragma("unroll") for (int n = 0; n < 2; ++n) _Pragma("unroll") for (int k = 0; k < 2; ++k) dst[n][k] = *(const PG8_LAS bf16x8*)(lds + PG8_SB(b, h) + boff + n * 2048 + k * 1024); } while (0)
; #define PG8_MMA(ai, bj, At, Bt) do { __builtin_amdgcn_s_setprio(1); _Pragma("unroll") for (int m = 0; m < 4; ++m) _Pragma("unroll") for (int n = 0; n < 2; ++n) _Pragma("unroll") for (int k = 0; k < 2; ++k) \
;         acc[ai][bj][m][n] = __builtin_amdgcn_mfma_f32_16x16x32_bf16(Bt[n][k], At[m][k], acc[ai][bj][m][n], 0, 0, 0); __builtin_amdgcn_s_setprio(0); } while (0)
; #define PG8_WAIT_V(n) asm volatile("s_waitcnt vmcnt(" #n ")" ::: "memory")
; #define PG8_WAIT_L(n) asm volatile("s_waitcnt lgkmcnt(" #n ")" ::: "memory")
; #define PG8_BAR __builtin_amdgcn_s_barrier()
; #define PG8_SCHED __builtin_amdgcn_sched_barrier(0)
; template <class Epi, class Sched, bool ALIGN_EPI = false, bool SP2 = false>
; __device__ __forceinline__ void gemm_phase(PG8_LAS unsigned char* lds, const Gemm g, const Sched& S, const Epi& E) {
;     ...
;             PG8_WAIT_V(8); PG8_WAIT_L(0); PG8_BAR; PG8_MMA(1, 0, At, B0); PG8_MMA(1, 1, At, B1); PG8_BAR; PG8_SCHED;
;             PG8_LDB(B0, 1, 0); PG8_LDB(B1, 1, 1); PG8_SCHED; PG8_LDA(At, 1, 0); PG8_STAGE(PG8_SA(0, 1), a2 + hstep, voffA);
;             PG8_WAIT_V(8); PG8_WAIT_L(0); PG8_BAR; PG8_MMA(0, 0, At, B0); PG8_MMA(0, 1, At, B1); PG8_BAR; PG8_SCHED;
	s_waitcnt lgkmcnt(0)
	v_mfma_f32_16x16x32_bf16 v[60:63], v[144:147], v[176:179], v[60:63]
	v_mfma_f32_16x16x32_bf16 v[52:55], v[152:155], v[176:179], v[52:55]
	v_mfma_f32_16x16x32_bf16 v[44:47], v[144:147], v[184:187], v[44:47]
	v_mfma_f32_16x16x32_bf16 v[36:39], v[152:155], v[184:187], v[36:39]
	v_mfma_f32_16x16x32_bf16 v[28:31], v[144:147], v[206:209], v[28:31]
	v_mfma_f32_16x16x32_bf16 v[20:23], v[152:155], v[206:209], v[20:23]
	v_mfma_f32_16x16x32_bf16 v[12:15], v[144:147], v[214:217], v[12:15]
	v_mfma_f32_16x16x32_bf16 v[4:7], v[152:155], v[214:217], v[4:7]
	v_mfma_f32_16x16x32_bf16 v[60:63], v[148:151], v[180:183], v[60:63]
	v_mfma_f32_16x16x32_bf16 v[52:55], v[156:159], v[180:183], v[52:55]
	v_mfma_f32_16x16x32_bf16 v[44:47], v[148:151], v[188:191], v[44:47]
	v_mfma_f32_16x16x32_bf16 v[36:39], v[156:159], v[188:191], v[36:39]
	v_mfma_f32_16x16x32_bf16 v[28:31], v[148:151], v[210:213], v[28:31]
	v_mfma_f32_16x16x32_bf16 v[20:23], v[156:159], v[210:213], v[20:23]
	v_mfma_f32_16x16x32_bf16 v[12:15], v[148:151], v[218:221], v[12:15]
	v_mfma_f32_16x16x32_bf16 v[4:7], v[156:159], v[218:221], v[4:7]
	v_mfma_f32_16x16x32_bf16 v[56:59], v[160:163], v[176:179], v[56:59]
	v_mfma_f32_16x16x32_bf16 v[48:51], v[168:171], v[176:179], v[48:51]
	v_mfma_f32_16x16x32_bf16 v[40:43], v[160:163], v[184:187], v[40:43]
	v_mfma_f32_16x16x32_bf16 v[32:35], v[168:171], v[184:187], v[32:35]
	v_mfma_f32_16x16x32_bf16 v[24:27], v[160:163], v[206:209], v[24:27]
	v_mfma_f32_16x16x32_bf16 v[16:19], v[168:171], v[206:209], v[16:19]
	v_mfma_f32_16x16x32_bf16 v[8:11], v[160:163], v[214:217], v[8:11]
	v_mfma_f32_16x16x32_bf16 v[0:3], v[168:171], v[214:217], v[0:3]
	v_mfma_f32_16x16x32_bf16 v[56:59], v[164:167], v[180:183], v[56:59]
	v_mfma_f32_16x16x32_bf16 v[48:51], v[172:175], v[180:183], v[48:51]
	v_mfma_f32_16x16x32_bf16 v[40:43], v[164:167], v[188:191], v[40:43]
	v_mfma_f32_16x16x32_bf16 v[32:35], v[172:175], v[188:191], v[32:35]
	v_mfma_f32_16x16x32_bf16 v[24:27], v[164:167], v[210:213], v[24:27]
	v_mfma_f32_16x16x32_bf16 v[16:19], v[172:175], v[210:213], v[16:19]
	v_mfma_f32_16x16x32_bf16 v[8:11], v[164:167], v[218:221], v[8:11]
	v_mfma_f32_16x16x32_bf16 v[0:3], v[172:175], v[218:221], v[0:3]
	s_barrier
	s_add_i32 s44, 0, 0x18000
	s_add_i32 s45, 0, 0x1c000
	v_add_u32_e32 v156, s44, v141
	v_add_u32_e32 v172, s45, v141
	ds_read_b128 v[144:147], v156
	ds_read_b128 v[148:151], v156 offset:1024
	ds_read_b128 v[152:155], v156 offset:2048
	ds_read_b128 v[156:159], v156 offset:3072
	ds_read_b128 v[160:163], v172
	ds_read_b128 v[164:167], v172 offset:1024
	ds_read_b128 v[168:171], v172 offset:2048
	ds_read_b128 v[172:175], v172 offset:3072
	s_add_u32 s18, s18, 0x40000
	s_addc_u32 s19, s19, 0
	s_mov_b32 m0, s27
	v_lshl_add_u64 v[228:229], s[18:19], 0, v[132:133]
	ds_read_b128 v[176:179], v143 offset:32768
	ds_read_b128 v[180:183], v143 offset:33792
	ds_read_b128 v[184:187], v143 offset:34816
	ds_read_b128 v[188:191], v143 offset:35840
	ds_read_b128 v[206:209], v143 offset:36864
	ds_read_b128 v[210:213], v143 offset:37888
	ds_read_b128 v[214:217], v143 offset:38912
	ds_read_b128 v[218:221], v143 offset:39936
	global_load_lds_dwordx4 v[228:229], off
	v_lshl_add_u64 v[228:229], s[18:19], 0, v[130:131]
	s_mov_b32 m0, s28
	s_nop 0
	global_load_lds_dwordx4 v[228:229], off
	s_waitcnt vmcnt(8)
	s_waitcnt lgkmcnt(0)
	s_barrier
	s_waitcnt lgkmcnt(0)
	v_mfma_f32_16x16x32_bf16 v[124:127], v[144:147], v[176:179], v[124:127]
	v_mfma_f32_16x16x32_bf16 v[116:119], v[152:155], v[176:179], v[116:119]
	v_mfma_f32_16x16x32_bf16 v[108:111], v[144:147], v[184:187], v[108:111]
	v_mfma_f32_16x16x32_bf16 v[100:103], v[152:155], v[184:187], v[100:103]
	v_mfma_f32_16x16x32_bf16 v[92:95], v[144:147], v[206:209], v[92:95]
	v_mfma_f32_16x16x32_bf16 v[84:87], v[152:155], v[206:209], v[84:87]
	v_mfma_f32_16x16x32_bf16 v[76:79], v[144:147], v[214:217], v[76:79]
	v_mfma_f32_16x16x32_bf16 v[68:71], v[152:155], v[214:217], v[68:71]
	v_mfma_f32_16x16x32_bf16 v[124:127], v[148:151], v[180:183], v[124:127]
	v_mfma_f32_16x16x32_bf16 v[116:119], v[156:159], v[180:183], v[116:119]
	v_mfma_f32_16x16x32_bf16 v[108:111], v[148:151], v[188:191], v[108:111]
	v_mfma_f32_16x16x32_bf16 v[100:103], v[156:159], v[188:191], v[100:103]
	v_mfma_f32_16x16x32_bf16 v[92:95], v[148:151], v[210:213], v[92:95]
	v_mfma_f32_16x16x32_bf16 v[84:87], v[156:159], v[210:213], v[84:87]
	v_mfma_f32_16x16x32_bf16 v[76:79], v[148:151], v[218:221], v[76:79]
	v_mfma_f32_16x16x32_bf16 v[68:71], v[156:159], v[218:221], v[68:71]
	v_mfma_f32_16x16x32_bf16 v[120:123], v[160:163], v[176:179], v[120:123]
	v_mfma_f32_16x16x32_bf16 v[112:115], v[168:171], v[176:179], v[112:115]
	v_mfma_f32_16x16x32_bf16 v[104:107], v[160:163], v[184:187], v[104:107]
	v_mfma_f32_16x16x32_bf16 v[96:99], v[168:171], v[184:187], v[96:99]
	v_mfma_f32_16x16x32_bf16 v[88:91], v[160:163], v[206:209], v[88:91]
	v_mfma_f32_16x16x32_bf16 v[80:83], v[168:171], v[206:209], v[80:83]
	v_mfma_f32_16x16x32_bf16 v[72:75], v[160:163], v[214:217], v[72:75]
	v_mfma_f32_16x16x32_bf16 v[64:67], v[168:171], v[214:217], v[64:67]
	v_mfma_f32_16x16x32_bf16 v[120:123], v[164:167], v[180:183], v[120:123]
	v_mfma_f32_16x16x32_bf16 v[112:115], v[172:175], v[180:183], v[112:115]
	v_mfma_f32_16x16x32_bf16 v[104:107], v[164:167], v[188:191], v[104:107]
	v_mfma_f32_16x16x32_bf16 v[96:99], v[172:175], v[188:191], v[96:99]
	v_mfma_f32_16x16x32_bf16 v[88:91], v[164:167], v[210:213], v[88:91]
	v_mfma_f32_16x16x32_bf16 v[80:83], v[172:175], v[210:213], v[80:83]
	v_mfma_f32_16x16x32_bf16 v[72:75], v[164:167], v[218:221], v[72:75]
	v_mfma_f32_16x16x32_bf16 v[64:67], v[172:175], v[218:221], v[64:67]
	s_barrier
; __device__ __forceinline__ unsigned cvt_pk_bf16(float lo, float hi) { unsigned r; asm volatile("v_cvt_pk_bf16_f32 %0, %1, %2" : "=v"(r) : "v"(lo), "v"(hi)); return r; }
; #define PG8_STAGE(bufoff, gbase, voff) do { _Pragma("unroll") for (int _i = 0; _i < 2; ++_i) \
;         __builtin_amdgcn_global_load_lds((const unsigned*)((const char*)(gbase) + (voff)[_i]), (PG8_LAS unsigned*)(lds + (bufoff) + ldsw + _i * 8192), 16, 0, 0); } while (0)
; #define PG8_LDA(dst, b, h) do { _Pragma("unroll") for (int m = 0; m < 4; ++m) _Pragma("unroll") for (int k = 0; k < 2; ++k) dst[m][k] = *(const PG8_LAS bf16x8*)(lds + PG8_SA(b, h) + aoff + m * 2048 + k * 1024); } while (0)
; #define PG8_MMA(ai, bj, At, Bt) do { __builtin_amdgcn_s_setprio(1); _Pragma("unroll") for (int m = 0; m < 4; ++m) _Pragma("unroll") for (int n = 0; n < 2; ++n) _Pragma("unroll") for (int k = 0; k < 2; ++k) \
;         acc[ai][bj][m][n] = __builtin_amdgcn_mfma_f32_16x16x32_bf16(Bt[n][k], At[m][k], acc[ai][bj][m][n], 0, 0, 0); __builtin_amdgcn_s_setprio(0); } while (0)
; #define PG8_WAIT_V(n) asm volatile("s_waitcnt vmcnt(" #n ")" ::: "memory")
; #define PG8_BAR __builtin_amdgcn_s_barrier()
; template <class Epi, class Sched, bool ALIGN_EPI = false, bool SP2 = false>
; __device__ __forceinline__ void gemm_phase(PG8_LAS unsigned char* lds, const Gemm g, const Sched& S, const Epi& E) {
;     ...
;             PG8_LDA(At, 1, 1); PG8_STAGE(PG8_SB(1, 0), b3, voffB); PG8_STAGE(PG8_SB(1, 1), b3 + hstep, voffB); PG8_STAGE(PG8_SA(1, 0), a3, voffA);
;             PG8_WAIT_V(8); PG8_WAIT_L(0); PG8_BAR; PG8_MMA(1, 0, At, B0); PG8_MMA(1, 1, At, B1); PG8_BAR; PG8_SCHED;
;     DI void operator()(const pg8::f32x4 (&acc)[2][2][4][2], const pg8::Unit& u, int wr, int wc, int fr, int fq) const {
;     ...
;             for (int m = 0; m < 4; ++m) { bf16* rowp = O + (size_t)(row0 + ai * 128 + m * 16) * FF + col0;
;                 float hv[8];
; #pragma unroll
;                 for (int n = 0; n < 2; ++n)
; #pragma unroll
;                     for (int j = 0; j < 4; ++j) { const float g = acc[ai][0][m][n][j], up = acc[ai][1][m][n][j]; hv[4 * n + j] = g * __builtin_amdgcn_rcpf(1.f + __expf(-g)) * up; }
;                 v4u w; w.x = pg8::cvt_pk_bf16(hv[0], hv[1]); w.y = pg8::cvt_pk_bf16(hv[2], hv[3]); w.z = pg8::cvt_pk_bf16(hv[4], hv[5]); w.w = pg8::cvt_pk_bf16(hv[6], hv[7]);
;                 *(v4u*)rowp = w; }
	s_add_i32 s18, s44, s24
	v_lshl_add_u64 v[138:139], v[138:139], 0, s[72:73]
	s_mov_b32 m0, s18
	ds_read_b128 v[176:179], v143 offset:49152
	ds_read_b128 v[180:183], v143 offset:50176
	ds_read_b128 v[184:187], v143 offset:51200
	ds_read_b128 v[188:191], v143 offset:52224
	ds_read_b128 v[206:209], v143 offset:53248
	ds_read_b128 v[210:213], v143 offset:54272
	ds_read_b128 v[214:217], v143 offset:55296
	ds_read_b128 v[218:221], v143 offset:56320
	global_load_lds_dwordx4 v[138:139], off
	s_add_i32 m0, s18, 0x2000
	s_add_u32 s16, s16, 0x40080
	v_lshl_add_u64 v[138:139], v[222:223], 0, s[72:73]
	s_addc_u32 s17, s17, 0
	s_add_i32 s18, s45, s24
	global_load_lds_dwordx4 v[138:139], off
	v_lshl_add_u64 v[138:139], s[16:17], 0, v[192:193]
	s_mov_b32 m0, s18
	s_nop 0
	global_load_lds_dwordx4 v[138:139], off
	v_lshl_add_u64 v[138:139], s[16:17], 0, v[128:129]
	s_add_i32 m0, s18, 0x2000
	s_nop 0
	global_load_lds_dwordx4 v[138:139], off
	v_lshl_add_u64 v[138:139], v[224:225], 0, s[72:73]
	s_mov_b32 m0, s29
	s_nop 0
	global_load_lds_dwordx4 v[138:139], off
	v_lshl_add_u64 v[138:139], v[226:227], 0, s[72:73]
	s_mov_b32 m0, s30
	s_nop 0
	global_load_lds_dwordx4 v[138:139], off
	s_waitcnt vmcnt(8)
	s_waitcnt lgkmcnt(0)
	s_barrier
	s_waitcnt lgkmcnt(0)
	v_mfma_f32_16x16x32_bf16 v[60:63], v[144:147], v[176:179], v[60:63]
	v_mfma_f32_16x16x32_bf16 v[52:55], v[152:155], v[176:179], v[52:55]
	v_mfma_f32_16x16x32_bf16 v[44:47], v[144:147], v[184:187], v[44:47]
	v_mfma_f32_16x16x32_bf16 v[36:39], v[152:155], v[184:187], v[36:39]
	v_mfma_f32_16x16x32_bf16 v[28:31], v[144:147], v[206:209], v[28:31]
	v_mfma_f32_16x16x32_bf16 v[20:23], v[152:155], v[206:209], v[20:23]
	v_mfma_f32_16x16x32_bf16 v[12:15], v[144:147], v[214:217], v[12:15]
	v_mfma_f32_16x16x32_bf16 v[4:7], v[152:155], v[214:217], v[4:7]
	v_mfma_f32_16x16x32_bf16 v[60:63], v[148:151], v[180:183], v[60:63]
	v_mfma_f32_16x16x32_bf16 v[52:55], v[156:159], v[180:183], v[52:55]
	v_mfma_f32_16x16x32_bf16 v[44:47], v[148:151], v[188:191], v[44:47]
	v_mfma_f32_16x16x32_bf16 v[36:39], v[156:159], v[188:191], v[36:39]
	v_mfma_f32_16x16x32_bf16 v[28:31], v[148:151], v[210:213], v[28:31]
	v_mfma_f32_16x16x32_bf16 v[20:23], v[156:159], v[210:213], v[20:23]
	v_mfma_f32_16x16x32_bf16 v[12:15], v[148:151], v[218:221], v[12:15]
	v_mfma_f32_16x16x32_bf16 v[4:7], v[156:159], v[218:221], v[4:7]
	v_mfma_f32_16x16x32_bf16 v[56:59], v[160:163], v[176:179], v[56:59]
	v_mfma_f32_16x16x32_bf16 v[48:51], v[168:171], v[176:179], v[48:51]
	v_mfma_f32_16x16x32_bf16 v[40:43], v[160:163], v[184:187], v[40:43]
	v_mfma_f32_16x16x32_bf16 v[32:35], v[168:171], v[184:187], v[32:35]
	v_mfma_f32_16x16x32_bf16 v[24:27], v[160:163], v[206:209], v[24:27]
	v_mfma_f32_16x16x32_bf16 v[16:19], v[168:171], v[206:209], v[16:19]
	v_mfma_f32_16x16x32_bf16 v[8:11], v[160:163], v[214:217], v[8:11]
	v_mfma_f32_16x16x32_bf16 v[0:3], v[168:171], v[214:217], v[0:3]
	v_mfma_f32_16x16x32_bf16 v[56:59], v[164:167], v[180:183], v[56:59]
	v_mfma_f32_16x16x32_bf16 v[48:51], v[172:175], v[180:183], v[48:51]
	v_mfma_f32_16x16x32_bf16 v[40:43], v[164:167], v[188:191], v[40:43]
	v_mfma_f32_16x16x32_bf16 v[32:35], v[172:175], v[188:191], v[32:35]
	v_mfma_f32_16x16x32_bf16 v[24:27], v[164:167], v[210:213], v[24:27]
	v_mfma_f32_16x16x32_bf16 v[16:19], v[172:175], v[210:213], v[16:19]
	v_mfma_f32_16x16x32_bf16 v[8:11], v[164:167], v[218:221], v[8:11]
	v_mfma_f32_16x16x32_bf16 v[0:3], v[172:175], v[218:221], v[0:3]
	s_barrier
	s_add_i32 s39, s39, 2
	s_add_u32 s14, s14, 0x100
	s_addc_u32 s15, s15, 0
	s_add_u32 s37, s37, 0x100
	s_addc_u32 s38, s38, 0
	s_cmp_gt_u32 s39, 13
	s_cbranch_scc0 .LBB0_1176
	s_and_b64 vcc, exec, s[4:5]
	s_cbranch_vccz .LBB0_1179
	s_barrier
.LBB0_1179:
	v_mul_f32_e32 v145, 0xbfb8aa3b, v124
	v_exp_f32_e32 v145, v145
	v_lshl_or_b32 v146, s33, 7, v142
	v_lshl_add_u32 v144, s34, 8, v140
	v_ashrrev_i32_e32 v147, 31, v146
	v_add_f32_e32 v145, 1.0, v145
	v_rcp_f32_e32 v145, v145
	v_mov_b64_e32 v[138:139], s[2:3]
	s_movk_i32 s7, 0x1600
	v_mad_i64_i32 v[148:149], s[14:15], v144, s7, v[138:139]
	v_mul_f32_e32 v124, v124, v145
	v_mul_f32_e32 v120, v124, v120
	v_mul_f32_e32 v124, 0xbfb8aa3b, v125
	v_exp_f32_e32 v124, v124
	s_andn2_b64 vcc, exec, s[42:43]
	v_add_f32_e32 v124, 1.0, v124
	v_rcp_f32_e32 v124, v124
	s_nop 0
	v_mul_f32_e32 v124, v125, v124
	v_mul_f32_e32 v121, v124, v121
	v_mul_f32_e32 v124, 0xbfb8aa3b, v126
	v_exp_f32_e32 v124, v124
	s_nop 0
	v_add_f32_e32 v124, 1.0, v124
	v_rcp_f32_e32 v124, v124
	s_nop 0
	v_mul_f32_e32 v124, v126, v124
	v_mul_f32_e32 v122, v124, v122
	v_mul_f32_e32 v124, 0xbfb8aa3b, v127
	v_exp_f32_e32 v124, v124
	s_nop 0
	v_add_f32_e32 v124, 1.0, v124
	v_rcp_f32_e32 v124, v124
	s_nop 0
	v_mul_f32_e32 v124, v127, v124
	v_mul_f32_e32 v123, v124, v123
	v_mul_f32_e32 v124, 0xbfb8aa3b, v116
	v_exp_f32_e32 v124, v124
	s_nop 0
	v_add_f32_e32 v124, 1.0, v124
	v_rcp_f32_e32 v124, v124
	s_nop 0
	v_mul_f32_e32 v116, v116, v124
	v_mul_f32_e32 v116, v116, v112
	v_mul_f32_e32 v112, 0xbfb8aa3b, v117
	v_exp_f32_e32 v112, v112
	s_nop 0
	v_add_f32_e32 v112, 1.0, v112
	v_rcp_f32_e32 v112, v112
	s_nop 0
	v_mul_f32_e32 v112, v117, v112
	v_mul_f32_e32 v117, v112, v113
	v_mul_f32_e32 v112, 0xbfb8aa3b, v118
	v_exp_f32_e32 v112, v112
	s_nop 0
	v_add_f32_e32 v112, 1.0, v112
	v_rcp_f32_e32 v112, v112
	s_nop 0
	v_mul_f32_e32 v112, v118, v112
	v_mul_f32_e32 v124, v112, v114
	v_mul_f32_e32 v112, 0xbfb8aa3b, v119
	v_exp_f32_e32 v112, v112
	v_cvt_pk_bf16_f32 v114, v120, v121
	s_nop 0
	v_add_f32_e32 v112, 1.0, v112
	v_rcp_f32_e32 v112, v112
	s_nop 0
	v_mul_f32_e32 v112, v119, v112
	v_mul_f32_e32 v125, v112, v115
	v_lshlrev_b64 v[112:113], 1, v[146:147]
; __device__ __forceinline__ unsigned cvt_pk_bf16(float lo, float hi) { unsigned r; asm volatile("v_cvt_pk_bf16_f32 %0, %1, %2" : "=v"(r) : "v"(lo), "v"(hi)); return r; }
;     DI void operator()(const pg8::f32x4 (&acc)[2][2][4][2], const pg8::Unit& u, int wr, int wc, int fr, int fq) const {
;     ...
;             for (int m = 0; m < 4; ++m) { bf16* rowp = O + (size_t)(row0 + ai * 128 + m * 16) * FF + col0;
;                 float hv[8];
; #pragma unroll
;                 for (int n = 0; n < 2; ++n)
; #pragma unroll
;                     for (int j = 0; j < 4; ++j) { const float g = acc[ai][0][m][n][j], up = acc[ai][1][m][n][j]; hv[4 * n + j] = g * __builtin_amdgcn_rcpf(1.f + __expf(-g)) * up; }
;                 v4u w; w.x = pg8::cvt_pk_bf16(hv[0], hv[1]); w.y = pg8::cvt_pk_bf16(hv[2], hv[3]); w.z = pg8::cvt_pk_bf16(hv[4], hv[5]); w.w = pg8::cvt_pk_bf16(hv[6], hv[7]);
;                 *(v4u*)rowp = w; }
	v_lshl_add_u64 v[118:119], v[148:149], 0, v[112:113]
	v_cvt_pk_bf16_f32 v115, v122, v123
	v_cvt_pk_bf16_f32 v116, v116, v117
	v_cvt_pk_bf16_f32 v117, v124, v125
	global_store_dwordx4 v[118:119], v[114:117], off
	s_nop 1
	v_mul_f32_e32 v116, 0xbfb8aa3b, v108
	v_exp_f32_e32 v116, v116
	v_or_b32_e32 v114, 16, v144
	v_mad_i64_i32 v[114:115], s[14:15], v114, s7, v[138:139]
	v_add_f32_e32 v116, 1.0, v116
	v_rcp_f32_e32 v116, v116
	s_nop 0
	v_mul_f32_e32 v108, v108, v116
	v_mul_f32_e32 v104, v108, v104
	v_mul_f32_e32 v108, 0xbfb8aa3b, v109
	v_exp_f32_e32 v108, v108
	s_nop 0
	v_add_f32_e32 v108, 1.0, v108
	v_rcp_f32_e32 v108, v108
	s_nop 0
	v_mul_f32_e32 v108, v109, v108
	v_mul_f32_e32 v105, v108, v105
	v_mul_f32_e32 v108, 0xbfb8aa3b, v110
	v_exp_f32_e32 v108, v108
	s_nop 0
	v_add_f32_e32 v108, 1.0, v108
	v_rcp_f32_e32 v108, v108
	s_nop 0
	v_mul_f32_e32 v108, v110, v108
	v_mul_f32_e32 v106, v108, v106
	v_mul_f32_e32 v108, 0xbfb8aa3b, v111
	v_exp_f32_e32 v108, v108
	s_nop 0
	v_add_f32_e32 v108, 1.0, v108
	v_rcp_f32_e32 v108, v108
	s_nop 0
	v_mul_f32_e32 v108, v111, v108
	v_mul_f32_e32 v107, v108, v107
	v_mul_f32_e32 v108, 0xbfb8aa3b, v100
	v_exp_f32_e32 v108, v108
	s_nop 0
	v_add_f32_e32 v108, 1.0, v108
	v_rcp_f32_e32 v108, v108
	s_nop 0
	v_mul_f32_e32 v100, v100, v108
	v_mul_f32_e32 v108, v100, v96
	v_mul_f32_e32 v96, 0xbfb8aa3b, v101
	v_exp_f32_e32 v96, v96
	s_nop 0
	v_add_f32_e32 v96, 1.0, v96
	v_rcp_f32_e32 v96, v96
	s_nop 0
	v_mul_f32_e32 v96, v101, v96
	v_mul_f32_e32 v109, v96, v97
	v_mul_f32_e32 v96, 0xbfb8aa3b, v102
	v_exp_f32_e32 v96, v96
	v_lshl_add_u64 v[100:101], v[114:115], 0, v[112:113]
	v_add_f32_e32 v96, 1.0, v96
	v_rcp_f32_e32 v96, v96
	s_nop 0
	v_mul_f32_e32 v96, v102, v96
	v_mul_f32_e32 v102, v96, v98
	v_mul_f32_e32 v96, 0xbfb8aa3b, v103
	v_exp_f32_e32 v96, v96
	s_nop 0
	v_add_f32_e32 v96, 1.0, v96
	v_rcp_f32_e32 v96, v96
	s_nop 0
	v_mul_f32_e32 v96, v103, v96
	v_mul_f32_e32 v99, v96, v99
	v_cvt_pk_bf16_f32 v96, v104, v105
	v_cvt_pk_bf16_f32 v97, v106, v107
	v_cvt_pk_bf16_f32 v98, v108, v109
	v_cvt_pk_bf16_f32 v99, v102, v99
	global_store_dwordx4 v[100:101], v[96:99], off
	s_nop 1
	v_mul_f32_e32 v98, 0xbfb8aa3b, v92
	v_exp_f32_e32 v98, v98
	v_or_b32_e32 v96, 32, v144
	v_mad_i64_i32 v[96:97], s[14:15], v96, s7, v[138:139]
	v_add_f32_e32 v98, 1.0, v98
	v_rcp_f32_e32 v98, v98
	s_nop 0
	v_mul_f32_e32 v92, v92, v98
	v_mul_f32_e32 v88, v92, v88
	v_mul_f32_e32 v92, 0xbfb8aa3b, v93
	v_exp_f32_e32 v92, v92
	s_nop 0
	v_add_f32_e32 v92, 1.0, v92
	v_rcp_f32_e32 v92, v92
	s_nop 0
	v_mul_f32_e32 v92, v93, v92
	v_mul_f32_e32 v89, v92, v89
	v_mul_f32_e32 v92, 0xbfb8aa3b, v94
	v_exp_f32_e32 v92, v92
	s_nop 0
	v_add_f32_e32 v92, 1.0, v92
	v_rcp_f32_e32 v92, v92
	s_nop 0
	v_mul_f32_e32 v92, v94, v92
	v_mul_f32_e32 v90, v92, v90
	v_mul_f32_e32 v92, 0xbfb8aa3b, v95
	v_exp_f32_e32 v92, v92
	s_nop 0
	v_add_f32_e32 v92, 1.0, v92
	v_rcp_f32_e32 v92, v92
	s_nop 0
	v_mul_f32_e32 v92, v95, v92
	v_mul_f32_e32 v91, v92, v91
	v_mul_f32_e32 v92, 0xbfb8aa3b, v84
	v_exp_f32_e32 v92, v92
	s_nop 0
	v_add_f32_e32 v92, 1.0, v92
	v_rcp_f32_e32 v92, v92
	s_nop 0
	v_mul_f32_e32 v84, v84, v92
	v_mul_f32_e32 v92, v84, v80
	v_mul_f32_e32 v80, 0xbfb8aa3b, v85
	v_exp_f32_e32 v80, v80
	s_nop 0
	v_add_f32_e32 v80, 1.0, v80
	v_rcp_f32_e32 v80, v80
	s_nop 0
	v_mul_f32_e32 v80, v85, v80
	v_mul_f32_e32 v93, v80, v81
	v_mul_f32_e32 v80, 0xbfb8aa3b, v86
	v_exp_f32_e32 v80, v80
	v_lshl_add_u64 v[84:85], v[96:97], 0, v[112:113]
	v_add_f32_e32 v80, 1.0, v80
	v_rcp_f32_e32 v80, v80
	s_nop 0
	v_mul_f32_e32 v80, v86, v80
	v_mul_f32_e32 v86, v80, v82
	v_mul_f32_e32 v80, 0xbfb8aa3b, v87
	v_exp_f32_e32 v80, v80
	s_nop 0
	v_add_f32_e32 v80, 1.0, v80
	v_rcp_f32_e32 v80, v80
	s_nop 0
	v_mul_f32_e32 v80, v87, v80
	v_mul_f32_e32 v83, v80, v83
	v_cvt_pk_bf16_f32 v80, v88, v89
	v_cvt_pk_bf16_f32 v81, v90, v91
	v_cvt_pk_bf16_f32 v82, v92, v93
	v_cvt_pk_bf16_f32 v83, v86, v83
	global_store_dwordx4 v[84:85], v[80:83], off
	s_nop 1
	v_mul_f32_e32 v82, 0xbfb8aa3b, v76
	v_exp_f32_e32 v82, v82
	v_or_b32_e32 v80, 48, v144
	v_mad_i64_i32 v[80:81], s[14:15], v80, s7, v[138:139]
	v_add_f32_e32 v82, 1.0, v82
	v_rcp_f32_e32 v82, v82
	s_nop 0
	v_mul_f32_e32 v76, v76, v82
	v_mul_f32_e32 v72, v76, v72
	v_mul_f32_e32 v76, 0xbfb8aa3b, v77
	v_exp_f32_e32 v76, v76
	s_nop 0
	v_add_f32_e32 v76, 1.0, v76
	v_rcp_f32_e32 v76, v76
	s_nop 0
	v_mul_f32_e32 v76, v77, v76
	v_mul_f32_e32 v73, v76, v73
	v_mul_f32_e32 v76, 0xbfb8aa3b, v78
	v_exp_f32_e32 v76, v76
	s_nop 0
	v_add_f32_e32 v76, 1.0, v76
	v_rcp_f32_e32 v76, v76
	s_nop 0
	v_mul_f32_e32 v76, v78, v76
	v_mul_f32_e32 v74, v76, v74
	v_mul_f32_e32 v76, 0xbfb8aa3b, v79
	v_exp_f32_e32 v76, v76
	s_nop 0
	v_add_f32_e32 v76, 1.0, v76
	v_rcp_f32_e32 v76, v76
	s_nop 0
	v_mul_f32_e32 v76, v79, v76
	v_mul_f32_e32 v75, v76, v75
	v_mul_f32_e32 v76, 0xbfb8aa3b, v68
	v_exp_f32_e32 v76, v76
	s_nop 0
	v_add_f32_e32 v76, 1.0, v76
	v_rcp_f32_e32 v76, v76
	s_nop 0
	v_mul_f32_e32 v68, v68, v76
	v_mul_f32_e32 v76, v68, v64
	v_mul_f32_e32 v64, 0xbfb8aa3b, v69
	v_exp_f32_e32 v64, v64
	s_nop 0
	v_add_f32_e32 v64, 1.0, v64
	v_rcp_f32_e32 v64, v64
	s_nop 0
	v_mul_f32_e32 v64, v69, v64
	v_mul_f32_e32 v77, v64, v65
	v_mul_f32_e32 v64, 0xbfb8aa3b, v70
	v_exp_f32_e32 v64, v64
	v_lshl_add_u64 v[68:69], v[80:81], 0, v[112:113]
	v_add_f32_e32 v64, 1.0, v64
	v_rcp_f32_e32 v64, v64
	s_nop 0
	v_mul_f32_e32 v64, v70, v64
	v_mul_f32_e32 v70, v64, v66
	v_mul_f32_e32 v64, 0xbfb8aa3b, v71
	v_exp_f32_e32 v64, v64
	s_nop 0
	v_add_f32_e32 v64, 1.0, v64
	v_rcp_f32_e32 v64, v64
	s_nop 0
	v_mul_f32_e32 v64, v71, v64
	v_mul_f32_e32 v67, v64, v67
	v_cvt_pk_bf16_f32 v64, v72, v73
	v_cvt_pk_bf16_f32 v65, v74, v75
; __device__ __forceinline__ unsigned cvt_pk_bf16(float lo, float hi) { unsigned r; asm volatile("v_cvt_pk_bf16_f32 %0, %1, %2" : "=v"(r) : "v"(lo), "v"(hi)); return r; }
;     DI void operator()(const pg8::f32x4 (&acc)[2][2][4][2], const pg8::Unit& u, int wr, int wc, int fr, int fq) const {
;     ...
;             for (int m = 0; m < 4; ++m) { bf16* rowp = O + (size_t)(row0 + ai * 128 + m * 16) * FF + col0;
;                 float hv[8];
; #pragma unroll
;                 for (int n = 0; n < 2; ++n)
; #pragma unroll
;                     for (int j = 0; j < 4; ++j) { const float g = acc[ai][0][m][n][j], up = acc[ai][1][m][n][j]; hv[4 * n + j] = g * __builtin_amdgcn_rcpf(1.f + __expf(-g)) * up; }
;                 v4u w; w.x = pg8::cvt_pk_bf16(hv[0], hv[1]); w.y = pg8::cvt_pk_bf16(hv[2], hv[3]); w.z = pg8::cvt_pk_bf16(hv[4], hv[5]); w.w = pg8::cvt_pk_bf16(hv[6], hv[7]);
;                 *(v4u*)rowp = w; }
	v_cvt_pk_bf16_f32 v66, v76, v77
	v_cvt_pk_bf16_f32 v67, v70, v67
	global_store_dwordx4 v[68:69], v[64:67], off
	s_nop 1
	v_mul_f32_e32 v66, 0xbfb8aa3b, v60
	v_exp_f32_e32 v66, v66
	v_add_u32_e32 v64, 0x80, v144
	v_mad_i64_i32 v[64:65], s[14:15], v64, s7, v[138:139]
	v_add_f32_e32 v66, 1.0, v66
	v_rcp_f32_e32 v66, v66
	s_nop 0
	v_mul_f32_e32 v60, v60, v66
	v_mul_f32_e32 v56, v60, v56
	v_mul_f32_e32 v60, 0xbfb8aa3b, v61
	v_exp_f32_e32 v60, v60
	s_nop 0
	v_add_f32_e32 v60, 1.0, v60
	v_rcp_f32_e32 v60, v60
	s_nop 0
	v_mul_f32_e32 v60, v61, v60
	v_mul_f32_e32 v57, v60, v57
	v_mul_f32_e32 v60, 0xbfb8aa3b, v62
	v_exp_f32_e32 v60, v60
	s_nop 0
	v_add_f32_e32 v60, 1.0, v60
	v_rcp_f32_e32 v60, v60
	s_nop 0
	v_mul_f32_e32 v60, v62, v60
	v_mul_f32_e32 v58, v60, v58
	v_mul_f32_e32 v60, 0xbfb8aa3b, v63
	v_exp_f32_e32 v60, v60
	s_nop 0
	v_add_f32_e32 v60, 1.0, v60
	v_rcp_f32_e32 v60, v60
	s_nop 0
	v_mul_f32_e32 v60, v63, v60
	v_mul_f32_e32 v59, v60, v59
	v_mul_f32_e32 v60, 0xbfb8aa3b, v52
	v_exp_f32_e32 v60, v60
	s_nop 0
	v_add_f32_e32 v60, 1.0, v60
	v_rcp_f32_e32 v60, v60
	s_nop 0
	v_mul_f32_e32 v52, v52, v60
	v_mul_f32_e32 v60, v52, v48
	v_mul_f32_e32 v48, 0xbfb8aa3b, v53
	v_exp_f32_e32 v48, v48
	s_nop 0
	v_add_f32_e32 v48, 1.0, v48
	v_rcp_f32_e32 v48, v48
	s_nop 0
	v_mul_f32_e32 v48, v53, v48
	v_mul_f32_e32 v61, v48, v49
	v_mul_f32_e32 v48, 0xbfb8aa3b, v54
	v_exp_f32_e32 v48, v48
	v_lshl_add_u64 v[52:53], v[64:65], 0, v[112:113]
	v_add_f32_e32 v48, 1.0, v48
	v_rcp_f32_e32 v48, v48
	s_nop 0
	v_mul_f32_e32 v48, v54, v48
	v_mul_f32_e32 v54, v48, v50
	v_mul_f32_e32 v48, 0xbfb8aa3b, v55
	v_exp_f32_e32 v48, v48
	s_nop 0
	v_add_f32_e32 v48, 1.0, v48
	v_rcp_f32_e32 v48, v48
	s_nop 0
	v_mul_f32_e32 v48, v55, v48
	v_mul_f32_e32 v51, v48, v51
	v_cvt_pk_bf16_f32 v48, v56, v57
	v_cvt_pk_bf16_f32 v49, v58, v59
	v_cvt_pk_bf16_f32 v50, v60, v61
	v_cvt_pk_bf16_f32 v51, v54, v51
	global_store_dwordx4 v[52:53], v[48:51], off
	s_nop 1
	v_mul_f32_e32 v50, 0xbfb8aa3b, v44
	v_exp_f32_e32 v50, v50
	v_add_u32_e32 v48, 0x90, v144
	v_mad_i64_i32 v[48:49], s[14:15], v48, s7, v[138:139]
	v_add_f32_e32 v50, 1.0, v50
	v_rcp_f32_e32 v50, v50
	s_nop 0
	v_mul_f32_e32 v44, v44, v50
	v_mul_f32_e32 v40, v44, v40
	v_mul_f32_e32 v44, 0xbfb8aa3b, v45
	v_exp_f32_e32 v44, v44
	s_nop 0
	v_add_f32_e32 v44, 1.0, v44
	v_rcp_f32_e32 v44, v44
	s_nop 0
	v_mul_f32_e32 v44, v45, v44
	v_mul_f32_e32 v41, v44, v41
	v_mul_f32_e32 v44, 0xbfb8aa3b, v46
	v_exp_f32_e32 v44, v44
	s_nop 0
	v_add_f32_e32 v44, 1.0, v44
	v_rcp_f32_e32 v44, v44
	s_nop 0
	v_mul_f32_e32 v44, v46, v44
	v_mul_f32_e32 v42, v44, v42
	v_mul_f32_e32 v44, 0xbfb8aa3b, v47
	v_exp_f32_e32 v44, v44
	s_nop 0
	v_add_f32_e32 v44, 1.0, v44
	v_rcp_f32_e32 v44, v44
	s_nop 0
	v_mul_f32_e32 v44, v47, v44
	v_mul_f32_e32 v43, v44, v43
	v_mul_f32_e32 v44, 0xbfb8aa3b, v36
	v_exp_f32_e32 v44, v44
	s_nop 0
	v_add_f32_e32 v44, 1.0, v44
	v_rcp_f32_e32 v44, v44
	s_nop 0
	v_mul_f32_e32 v36, v36, v44
	v_mul_f32_e32 v44, v36, v32
	v_mul_f32_e32 v32, 0xbfb8aa3b, v37
	v_exp_f32_e32 v32, v32
	s_nop 0
	v_add_f32_e32 v32, 1.0, v32
	v_rcp_f32_e32 v32, v32
	s_nop 0
	v_mul_f32_e32 v32, v37, v32
	v_mul_f32_e32 v45, v32, v33
	v_mul_f32_e32 v32, 0xbfb8aa3b, v38
	v_exp_f32_e32 v32, v32
	v_lshl_add_u64 v[36:37], v[48:49], 0, v[112:113]
	v_add_f32_e32 v32, 1.0, v32
	v_rcp_f32_e32 v32, v32
	s_nop 0
	v_mul_f32_e32 v32, v38, v32
	v_mul_f32_e32 v38, v32, v34
	v_mul_f32_e32 v32, 0xbfb8aa3b, v39
	v_exp_f32_e32 v32, v32
	s_nop 0
	v_add_f32_e32 v32, 1.0, v32
	v_rcp_f32_e32 v32, v32
	s_nop 0
	v_mul_f32_e32 v32, v39, v32
	v_mul_f32_e32 v35, v32, v35
	v_cvt_pk_bf16_f32 v32, v40, v41
	v_cvt_pk_bf16_f32 v33, v42, v43
	v_cvt_pk_bf16_f32 v34, v44, v45
	v_cvt_pk_bf16_f32 v35, v38, v35
	global_store_dwordx4 v[36:37], v[32:35], off
	s_nop 1
	v_mul_f32_e32 v34, 0xbfb8aa3b, v28
	v_exp_f32_e32 v34, v34
	v_add_u32_e32 v32, 0xa0, v144
	v_mad_i64_i32 v[32:33], s[14:15], v32, s7, v[138:139]
	v_add_f32_e32 v34, 1.0, v34
	v_rcp_f32_e32 v34, v34
	s_nop 0
	v_mul_f32_e32 v28, v28, v34
	v_mul_f32_e32 v24, v28, v24
; __device__ __forceinline__ unsigned cvt_pk_bf16(float lo, float hi) { unsigned r; asm volatile("v_cvt_pk_bf16_f32 %0, %1, %2" : "=v"(r) : "v"(lo), "v"(hi)); return r; }
;     DI void operator()(const pg8::f32x4 (&acc)[2][2][4][2], const pg8::Unit& u, int wr, int wc, int fr, int fq) const {
;     ...
;             for (int m = 0; m < 4; ++m) { bf16* rowp = O + (size_t)(row0 + ai * 128 + m * 16) * FF + col0;
;                 float hv[8];
; #pragma unroll
;                 for (int n = 0; n < 2; ++n)
; #pragma unroll
;                     for (int j = 0; j < 4; ++j) { const float g = acc[ai][0][m][n][j], up = acc[ai][1][m][n][j]; hv[4 * n + j] = g * __builtin_amdgcn_rcpf(1.f + __expf(-g)) * up; }
;                 v4u w; w.x = pg8::cvt_pk_bf16(hv[0], hv[1]); w.y = pg8::cvt_pk_bf16(hv[2], hv[3]); w.z = pg8::cvt_pk_bf16(hv[4], hv[5]); w.w = pg8::cvt_pk_bf16(hv[6], hv[7]);
;                 *(v4u*)rowp = w; }
	v_mul_f32_e32 v28, 0xbfb8aa3b, v29
	v_exp_f32_e32 v28, v28
	s_nop 0
	v_add_f32_e32 v28, 1.0, v28
	v_rcp_f32_e32 v28, v28
	s_nop 0
	v_mul_f32_e32 v28, v29, v28
	v_mul_f32_e32 v25, v28, v25
	v_mul_f32_e32 v28, 0xbfb8aa3b, v30
	v_exp_f32_e32 v28, v28
	s_nop 0
	v_add_f32_e32 v28, 1.0, v28
	v_rcp_f32_e32 v28, v28
	s_nop 0
	v_mul_f32_e32 v28, v30, v28
	v_mul_f32_e32 v26, v28, v26
	v_mul_f32_e32 v28, 0xbfb8aa3b, v31
	v_exp_f32_e32 v28, v28
	s_nop 0
	v_add_f32_e32 v28, 1.0, v28
	v_rcp_f32_e32 v28, v28
	s_nop 0
	v_mul_f32_e32 v28, v31, v28
	v_mul_f32_e32 v27, v28, v27
	v_mul_f32_e32 v28, 0xbfb8aa3b, v20
	v_exp_f32_e32 v28, v28
	s_nop 0
	v_add_f32_e32 v28, 1.0, v28
	v_rcp_f32_e32 v28, v28
	s_nop 0
	v_mul_f32_e32 v20, v20, v28
	v_mul_f32_e32 v28, v20, v16
	v_mul_f32_e32 v16, 0xbfb8aa3b, v21
	v_exp_f32_e32 v16, v16
	s_nop 0
	v_add_f32_e32 v16, 1.0, v16
	v_rcp_f32_e32 v16, v16
	s_nop 0
	v_mul_f32_e32 v16, v21, v16
	v_mul_f32_e32 v29, v16, v17
	v_mul_f32_e32 v16, 0xbfb8aa3b, v22
	v_exp_f32_e32 v16, v16
	v_lshl_add_u64 v[20:21], v[32:33], 0, v[112:113]
	v_add_f32_e32 v16, 1.0, v16
	v_rcp_f32_e32 v16, v16
	s_nop 0
	v_mul_f32_e32 v16, v22, v16
	v_mul_f32_e32 v22, v16, v18
	v_mul_f32_e32 v16, 0xbfb8aa3b, v23
	v_exp_f32_e32 v16, v16
	s_nop 0
	v_add_f32_e32 v16, 1.0, v16
	v_rcp_f32_e32 v16, v16
	s_nop 0
	v_mul_f32_e32 v16, v23, v16
	v_mul_f32_e32 v19, v16, v19
	v_cvt_pk_bf16_f32 v16, v24, v25
	v_cvt_pk_bf16_f32 v17, v26, v27
	v_cvt_pk_bf16_f32 v18, v28, v29
	v_cvt_pk_bf16_f32 v19, v22, v19
	global_store_dwordx4 v[20:21], v[16:19], off
	s_nop 1
	v_mul_f32_e32 v18, 0xbfb8aa3b, v12
	v_exp_f32_e32 v18, v18
	v_add_u32_e32 v16, 0xb0, v144
	v_mad_i64_i32 v[16:17], s[14:15], v16, s7, v[138:139]
	v_add_f32_e32 v18, 1.0, v18
	v_rcp_f32_e32 v18, v18
	s_mov_b64 s[14:15], -1
	v_mul_f32_e32 v12, v12, v18
	v_mul_f32_e32 v8, v12, v8
	v_mul_f32_e32 v12, 0xbfb8aa3b, v13
	v_exp_f32_e32 v12, v12
	s_nop 0
	v_add_f32_e32 v12, 1.0, v12
	v_rcp_f32_e32 v12, v12
	s_nop 0
	v_mul_f32_e32 v12, v13, v12
	v_mul_f32_e32 v9, v12, v9
	v_mul_f32_e32 v12, 0xbfb8aa3b, v14
	v_exp_f32_e32 v12, v12
	s_nop 0
	v_add_f32_e32 v12, 1.0, v12
	v_rcp_f32_e32 v12, v12
	s_nop 0
	v_mul_f32_e32 v12, v14, v12
	v_mul_f32_e32 v10, v12, v10
	v_mul_f32_e32 v12, 0xbfb8aa3b, v15
	v_exp_f32_e32 v12, v12
	s_nop 0
	v_add_f32_e32 v12, 1.0, v12
	v_rcp_f32_e32 v12, v12
	s_nop 0
	v_mul_f32_e32 v12, v15, v12
	v_mul_f32_e32 v11, v12, v11
	v_mul_f32_e32 v12, 0xbfb8aa3b, v4
	v_exp_f32_e32 v12, v12
	s_nop 0
	v_add_f32_e32 v12, 1.0, v12
	v_rcp_f32_e32 v12, v12
	s_nop 0
	v_mul_f32_e32 v4, v4, v12
	v_mul_f32_e32 v12, v4, v0
	v_mul_f32_e32 v0, 0xbfb8aa3b, v5
	v_exp_f32_e32 v0, v0
	s_nop 0
	v_add_f32_e32 v0, 1.0, v0
	v_rcp_f32_e32 v0, v0
	s_nop 0
	v_mul_f32_e32 v0, v5, v0
	v_mul_f32_e32 v13, v0, v1
	v_mul_f32_e32 v0, 0xbfb8aa3b, v6
	v_exp_f32_e32 v0, v0
	v_lshl_add_u64 v[4:5], v[16:17], 0, v[112:113]
	v_add_f32_e32 v0, 1.0, v0
	v_rcp_f32_e32 v0, v0
	s_nop 0
	v_mul_f32_e32 v0, v6, v0
	v_mul_f32_e32 v6, v0, v2
	v_mul_f32_e32 v0, 0xbfb8aa3b, v7
	v_exp_f32_e32 v0, v0
	s_nop 0
	v_add_f32_e32 v0, 1.0, v0
	v_rcp_f32_e32 v0, v0
	s_nop 0
	v_mul_f32_e32 v0, v7, v0
	v_mul_f32_e32 v3, v0, v3
	v_cvt_pk_bf16_f32 v0, v8, v9
	v_cvt_pk_bf16_f32 v1, v10, v11
	v_cvt_pk_bf16_f32 v2, v12, v13
	v_cvt_pk_bf16_f32 v3, v6, v3
	global_store_dwordx4 v[4:5], v[0:3], off
	s_cbranch_vccnz .LBB0_1172
	s_andn2_b64 vcc, exec, s[0:1]
	s_cbranch_vccnz .LBB0_1171
	s_barrier
	s_branch .LBB0_1171
.LBB0_1182:
	s_setprio 0
	s_waitcnt vmcnt(0)
	s_barrier
.LBB0_1183:
	s_waitcnt vmcnt(0)
	s_waitcnt vmcnt(0)
	s_barrier
	s_mov_b64 s[0:1], exec
	v_readlane_b32 s2, v252, 4
	v_readlane_b32 s3, v252, 5
	s_and_b64 s[2:3], s[0:1], s[2:3]
	s_mov_b64 exec, s[2:3]
	s_cbranch_execz .LBB0_1235
	v_readlane_b32 s2, v254, 4
	s_waitcnt vmcnt(0) expcnt(0) lgkmcnt(0)
	s_nop 0
	v_mov_b32_e32 v0, s2
	ds_read_b32 v2, v0
	v_readlane_b32 s2, v254, 5
	s_waitcnt lgkmcnt(0)
	v_cmp_ne_u32_e32 vcc, 0, v2
	v_mov_b32_e32 v0, s2
	ds_read_b32 v0, v0
	s_cbranch_vccnz .LBB0_1199
	s_mov_b32 s8, 1
	s_branch .LBB0_1187

; #define PG8_STAGE(bufoff, gbase, voff) do { _Pragma("unroll") for (int _i = 0; _i < 2; ++_i) \
;         __builtin_amdgcn_global_load_lds((const unsigned*)((const char*)(gbase) + (voff)[_i]), (PG8_LAS unsigned*)(lds + (bufoff) + ldsw + _i * 8192), 16, 0, 0); } while (0)
; #define PG8_LDA(dst, b, h) do { _Pragma("unroll") for (int m = 0; m < 4; ++m) _Pragma("unroll") for (int k = 0; k < 2; ++k) dst[m][k] = *(const PG8_LAS bf16x8*)(lds + PG8_SA(b, h) + aoff + m * 2048 + k * 1024); } while (0)
; #define PG8_LDB(dst, b, h) do { _Pragma("unroll") for (int n = 0; n < 2; ++n) _Pragma("unroll") for (int k = 0; k < 2; ++k) dst[n][k] = *(const PG8_LAS bf16x8*)(lds + PG8_SB(b, h) + boff + n * 2048 + k * 1024); } while (0)
; #define PG8_MMA(ai, bj, At, Bt) do { __builtin_amdgcn_s_setprio(1); _Pragma("unroll") for (int m = 0; m < 4; ++m) _Pragma("unroll") for (int n = 0; n < 2; ++n) _Pragma("unroll") for (int k = 0; k < 2; ++k) \
;         acc[ai][bj][m][n] = __builtin_amdgcn_mfma_f32_16x16x32_bf16(Bt[n][k], At[m][k], acc[ai][bj][m][n], 0, 0, 0); __builtin_amdgcn_s_setprio(0); } while (0)
; #define PG8_WAIT_V(n) asm volatile("s_waitcnt vmcnt(" #n ")" ::: "memory")
; #define PG8_WAIT_L(n) asm volatile("s_waitcnt lgkmcnt(" #n ")" ::: "memory")
; #define PG8_BAR __builtin_amdgcn_s_barrier()
; #define PG8_SCHED __builtin_amdgcn_sched_barrier(0)
; template <class Epi, class Sched, bool ALIGN_EPI = false, bool SP2 = false>
; __device__ __forceinline__ void gemm_phase(PG8_LAS unsigned char* lds, const Gemm g, const Sched& S, const Epi& E) {
;     ...
;             PG8_LDB(B0, 0, 0); PG8_LDB(B1, 0, 1); PG8_SCHED; PG8_LDA(At, 0, 0); PG8_STAGE(PG8_SA(1, 1), a1 + hstep, voffA);
;             PG8_WAIT_V(8); PG8_WAIT_L(0); PG8_BAR; PG8_MMA(0, 0, At, B0); PG8_MMA(0, 1, At, B1); PG8_BAR; PG8_SCHED;
;             PG8_LDA(At, 0, 1); PG8_STAGE(PG8_SB(0, 0), b2, voffB); PG8_STAGE(PG8_SB(0, 1), b2 + hstep, voffB); PG8_STAGE(PG8_SA(0, 0), a2, voffA);
;             PG8_WAIT_V(8); PG8_WAIT_L(0); PG8_BAR; PG8_MMA(1, 0, At, B0); PG8_MMA(1, 1, At, B1); PG8_BAR; PG8_SCHED;
.LBB0_1252:
	s_add_u32 s14, s12, 0x100
	s_addc_u32 s15, s13, 0
	s_add_i32 s42, 0, 0x10000
	s_cmp_eq_u32 s39, 40
	s_cselect_b32 s19, s1, s15
	s_cselect_b32 s18, s0, s14
	s_cselect_b32 s17, s11, s38
	s_cselect_b32 s16, s10, s37
	s_add_i32 s43, 0, 0x14000
	v_add_u32_e32 v140, s42, v242
	v_add_u32_e32 v156, s43, v242
	ds_read_b128 v[128:131], v140
	ds_read_b128 v[132:135], v140 offset:1024
	ds_read_b128 v[136:139], v140 offset:2048
	ds_read_b128 v[140:143], v140 offset:3072
	ds_read_b128 v[144:147], v156
	ds_read_b128 v[148:151], v156 offset:1024
	ds_read_b128 v[152:155], v156 offset:2048
	ds_read_b128 v[156:159], v156 offset:3072
	v_lshl_add_u64 v[216:217], s[12:13], 0, v[212:213]
	s_add_i32 m0, s25, 0xc000
	ds_read_b128 v[160:163], v244
	ds_read_b128 v[164:167], v244 offset:1024
	ds_read_b128 v[168:171], v244 offset:2048
	ds_read_b128 v[172:175], v244 offset:3072
	ds_read_b128 v[176:179], v244 offset:4096
	ds_read_b128 v[180:183], v244 offset:5120
	ds_read_b128 v[184:187], v244 offset:6144
	ds_read_b128 v[188:191], v244 offset:7168
	global_load_lds_dwordx4 v[216:217], off
	v_lshl_add_u64 v[216:217], s[12:13], 0, v[214:215]
	s_add_i32 m0, s25, 0xe000
	s_nop 0
	global_load_lds_dwordx4 v[216:217], off
	s_waitcnt vmcnt(8)
	s_waitcnt lgkmcnt(0)
	s_barrier
	s_waitcnt lgkmcnt(0)
	v_mfma_f32_16x16x32_bf16 v[124:127], v[128:131], v[160:163], v[124:127]
	v_mfma_f32_16x16x32_bf16 v[120:123], v[136:139], v[160:163], v[120:123]
	v_mfma_f32_16x16x32_bf16 v[108:111], v[128:131], v[168:171], v[108:111]
	v_mfma_f32_16x16x32_bf16 v[104:107], v[136:139], v[168:171], v[104:107]
	v_mfma_f32_16x16x32_bf16 v[96:99], v[128:131], v[176:179], v[96:99]
	v_mfma_f32_16x16x32_bf16 v[88:91], v[136:139], v[176:179], v[88:91]
	v_mfma_f32_16x16x32_bf16 v[80:83], v[128:131], v[184:187], v[80:83]
	v_mfma_f32_16x16x32_bf16 v[72:75], v[136:139], v[184:187], v[72:75]
	v_mfma_f32_16x16x32_bf16 v[124:127], v[132:135], v[164:167], v[124:127]
	v_mfma_f32_16x16x32_bf16 v[120:123], v[140:143], v[164:167], v[120:123]
	v_mfma_f32_16x16x32_bf16 v[108:111], v[132:135], v[172:175], v[108:111]
	v_mfma_f32_16x16x32_bf16 v[104:107], v[140:143], v[172:175], v[104:107]
	v_mfma_f32_16x16x32_bf16 v[96:99], v[132:135], v[180:183], v[96:99]
	v_mfma_f32_16x16x32_bf16 v[88:91], v[140:143], v[180:183], v[88:91]
	v_mfma_f32_16x16x32_bf16 v[80:83], v[132:135], v[188:191], v[80:83]
	v_mfma_f32_16x16x32_bf16 v[72:75], v[140:143], v[188:191], v[72:75]
	v_mfma_f32_16x16x32_bf16 v[116:119], v[144:147], v[160:163], v[116:119]
	v_mfma_f32_16x16x32_bf16 v[112:115], v[152:155], v[160:163], v[112:115]
	v_mfma_f32_16x16x32_bf16 v[100:103], v[144:147], v[168:171], v[100:103]
	v_mfma_f32_16x16x32_bf16 v[92:95], v[152:155], v[168:171], v[92:95]
	v_mfma_f32_16x16x32_bf16 v[84:87], v[144:147], v[176:179], v[84:87]
	v_mfma_f32_16x16x32_bf16 v[76:79], v[152:155], v[176:179], v[76:79]
	v_mfma_f32_16x16x32_bf16 v[68:71], v[144:147], v[184:187], v[68:71]
	v_mfma_f32_16x16x32_bf16 v[64:67], v[152:155], v[184:187], v[64:67]
	v_mfma_f32_16x16x32_bf16 v[116:119], v[148:151], v[164:167], v[116:119]
	v_mfma_f32_16x16x32_bf16 v[112:115], v[156:159], v[164:167], v[112:115]
	v_mfma_f32_16x16x32_bf16 v[100:103], v[148:151], v[172:175], v[100:103]
	v_mfma_f32_16x16x32_bf16 v[92:95], v[156:159], v[172:175], v[92:95]
	v_mfma_f32_16x16x32_bf16 v[84:87], v[148:151], v[180:183], v[84:87]
	v_mfma_f32_16x16x32_bf16 v[76:79], v[156:159], v[180:183], v[76:79]
	v_mfma_f32_16x16x32_bf16 v[68:71], v[148:151], v[188:191], v[68:71]
	v_mfma_f32_16x16x32_bf16 v[64:67], v[156:159], v[188:191], v[64:67]
	s_barrier
	s_add_i32 s12, s42, s24
	v_lshl_add_u64 v[216:217], s[16:17], 0, v[192:193]
	s_mov_b32 m0, s12
	ds_read_b128 v[160:163], v244 offset:16384
	ds_read_b128 v[164:167], v244 offset:17408
	ds_read_b128 v[168:171], v244 offset:18432
	ds_read_b128 v[172:175], v244 offset:19456
	ds_read_b128 v[176:179], v244 offset:20480
	ds_read_b128 v[180:183], v244 offset:21504
	ds_read_b128 v[184:187], v244 offset:22528
	ds_read_b128 v[188:191], v244 offset:23552
	global_load_lds_dwordx4 v[216:217], off
	s_add_i32 m0, s12, 0x2000
	s_add_u32 s12, s16, 0xb0000
	v_lshl_add_u64 v[218:219], s[16:17], 0, v[206:207]
	s_addc_u32 s13, s17, 0
	s_add_i32 s42, s43, s24
	global_load_lds_dwordx4 v[218:219], off
	v_lshl_add_u64 v[220:221], s[12:13], 0, v[192:193]
	s_mov_b32 m0, s42
	v_lshl_add_u64 v[222:223], s[18:19], 0, v[208:209]
	global_load_lds_dwordx4 v[220:221], off
	v_lshl_add_u64 v[220:221], s[12:13], 0, v[206:207]
	s_add_i32 m0, s42, 0x2000
	s_nop 0
	global_load_lds_dwordx4 v[220:221], off
	v_lshl_add_u64 v[220:221], s[18:19], 0, v[210:211]
	s_mov_b32 m0, s25
	s_nop 0
	global_load_lds_dwordx4 v[220:221], off
	s_mov_b32 m0, s26
	s_nop 0
	global_load_lds_dwordx4 v[222:223], off
	s_waitcnt vmcnt(8)
	s_waitcnt lgkmcnt(0)
	s_barrier
; #define PG8_STAGE(bufoff, gbase, voff) do { _Pragma("unroll") for (int _i = 0; _i < 2; ++_i) \
;         __builtin_amdgcn_global_load_lds((const unsigned*)((const char*)(gbase) + (voff)[_i]), (PG8_LAS unsigned*)(lds + (bufoff) + ldsw + _i * 8192), 16, 0, 0); } while (0)
; #define PG8_LDA(dst, b, h) do { _Pragma("unroll") for (int m = 0; m < 4; ++m) _Pragma("unroll") for (int k = 0; k < 2; ++k) dst[m][k] = *(const PG8_LAS bf16x8*)(lds + PG8_SA(b, h) + aoff + m * 2048 + k * 1024); } while (0)
; #define PG8_LDB(dst, b, h) do { _Pragma("unroll") for (int n = 0; n < 2; ++n) _Pragma("unroll") for (int k = 0; k < 2; ++k) dst[n][k] = *(const PG8_LAS bf16x8*)(lds + PG8_SB(b, h) + boff + n * 2048 + k * 1024); } while (0)
; #define PG8_MMA(ai, bj, At, Bt) do { __builtin_amdgcn_s_setprio(1); _Pragma("unroll") for (int m = 0; m < 4; ++m) _Pragma("unroll") for (int n = 0; n < 2; ++n) _Pragma("unroll") for (int k = 0; k < 2; ++k) \
;         acc[ai][bj][m][n] = __builtin_amdgcn_mfma_f32_16x16x32_bf16(Bt[n][k], At[m][k], acc[ai][bj][m][n], 0, 0, 0); __builtin_amdgcn_s_setprio(0); } while (0)
; #define PG8_WAIT_V(n) asm volatile("s_waitcnt vmcnt(" #n ")" ::: "memory")
; #define PG8_WAIT_L(n) asm volatile("s_waitcnt lgkmcnt(" #n ")" ::: "memory")
; #define PG8_BAR __builtin_amdgcn_s_barrier()
; #define PG8_SCHED __builtin_amdgcn_sched_barrier(0)
; template <class Epi, class Sched, bool ALIGN_EPI = false, bool SP2 = false>
; __device__ __forceinline__ void gemm_phase(PG8_LAS unsigned char* lds, const Gemm g, const Sched& S, const Epi& E) {
;     ...
;             PG8_WAIT_V(8); PG8_WAIT_L(0); PG8_BAR; PG8_MMA(1, 0, At, B0); PG8_MMA(1, 1, At, B1); PG8_BAR; PG8_SCHED;
;             PG8_LDB(B0, 1, 0); PG8_LDB(B1, 1, 1); PG8_SCHED; PG8_LDA(At, 1, 0); PG8_STAGE(PG8_SA(0, 1), a2 + hstep, voffA);
;             PG8_WAIT_V(8); PG8_WAIT_L(0); PG8_BAR; PG8_MMA(0, 0, At, B0); PG8_MMA(0, 1, At, B1); PG8_BAR; PG8_SCHED;
	s_waitcnt lgkmcnt(0)
	v_mfma_f32_16x16x32_bf16 v[60:63], v[128:131], v[160:163], v[60:63]
	v_mfma_f32_16x16x32_bf16 v[56:59], v[136:139], v[160:163], v[56:59]
	v_mfma_f32_16x16x32_bf16 v[48:51], v[128:131], v[168:171], v[48:51]
	v_mfma_f32_16x16x32_bf16 v[40:43], v[136:139], v[168:171], v[40:43]
	v_mfma_f32_16x16x32_bf16 v[32:35], v[128:131], v[176:179], v[32:35]
	v_mfma_f32_16x16x32_bf16 v[24:27], v[136:139], v[176:179], v[24:27]
	v_mfma_f32_16x16x32_bf16 v[16:19], v[128:131], v[184:187], v[16:19]
	v_mfma_f32_16x16x32_bf16 v[8:11], v[136:139], v[184:187], v[8:11]
	v_mfma_f32_16x16x32_bf16 v[60:63], v[132:135], v[164:167], v[60:63]
	v_mfma_f32_16x16x32_bf16 v[56:59], v[140:143], v[164:167], v[56:59]
	v_mfma_f32_16x16x32_bf16 v[48:51], v[132:135], v[172:175], v[48:51]
	v_mfma_f32_16x16x32_bf16 v[40:43], v[140:143], v[172:175], v[40:43]
	v_mfma_f32_16x16x32_bf16 v[32:35], v[132:135], v[180:183], v[32:35]
	v_mfma_f32_16x16x32_bf16 v[24:27], v[140:143], v[180:183], v[24:27]
	v_mfma_f32_16x16x32_bf16 v[16:19], v[132:135], v[188:191], v[16:19]
	v_mfma_f32_16x16x32_bf16 v[8:11], v[140:143], v[188:191], v[8:11]
	v_mfma_f32_16x16x32_bf16 v[52:55], v[144:147], v[160:163], v[52:55]
	v_mfma_f32_16x16x32_bf16 v[44:47], v[152:155], v[160:163], v[44:47]
	v_mfma_f32_16x16x32_bf16 v[36:39], v[144:147], v[168:171], v[36:39]
	v_mfma_f32_16x16x32_bf16 v[28:31], v[152:155], v[168:171], v[28:31]
	v_mfma_f32_16x16x32_bf16 v[20:23], v[144:147], v[176:179], v[20:23]
	v_mfma_f32_16x16x32_bf16 v[12:15], v[152:155], v[176:179], v[12:15]
	v_mfma_f32_16x16x32_bf16 v[4:7], v[144:147], v[184:187], v[4:7]
	v_mfma_f32_16x16x32_bf16 v[0:3], v[152:155], v[184:187], v[0:3]
	v_mfma_f32_16x16x32_bf16 v[52:55], v[148:151], v[164:167], v[52:55]
	v_mfma_f32_16x16x32_bf16 v[44:47], v[156:159], v[164:167], v[44:47]
	v_mfma_f32_16x16x32_bf16 v[36:39], v[148:151], v[172:175], v[36:39]
	v_mfma_f32_16x16x32_bf16 v[28:31], v[156:159], v[172:175], v[28:31]
	v_mfma_f32_16x16x32_bf16 v[20:23], v[148:151], v[180:183], v[20:23]
	v_mfma_f32_16x16x32_bf16 v[12:15], v[156:159], v[180:183], v[12:15]
	v_mfma_f32_16x16x32_bf16 v[4:7], v[148:151], v[188:191], v[4:7]
	v_mfma_f32_16x16x32_bf16 v[0:3], v[156:159], v[188:191], v[0:3]
	s_barrier
	s_add_i32 s42, 0, 0x18000
	s_add_i32 s43, 0, 0x1c000
	v_add_u32_e32 v140, s42, v242
	v_add_u32_e32 v156, s43, v242
	ds_read_b128 v[128:131], v140
	ds_read_b128 v[132:135], v140 offset:1024
	ds_read_b128 v[136:139], v140 offset:2048
	ds_read_b128 v[140:143], v140 offset:3072
	ds_read_b128 v[144:147], v156
	ds_read_b128 v[148:151], v156 offset:1024
	ds_read_b128 v[152:155], v156 offset:2048
	ds_read_b128 v[156:159], v156 offset:3072
	s_add_u32 s12, s18, 0xb0000
	s_addc_u32 s13, s19, 0
	s_mov_b32 m0, s27
	v_lshl_add_u64 v[224:225], s[12:13], 0, v[210:211]
	ds_read_b128 v[160:163], v244 offset:32768
	ds_read_b128 v[164:167], v244 offset:33792
	ds_read_b128 v[168:171], v244 offset:34816
	ds_read_b128 v[172:175], v244 offset:35840
	ds_read_b128 v[176:179], v244 offset:36864
	ds_read_b128 v[180:183], v244 offset:37888
	ds_read_b128 v[184:187], v244 offset:38912
	ds_read_b128 v[188:191], v244 offset:39936
	global_load_lds_dwordx4 v[224:225], off
	v_lshl_add_u64 v[224:225], s[12:13], 0, v[208:209]
	s_mov_b32 m0, s28
	s_nop 0
	global_load_lds_dwordx4 v[224:225], off
	s_waitcnt vmcnt(8)
	s_waitcnt lgkmcnt(0)
	s_barrier
	s_waitcnt lgkmcnt(0)
	v_mfma_f32_16x16x32_bf16 v[124:127], v[128:131], v[160:163], v[124:127]
	v_mfma_f32_16x16x32_bf16 v[120:123], v[136:139], v[160:163], v[120:123]
	v_mfma_f32_16x16x32_bf16 v[108:111], v[128:131], v[168:171], v[108:111]
	v_mfma_f32_16x16x32_bf16 v[104:107], v[136:139], v[168:171], v[104:107]
	v_mfma_f32_16x16x32_bf16 v[96:99], v[128:131], v[176:179], v[96:99]
	v_mfma_f32_16x16x32_bf16 v[88:91], v[136:139], v[176:179], v[88:91]
	v_mfma_f32_16x16x32_bf16 v[80:83], v[128:131], v[184:187], v[80:83]
	v_mfma_f32_16x16x32_bf16 v[72:75], v[136:139], v[184:187], v[72:75]
	v_mfma_f32_16x16x32_bf16 v[124:127], v[132:135], v[164:167], v[124:127]
	v_mfma_f32_16x16x32_bf16 v[120:123], v[140:143], v[164:167], v[120:123]
	v_mfma_f32_16x16x32_bf16 v[108:111], v[132:135], v[172:175], v[108:111]
	v_mfma_f32_16x16x32_bf16 v[104:107], v[140:143], v[172:175], v[104:107]
	v_mfma_f32_16x16x32_bf16 v[96:99], v[132:135], v[180:183], v[96:99]
	v_mfma_f32_16x16x32_bf16 v[88:91], v[140:143], v[180:183], v[88:91]
	v_mfma_f32_16x16x32_bf16 v[80:83], v[132:135], v[188:191], v[80:83]
	v_mfma_f32_16x16x32_bf16 v[72:75], v[140:143], v[188:191], v[72:75]
	v_mfma_f32_16x16x32_bf16 v[116:119], v[144:147], v[160:163], v[116:119]
	v_mfma_f32_16x16x32_bf16 v[112:115], v[152:155], v[160:163], v[112:115]
	v_mfma_f32_16x16x32_bf16 v[100:103], v[144:147], v[168:171], v[100:103]
	v_mfma_f32_16x16x32_bf16 v[92:95], v[152:155], v[168:171], v[92:95]
	v_mfma_f32_16x16x32_bf16 v[84:87], v[144:147], v[176:179], v[84:87]
	v_mfma_f32_16x16x32_bf16 v[76:79], v[152:155], v[176:179], v[76:79]
	v_mfma_f32_16x16x32_bf16 v[68:71], v[144:147], v[184:187], v[68:71]
	v_mfma_f32_16x16x32_bf16 v[64:67], v[152:155], v[184:187], v[64:67]
	v_mfma_f32_16x16x32_bf16 v[116:119], v[148:151], v[164:167], v[116:119]
	v_mfma_f32_16x16x32_bf16 v[112:115], v[156:159], v[164:167], v[112:115]
	v_mfma_f32_16x16x32_bf16 v[100:103], v[148:151], v[172:175], v[100:103]
	v_mfma_f32_16x16x32_bf16 v[92:95], v[156:159], v[172:175], v[92:95]
	v_mfma_f32_16x16x32_bf16 v[84:87], v[148:151], v[180:183], v[84:87]
	v_mfma_f32_16x16x32_bf16 v[76:79], v[156:159], v[180:183], v[76:79]
	v_mfma_f32_16x16x32_bf16 v[68:71], v[148:151], v[188:191], v[68:71]
	v_mfma_f32_16x16x32_bf16 v[64:67], v[156:159], v[188:191], v[64:67]
	s_barrier
; #define PG8_STAGE(bufoff, gbase, voff) do { _Pragma("unroll") for (int _i = 0; _i < 2; ++_i) \
;         __builtin_amdgcn_global_load_lds((const unsigned*)((const char*)(gbase) + (voff)[_i]), (PG8_LAS unsigned*)(lds + (bufoff) + ldsw + _i * 8192), 16, 0, 0); } while (0)
; #define PG8_LDA(dst, b, h) do { _Pragma("unroll") for (int m = 0; m < 4; ++m) _Pragma("unroll") for (int k = 0; k < 2; ++k) dst[m][k] = *(const PG8_LAS bf16x8*)(lds + PG8_SA(b, h) + aoff + m * 2048 + k * 1024); } while (0)
; #define PG8_MMA(ai, bj, At, Bt) do { __builtin_amdgcn_s_setprio(1); _Pragma("unroll") for (int m = 0; m < 4; ++m) _Pragma("unroll") for (int n = 0; n < 2; ++n) _Pragma("unroll") for (int k = 0; k < 2; ++k) \
;         acc[ai][bj][m][n] = __builtin_amdgcn_mfma_f32_16x16x32_bf16(Bt[n][k], At[m][k], acc[ai][bj][m][n], 0, 0, 0); __builtin_amdgcn_s_setprio(0); } while (0)
; #define PG8_WAIT_V(n) asm volatile("s_waitcnt vmcnt(" #n ")" ::: "memory")
; #define PG8_WAIT_L(n) asm volatile("s_waitcnt lgkmcnt(" #n ")" ::: "memory")
; #define PG8_BAR __builtin_amdgcn_s_barrier()
; #define PG8_SCHED __builtin_amdgcn_sched_barrier(0)
; template <class Epi, class Sched, bool ALIGN_EPI = false, bool SP2 = false>
; __device__ __forceinline__ void gemm_phase(PG8_LAS unsigned char* lds, const Gemm g, const Sched& S, const Epi& E) {
;     ...
;             PG8_LDA(At, 1, 1); PG8_STAGE(PG8_SB(1, 0), b3, voffB); PG8_STAGE(PG8_SB(1, 1), b3 + hstep, voffB); PG8_STAGE(PG8_SA(1, 0), a3, voffA);
;             PG8_WAIT_V(8); PG8_WAIT_L(0); PG8_BAR; PG8_MMA(1, 0, At, B0); PG8_MMA(1, 1, At, B1); PG8_BAR; PG8_SCHED;
;     DI void operator()(const pg8::f32x4 (&acc)[2][2][4][2], const pg8::Unit& u, int wr, int wc, int fr, int fq) const {
;         const int row0 = u.pm * 256 + wr * 64 + fr, col0 = u.pn * 256 + wc * 32 + 8 * fq;
;         v4u rb[2][4][2];
; #pragma unroll
;         for (int ai = 0; ai < 2; ++ai)
; #pragma unroll
;             for (int m = 0; m < 4; ++m) { const size_t off = (size_t)(row0 + ai * 128 + m * 16) * D + col0;
; #pragma unroll
;                 for (int bj = 0; bj < 2; ++bj) rb[ai][m][bj] = *(const v4u*)(res + off + bj * 128); }
	s_add_i32 s12, s42, s24
	v_lshl_add_u64 v[216:217], v[216:217], 0, s[72:73]
	s_mov_b32 m0, s12
	ds_read_b128 v[160:163], v244 offset:49152
	ds_read_b128 v[164:167], v244 offset:50176
	ds_read_b128 v[168:171], v244 offset:51200
	ds_read_b128 v[172:175], v244 offset:52224
	ds_read_b128 v[176:179], v244 offset:53248
	ds_read_b128 v[180:183], v244 offset:54272
	ds_read_b128 v[184:187], v244 offset:55296
	ds_read_b128 v[188:191], v244 offset:56320
	global_load_lds_dwordx4 v[216:217], off
	s_add_i32 m0, s12, 0x2000
	s_add_u32 s12, s16, 0xb0080
	v_lshl_add_u64 v[216:217], v[218:219], 0, s[72:73]
	s_addc_u32 s13, s17, 0
	s_add_i32 s16, s43, s24
	global_load_lds_dwordx4 v[216:217], off
	v_lshl_add_u64 v[216:217], s[12:13], 0, v[192:193]
	s_mov_b32 m0, s16
	s_nop 0
	global_load_lds_dwordx4 v[216:217], off
	v_lshl_add_u64 v[216:217], s[12:13], 0, v[206:207]
	s_add_i32 m0, s16, 0x2000
	s_nop 0
	global_load_lds_dwordx4 v[216:217], off
	v_lshl_add_u64 v[216:217], v[220:221], 0, s[72:73]
	s_mov_b32 m0, s29
	s_nop 0
	global_load_lds_dwordx4 v[216:217], off
	v_lshl_add_u64 v[216:217], v[222:223], 0, s[72:73]
	s_mov_b32 m0, s30
	s_nop 0
	global_load_lds_dwordx4 v[216:217], off
	s_waitcnt vmcnt(8)
	s_waitcnt lgkmcnt(0)
	s_barrier
	s_waitcnt lgkmcnt(0)
	v_mfma_f32_16x16x32_bf16 v[60:63], v[128:131], v[160:163], v[60:63]
	v_mfma_f32_16x16x32_bf16 v[56:59], v[136:139], v[160:163], v[56:59]
	v_mfma_f32_16x16x32_bf16 v[48:51], v[128:131], v[168:171], v[48:51]
	v_mfma_f32_16x16x32_bf16 v[40:43], v[136:139], v[168:171], v[40:43]
	v_mfma_f32_16x16x32_bf16 v[32:35], v[128:131], v[176:179], v[32:35]
	v_mfma_f32_16x16x32_bf16 v[24:27], v[136:139], v[176:179], v[24:27]
	v_mfma_f32_16x16x32_bf16 v[16:19], v[128:131], v[184:187], v[16:19]
	v_mfma_f32_16x16x32_bf16 v[8:11], v[136:139], v[184:187], v[8:11]
	v_mfma_f32_16x16x32_bf16 v[60:63], v[132:135], v[164:167], v[60:63]
	v_mfma_f32_16x16x32_bf16 v[56:59], v[140:143], v[164:167], v[56:59]
	v_mfma_f32_16x16x32_bf16 v[48:51], v[132:135], v[172:175], v[48:51]
	v_mfma_f32_16x16x32_bf16 v[40:43], v[140:143], v[172:175], v[40:43]
	v_mfma_f32_16x16x32_bf16 v[32:35], v[132:135], v[180:183], v[32:35]
	v_mfma_f32_16x16x32_bf16 v[24:27], v[140:143], v[180:183], v[24:27]
	v_mfma_f32_16x16x32_bf16 v[16:19], v[132:135], v[188:191], v[16:19]
	v_mfma_f32_16x16x32_bf16 v[8:11], v[140:143], v[188:191], v[8:11]
	v_mfma_f32_16x16x32_bf16 v[52:55], v[144:147], v[160:163], v[52:55]
	v_mfma_f32_16x16x32_bf16 v[44:47], v[152:155], v[160:163], v[44:47]
	v_mfma_f32_16x16x32_bf16 v[36:39], v[144:147], v[168:171], v[36:39]
	v_mfma_f32_16x16x32_bf16 v[28:31], v[152:155], v[168:171], v[28:31]
	v_mfma_f32_16x16x32_bf16 v[20:23], v[144:147], v[176:179], v[20:23]
	v_mfma_f32_16x16x32_bf16 v[12:15], v[152:155], v[176:179], v[12:15]
	v_mfma_f32_16x16x32_bf16 v[4:7], v[144:147], v[184:187], v[4:7]
	v_mfma_f32_16x16x32_bf16 v[0:3], v[152:155], v[184:187], v[0:3]
	v_mfma_f32_16x16x32_bf16 v[52:55], v[148:151], v[164:167], v[52:55]
	v_mfma_f32_16x16x32_bf16 v[44:47], v[156:159], v[164:167], v[44:47]
	v_mfma_f32_16x16x32_bf16 v[36:39], v[148:151], v[172:175], v[36:39]
	v_mfma_f32_16x16x32_bf16 v[28:31], v[156:159], v[172:175], v[28:31]
	v_mfma_f32_16x16x32_bf16 v[20:23], v[148:151], v[180:183], v[20:23]
	v_mfma_f32_16x16x32_bf16 v[12:15], v[156:159], v[180:183], v[12:15]
	v_mfma_f32_16x16x32_bf16 v[4:7], v[148:151], v[188:191], v[4:7]
	v_mfma_f32_16x16x32_bf16 v[0:3], v[156:159], v[188:191], v[0:3]
	s_barrier
	s_add_i32 s39, s39, 2
	s_add_u32 s37, s37, 0x100
	s_addc_u32 s38, s38, 0
	s_cmp_gt_u32 s39, 41
	s_mov_b64 s[12:13], s[14:15]
	s_cbranch_scc0 .LBB0_1252
	s_and_b64 vcc, exec, s[8:9]
	s_cbranch_vccz .LBB0_1255
	s_barrier
.LBB0_1255:
	v_lshl_add_u32 v246, s36, 8, v241
	v_lshl_or_b32 v230, s35, 8, v243
	v_ashrrev_i32_e32 v231, 31, v230
	v_ashrrev_i32_e32 v247, 31, v246
	v_lshl_add_u64 v[128:129], v[230:231], 1, s[6:7]
	v_lshlrev_b64 v[130:131], 11, v[246:247]
	v_lshl_add_u64 v[130:131], v[128:129], 0, v[130:131]
	global_load_dwordx4 v[188:191], v[130:131], off
	global_load_dwordx4 v[184:187], v[130:131], off offset:256
	v_or_b32_e32 v228, 16, v246
	v_ashrrev_i32_e32 v229, 31, v228
	v_lshlrev_b64 v[130:131], 11, v[228:229]
	v_lshl_add_u64 v[130:131], v[128:129], 0, v[130:131]
	global_load_dwordx4 v[180:183], v[130:131], off
	global_load_dwordx4 v[176:179], v[130:131], off offset:256
	v_or_b32_e32 v226, 32, v246
	v_ashrrev_i32_e32 v227, 31, v226
	v_lshlrev_b64 v[130:131], 11, v[226:227]
	v_lshl_add_u64 v[130:131], v[128:129], 0, v[130:131]
	global_load_dwordx4 v[172:175], v[130:131], off
	global_load_dwordx4 v[168:171], v[130:131], off offset:256
	v_or_b32_e32 v224, 48, v246
	v_ashrrev_i32_e32 v225, 31, v224
	v_lshlrev_b64 v[130:131], 11, v[224:225]
	v_lshl_add_u64 v[130:131], v[128:129], 0, v[130:131]
	global_load_dwordx4 v[164:167], v[130:131], off
	global_load_dwordx4 v[160:163], v[130:131], off offset:256
	v_add_u32_e32 v222, 0x80, v246
	v_ashrrev_i32_e32 v223, 31, v222
	v_lshlrev_b64 v[130:131], 11, v[222:223]
	v_lshl_add_u64 v[130:131], v[128:129], 0, v[130:131]
	global_load_dwordx4 v[156:159], v[130:131], off
	global_load_dwordx4 v[152:155], v[130:131], off offset:256
	v_add_u32_e32 v220, 0x90, v246
	v_ashrrev_i32_e32 v221, 31, v220
	v_lshlrev_b64 v[130:131], 11, v[220:221]
	v_lshl_add_u64 v[130:131], v[128:129], 0, v[130:131]
	global_load_dwordx4 v[148:151], v[130:131], off
	global_load_dwordx4 v[144:147], v[130:131], off offset:256
	v_add_u32_e32 v218, 0xa0, v246
	v_ashrrev_i32_e32 v219, 31, v218
	v_lshlrev_b64 v[130:131], 11, v[218:219]
	v_lshl_add_u64 v[130:131], v[128:129], 0, v[130:131]
	global_load_dwordx4 v[140:143], v[130:131], off
	global_load_dwordx4 v[132:135], v[130:131], off offset:256
	v_add_u32_e32 v216, 0xb0, v246
	v_ashrrev_i32_e32 v217, 31, v216
	v_lshlrev_b64 v[250:251], 12, v[246:247]
	s_mov_b32 s12, 0x3fb504f3
	v_lshlrev_b64 v[130:131], 11, v[216:217]
	v_lshl_add_u64 v[128:129], v[128:129], 0, v[130:131]
	global_load_dwordx4 v[136:139], v[128:129], off
	s_nop 0
	global_load_dwordx4 v[128:131], v[128:129], off offset:256
	s_and_b64 vcc, exec, s[40:41]
	s_waitcnt vmcnt(0)
;     DI void operator()(const pg8::f32x4 (&acc)[2][2][4][2], const pg8::Unit& u, int wr, int wc, int fr, int fq) const {
;     ...
; #pragma unroll
;         for (int ai = 0; ai < 2; ++ai)
; #pragma unroll
;             for (int m = 0; m < 4; ++m) { const size_t off = (size_t)(row0 + ai * 128 + m * 16) * D + col0;
; #pragma unroll
;                 for (int bj = 0; bj < 2; ++bj) { const v4u q = rb[ai][m][bj]; const float r8[8] = {bflo(q.x), bfhi(q.x), bflo(q.y), bfhi(q.y), bflo(q.z), bfhi(q.z), bflo(q.w), bfhi(q.w)};
; #pragma unroll
;                     for (int n = 0; n < 2; ++n) { const pg8::f32x4 a = acc[ai][bj][m][n];
;                         f32x4 o; o[0] = ALPHA * r8[4 * n] + a[0]; o[1] = ALPHA * r8[4 * n + 1] + a[1]; o[2] = ALPHA * r8[4 * n + 2] + a[2]; o[3] = ALPHA * r8[4 * n + 3] + a[3];
;                         *(f32x4*)(out + off + bj * 128 + 4 * n) = o; } } }
	v_lshlrev_b32_e32 v246, 16, v188
	v_and_b32_e32 v247, 0xffff0000, v188
	v_pk_fma_f32 v[246:247], v[246:247], s[12:13], v[124:125] op_sel_hi:[1,0,1]
	v_lshlrev_b32_e32 v124, 16, v189
	v_and_b32_e32 v125, 0xffff0000, v189
	v_lshlrev_b32_e32 v188, 16, v190
	v_and_b32_e32 v189, 0xffff0000, v190
	v_pk_fma_f32 v[248:249], v[124:125], s[12:13], v[126:127] op_sel_hi:[1,0,1]
	v_lshl_add_u64 v[126:127], s[4:5], 0, v[250:251]
	v_lshlrev_b64 v[124:125], 2, v[230:231]
	v_pk_fma_f32 v[120:121], v[188:189], s[12:13], v[120:121] op_sel_hi:[1,0,1]
	v_lshlrev_b32_e32 v188, 16, v191
	v_and_b32_e32 v189, 0xffff0000, v191
	v_lshl_add_u64 v[126:127], v[126:127], 0, v[124:125]
	v_pk_fma_f32 v[122:123], v[188:189], s[12:13], v[122:123] op_sel_hi:[1,0,1]
	global_store_dwordx4 v[126:127], v[120:123], off offset:16
	global_store_dwordx4 v[126:127], v[246:249], off
	s_nop 0
	v_lshlrev_b32_e32 v120, 16, v184
	v_and_b32_e32 v121, 0xffff0000, v184
	v_pk_fma_f32 v[116:117], v[120:121], s[12:13], v[116:117] op_sel_hi:[1,0,1]
	v_lshlrev_b32_e32 v120, 16, v185
	v_and_b32_e32 v121, 0xffff0000, v185
	v_pk_fma_f32 v[118:119], v[120:121], s[12:13], v[118:119] op_sel_hi:[1,0,1]
	global_store_dwordx4 v[126:127], v[116:119], off offset:512
	s_nop 1
	v_lshlrev_b32_e32 v116, 16, v186
	v_and_b32_e32 v117, 0xffff0000, v186
	v_pk_fma_f32 v[112:113], v[116:117], s[12:13], v[112:113] op_sel_hi:[1,0,1]
	v_lshlrev_b32_e32 v116, 16, v187
	v_and_b32_e32 v117, 0xffff0000, v187
	v_pk_fma_f32 v[114:115], v[116:117], s[12:13], v[114:115] op_sel_hi:[1,0,1]
	global_store_dwordx4 v[126:127], v[112:115], off offset:528
	s_nop 1
	v_lshlrev_b64 v[112:113], 12, v[228:229]
	v_lshlrev_b32_e32 v114, 16, v180
	v_and_b32_e32 v115, 0xffff0000, v180
	v_pk_fma_f32 v[108:109], v[114:115], s[12:13], v[108:109] op_sel_hi:[1,0,1]
	v_lshlrev_b32_e32 v114, 16, v181
	v_and_b32_e32 v115, 0xffff0000, v181
	v_lshl_add_u64 v[112:113], s[4:5], 0, v[112:113]
	v_pk_fma_f32 v[110:111], v[114:115], s[12:13], v[110:111] op_sel_hi:[1,0,1]
	v_lshl_add_u64 v[112:113], v[112:113], 0, v[124:125]
	global_store_dwordx4 v[112:113], v[108:111], off
	s_nop 1
	v_lshlrev_b32_e32 v108, 16, v182
	v_and_b32_e32 v109, 0xffff0000, v182
	v_pk_fma_f32 v[104:105], v[108:109], s[12:13], v[104:105] op_sel_hi:[1,0,1]
	v_lshlrev_b32_e32 v108, 16, v183
	v_and_b32_e32 v109, 0xffff0000, v183
	v_pk_fma_f32 v[106:107], v[108:109], s[12:13], v[106:107] op_sel_hi:[1,0,1]
	global_store_dwordx4 v[112:113], v[104:107], off offset:16
	s_nop 1
	v_lshlrev_b32_e32 v104, 16, v176
	v_and_b32_e32 v105, 0xffff0000, v176
	v_pk_fma_f32 v[100:101], v[104:105], s[12:13], v[100:101] op_sel_hi:[1,0,1]
	v_lshlrev_b32_e32 v104, 16, v177
	v_and_b32_e32 v105, 0xffff0000, v177
	v_pk_fma_f32 v[102:103], v[104:105], s[12:13], v[102:103] op_sel_hi:[1,0,1]
	global_store_dwordx4 v[112:113], v[100:103], off offset:512
	s_nop 1
	v_lshlrev_b32_e32 v100, 16, v178
	v_and_b32_e32 v101, 0xffff0000, v178
	v_pk_fma_f32 v[92:93], v[100:101], s[12:13], v[92:93] op_sel_hi:[1,0,1]
	v_lshlrev_b32_e32 v100, 16, v179
	v_and_b32_e32 v101, 0xffff0000, v179
	v_pk_fma_f32 v[94:95], v[100:101], s[12:13], v[94:95] op_sel_hi:[1,0,1]
	global_store_dwordx4 v[112:113], v[92:95], off offset:528
	v_lshlrev_b64 v[100:101], 12, v[226:227]
	s_nop 0
	v_lshlrev_b32_e32 v92, 16, v172
	v_and_b32_e32 v93, 0xffff0000, v172
	v_pk_fma_f32 v[92:93], v[92:93], s[12:13], v[96:97] op_sel_hi:[1,0,1]
	v_lshlrev_b32_e32 v94, 16, v173
	v_and_b32_e32 v95, 0xffff0000, v173
	v_lshl_add_u64 v[96:97], s[4:5], 0, v[100:101]
	v_pk_fma_f32 v[94:95], v[94:95], s[12:13], v[98:99] op_sel_hi:[1,0,1]
	v_lshl_add_u64 v[96:97], v[96:97], 0, v[124:125]
	global_store_dwordx4 v[96:97], v[92:95], off
	s_nop 1
	v_lshlrev_b32_e32 v92, 16, v174
	v_and_b32_e32 v93, 0xffff0000, v174
	v_pk_fma_f32 v[88:89], v[92:93], s[12:13], v[88:89] op_sel_hi:[1,0,1]
	v_lshlrev_b32_e32 v92, 16, v175
	v_and_b32_e32 v93, 0xffff0000, v175
	v_pk_fma_f32 v[90:91], v[92:93], s[12:13], v[90:91] op_sel_hi:[1,0,1]
	global_store_dwordx4 v[96:97], v[88:91], off offset:16
	s_nop 1
	v_lshlrev_b32_e32 v88, 16, v168
	v_and_b32_e32 v89, 0xffff0000, v168
	v_pk_fma_f32 v[84:85], v[88:89], s[12:13], v[84:85] op_sel_hi:[1,0,1]
	v_lshlrev_b32_e32 v88, 16, v169
	v_and_b32_e32 v89, 0xffff0000, v169
	v_pk_fma_f32 v[86:87], v[88:89], s[12:13], v[86:87] op_sel_hi:[1,0,1]
	global_store_dwordx4 v[96:97], v[84:87], off offset:512
	s_nop 1
	v_lshlrev_b32_e32 v84, 16, v170
	v_and_b32_e32 v85, 0xffff0000, v170
	v_pk_fma_f32 v[76:77], v[84:85], s[12:13], v[76:77] op_sel_hi:[1,0,1]
	v_lshlrev_b32_e32 v84, 16, v171
	v_and_b32_e32 v85, 0xffff0000, v171
	v_pk_fma_f32 v[78:79], v[84:85], s[12:13], v[78:79] op_sel_hi:[1,0,1]
	global_store_dwordx4 v[96:97], v[76:79], off offset:528
	v_lshlrev_b64 v[84:85], 12, v[224:225]
	s_nop 0
	v_lshlrev_b32_e32 v76, 16, v164
	v_and_b32_e32 v77, 0xffff0000, v164
	v_pk_fma_f32 v[76:77], v[76:77], s[12:13], v[80:81] op_sel_hi:[1,0,1]
	v_lshlrev_b32_e32 v78, 16, v165
	v_and_b32_e32 v79, 0xffff0000, v165
	v_lshl_add_u64 v[80:81], s[4:5], 0, v[84:85]
	v_pk_fma_f32 v[78:79], v[78:79], s[12:13], v[82:83] op_sel_hi:[1,0,1]
	v_lshl_add_u64 v[80:81], v[80:81], 0, v[124:125]
	global_store_dwordx4 v[80:81], v[76:79], off
	s_nop 1
	v_lshlrev_b32_e32 v76, 16, v166
	v_and_b32_e32 v77, 0xffff0000, v166
	v_pk_fma_f32 v[72:73], v[76:77], s[12:13], v[72:73] op_sel_hi:[1,0,1]
	v_lshlrev_b32_e32 v76, 16, v167
	v_and_b32_e32 v77, 0xffff0000, v167
	v_pk_fma_f32 v[74:75], v[76:77], s[12:13], v[74:75] op_sel_hi:[1,0,1]
	global_store_dwordx4 v[80:81], v[72:75], off offset:16
	s_nop 1
	v_lshlrev_b32_e32 v72, 16, v160
	v_and_b32_e32 v73, 0xffff0000, v160
	v_pk_fma_f32 v[68:69], v[72:73], s[12:13], v[68:69] op_sel_hi:[1,0,1]
;     DI void operator()(const pg8::f32x4 (&acc)[2][2][4][2], const pg8::Unit& u, int wr, int wc, int fr, int fq) const {
;     ...
; #pragma unroll
;         for (int ai = 0; ai < 2; ++ai)
; #pragma unroll
;             for (int m = 0; m < 4; ++m) { const size_t off = (size_t)(row0 + ai * 128 + m * 16) * D + col0;
; #pragma unroll
;                 for (int bj = 0; bj < 2; ++bj) { const v4u q = rb[ai][m][bj]; const float r8[8] = {bflo(q.x), bfhi(q.x), bflo(q.y), bfhi(q.y), bflo(q.z), bfhi(q.z), bflo(q.w), bfhi(q.w)};
; #pragma unroll
;                     for (int n = 0; n < 2; ++n) { const pg8::f32x4 a = acc[ai][bj][m][n];
;                         f32x4 o; o[0] = ALPHA * r8[4 * n] + a[0]; o[1] = ALPHA * r8[4 * n + 1] + a[1]; o[2] = ALPHA * r8[4 * n + 2] + a[2]; o[3] = ALPHA * r8[4 * n + 3] + a[3];
;                         *(f32x4*)(out + off + bj * 128 + 4 * n) = o; } } }
	v_lshlrev_b32_e32 v72, 16, v161
	v_and_b32_e32 v73, 0xffff0000, v161
	v_pk_fma_f32 v[70:71], v[72:73], s[12:13], v[70:71] op_sel_hi:[1,0,1]
	global_store_dwordx4 v[80:81], v[68:71], off offset:512
	s_nop 1
	v_lshlrev_b32_e32 v68, 16, v162
	v_and_b32_e32 v69, 0xffff0000, v162
	v_pk_fma_f32 v[64:65], v[68:69], s[12:13], v[64:65] op_sel_hi:[1,0,1]
	v_lshlrev_b32_e32 v68, 16, v163
	v_and_b32_e32 v69, 0xffff0000, v163
	v_pk_fma_f32 v[66:67], v[68:69], s[12:13], v[66:67] op_sel_hi:[1,0,1]
	global_store_dwordx4 v[80:81], v[64:67], off offset:528
	s_nop 1
	v_lshlrev_b64 v[64:65], 12, v[222:223]
	v_lshlrev_b32_e32 v66, 16, v156
	v_and_b32_e32 v67, 0xffff0000, v156
	v_pk_fma_f32 v[60:61], v[66:67], s[12:13], v[60:61] op_sel_hi:[1,0,1]
	v_lshlrev_b32_e32 v66, 16, v157
	v_and_b32_e32 v67, 0xffff0000, v157
	v_lshl_add_u64 v[64:65], s[4:5], 0, v[64:65]
	v_pk_fma_f32 v[62:63], v[66:67], s[12:13], v[62:63] op_sel_hi:[1,0,1]
	v_lshl_add_u64 v[64:65], v[64:65], 0, v[124:125]
	global_store_dwordx4 v[64:65], v[60:63], off
	s_nop 1
	v_lshlrev_b32_e32 v60, 16, v158
	v_and_b32_e32 v61, 0xffff0000, v158
	v_pk_fma_f32 v[56:57], v[60:61], s[12:13], v[56:57] op_sel_hi:[1,0,1]
	v_lshlrev_b32_e32 v60, 16, v159
	v_and_b32_e32 v61, 0xffff0000, v159
	v_pk_fma_f32 v[58:59], v[60:61], s[12:13], v[58:59] op_sel_hi:[1,0,1]
	global_store_dwordx4 v[64:65], v[56:59], off offset:16
	s_nop 1
	v_lshlrev_b32_e32 v56, 16, v152
	v_and_b32_e32 v57, 0xffff0000, v152
	v_pk_fma_f32 v[52:53], v[56:57], s[12:13], v[52:53] op_sel_hi:[1,0,1]
	v_lshlrev_b32_e32 v56, 16, v153
	v_and_b32_e32 v57, 0xffff0000, v153
	v_pk_fma_f32 v[54:55], v[56:57], s[12:13], v[54:55] op_sel_hi:[1,0,1]
	global_store_dwordx4 v[64:65], v[52:55], off offset:512
	s_nop 1
	v_lshlrev_b32_e32 v52, 16, v154
	v_and_b32_e32 v53, 0xffff0000, v154
	v_pk_fma_f32 v[44:45], v[52:53], s[12:13], v[44:45] op_sel_hi:[1,0,1]
	v_lshlrev_b32_e32 v52, 16, v155
	v_and_b32_e32 v53, 0xffff0000, v155
	v_pk_fma_f32 v[46:47], v[52:53], s[12:13], v[46:47] op_sel_hi:[1,0,1]
	global_store_dwordx4 v[64:65], v[44:47], off offset:528
	v_lshlrev_b64 v[52:53], 12, v[220:221]
	s_nop 0
	v_lshlrev_b32_e32 v44, 16, v148
	v_and_b32_e32 v45, 0xffff0000, v148
	v_pk_fma_f32 v[44:45], v[44:45], s[12:13], v[48:49] op_sel_hi:[1,0,1]
	v_lshlrev_b32_e32 v46, 16, v149
	v_and_b32_e32 v47, 0xffff0000, v149
	v_lshl_add_u64 v[48:49], s[4:5], 0, v[52:53]
	v_pk_fma_f32 v[46:47], v[46:47], s[12:13], v[50:51] op_sel_hi:[1,0,1]
	v_lshl_add_u64 v[48:49], v[48:49], 0, v[124:125]
	global_store_dwordx4 v[48:49], v[44:47], off
	s_nop 1
	v_lshlrev_b32_e32 v44, 16, v150
	v_and_b32_e32 v45, 0xffff0000, v150
	v_pk_fma_f32 v[40:41], v[44:45], s[12:13], v[40:41] op_sel_hi:[1,0,1]
	v_lshlrev_b32_e32 v44, 16, v151
	v_and_b32_e32 v45, 0xffff0000, v151
	v_pk_fma_f32 v[42:43], v[44:45], s[12:13], v[42:43] op_sel_hi:[1,0,1]
	global_store_dwordx4 v[48:49], v[40:43], off offset:16
	s_nop 1
	v_lshlrev_b32_e32 v40, 16, v144
	v_and_b32_e32 v41, 0xffff0000, v144
	v_pk_fma_f32 v[36:37], v[40:41], s[12:13], v[36:37] op_sel_hi:[1,0,1]
	v_lshlrev_b32_e32 v40, 16, v145
	v_and_b32_e32 v41, 0xffff0000, v145
	v_pk_fma_f32 v[38:39], v[40:41], s[12:13], v[38:39] op_sel_hi:[1,0,1]
	global_store_dwordx4 v[48:49], v[36:39], off offset:512
	s_nop 1
	v_lshlrev_b32_e32 v36, 16, v146
	v_and_b32_e32 v37, 0xffff0000, v146
	v_pk_fma_f32 v[28:29], v[36:37], s[12:13], v[28:29] op_sel_hi:[1,0,1]
	v_lshlrev_b32_e32 v36, 16, v147
	v_and_b32_e32 v37, 0xffff0000, v147
	v_pk_fma_f32 v[30:31], v[36:37], s[12:13], v[30:31] op_sel_hi:[1,0,1]
	global_store_dwordx4 v[48:49], v[28:31], off offset:528
	v_lshlrev_b64 v[36:37], 12, v[218:219]
	s_nop 0
	v_lshlrev_b32_e32 v28, 16, v140
	v_and_b32_e32 v29, 0xffff0000, v140
	v_pk_fma_f32 v[28:29], v[28:29], s[12:13], v[32:33] op_sel_hi:[1,0,1]
	v_lshlrev_b32_e32 v30, 16, v141
	v_and_b32_e32 v31, 0xffff0000, v141
	v_lshl_add_u64 v[32:33], s[4:5], 0, v[36:37]
	v_pk_fma_f32 v[30:31], v[30:31], s[12:13], v[34:35] op_sel_hi:[1,0,1]
	v_lshl_add_u64 v[32:33], v[32:33], 0, v[124:125]
	global_store_dwordx4 v[32:33], v[28:31], off
	s_nop 1
	v_lshlrev_b32_e32 v28, 16, v142
	v_and_b32_e32 v29, 0xffff0000, v142
	v_pk_fma_f32 v[24:25], v[28:29], s[12:13], v[24:25] op_sel_hi:[1,0,1]
	v_lshlrev_b32_e32 v28, 16, v143
	v_and_b32_e32 v29, 0xffff0000, v143
	v_pk_fma_f32 v[26:27], v[28:29], s[12:13], v[26:27] op_sel_hi:[1,0,1]
	global_store_dwordx4 v[32:33], v[24:27], off offset:16
	s_nop 1
	v_lshlrev_b32_e32 v24, 16, v132
	v_and_b32_e32 v25, 0xffff0000, v132
	v_pk_fma_f32 v[20:21], v[24:25], s[12:13], v[20:21] op_sel_hi:[1,0,1]
	v_lshlrev_b32_e32 v24, 16, v133
	v_and_b32_e32 v25, 0xffff0000, v133
	v_pk_fma_f32 v[22:23], v[24:25], s[12:13], v[22:23] op_sel_hi:[1,0,1]
	global_store_dwordx4 v[32:33], v[20:23], off offset:512
	s_nop 1
	v_lshlrev_b32_e32 v20, 16, v134
	v_and_b32_e32 v21, 0xffff0000, v134
	v_pk_fma_f32 v[12:13], v[20:21], s[12:13], v[12:13] op_sel_hi:[1,0,1]
	v_lshlrev_b32_e32 v20, 16, v135
	v_and_b32_e32 v21, 0xffff0000, v135
	v_pk_fma_f32 v[14:15], v[20:21], s[12:13], v[14:15] op_sel_hi:[1,0,1]
	global_store_dwordx4 v[32:33], v[12:15], off offset:528
	v_lshlrev_b64 v[20:21], 12, v[216:217]
	s_nop 0
	v_lshlrev_b32_e32 v12, 16, v136
	v_and_b32_e32 v13, 0xffff0000, v136
	v_pk_fma_f32 v[12:13], v[12:13], s[12:13], v[16:17] op_sel_hi:[1,0,1]
	v_lshlrev_b32_e32 v14, 16, v137
	v_and_b32_e32 v15, 0xffff0000, v137
	v_lshl_add_u64 v[16:17], s[4:5], 0, v[20:21]
	v_pk_fma_f32 v[14:15], v[14:15], s[12:13], v[18:19] op_sel_hi:[1,0,1]
	v_lshl_add_u64 v[16:17], v[16:17], 0, v[124:125]
	global_store_dwordx4 v[16:17], v[12:15], off
	s_nop 1
	v_lshlrev_b32_e32 v12, 16, v138
	v_and_b32_e32 v13, 0xffff0000, v138
	v_pk_fma_f32 v[8:9], v[12:13], s[12:13], v[8:9] op_sel_hi:[1,0,1]
	v_lshlrev_b32_e32 v12, 16, v139
	v_and_b32_e32 v13, 0xffff0000, v139
	v_pk_fma_f32 v[10:11], v[12:13], s[12:13], v[10:11] op_sel_hi:[1,0,1]
	global_store_dwordx4 v[16:17], v[8:11], off offset:16
	s_nop 1
	v_lshlrev_b32_e32 v8, 16, v128
	v_and_b32_e32 v9, 0xffff0000, v128
	v_pk_fma_f32 v[4:5], v[8:9], s[12:13], v[4:5] op_sel_hi:[1,0,1]
	v_lshlrev_b32_e32 v8, 16, v129
	v_and_b32_e32 v9, 0xffff0000, v129
	v_pk_fma_f32 v[6:7], v[8:9], s[12:13], v[6:7] op_sel_hi:[1,0,1]
	global_store_dwordx4 v[16:17], v[4:7], off offset:512
	s_nop 1
	v_lshlrev_b32_e32 v4, 16, v130
	v_and_b32_e32 v5, 0xffff0000, v130
	v_pk_fma_f32 v[0:1], v[4:5], s[12:13], v[0:1] op_sel_hi:[1,0,1]
	v_lshlrev_b32_e32 v4, 16, v131
	v_and_b32_e32 v5, 0xffff0000, v131
	v_pk_fma_f32 v[2:3], v[4:5], s[12:13], v[2:3] op_sel_hi:[1,0,1]
	s_mov_b64 s[12:13], -1
	global_store_dwordx4 v[16:17], v[0:3], off offset:528
	s_cbranch_vccnz .LBB0_1240
	s_andn2_b64 vcc, exec, s[2:3]
	s_cbranch_vccnz .LBB0_1239
	s_barrier
	s_branch .LBB0_1239
; #define PG8_WAIT_V(n) asm volatile("s_waitcnt vmcnt(" #n ")" ::: "memory")
; #define PG8_BAR __builtin_amdgcn_s_barrier()
; template <class Epi, class Sched, bool ALIGN_EPI = false, bool SP2 = false>
; __device__ __forceinline__ void gemm_phase(PG8_LAS unsigned char* lds, const Gemm g, const Sched& S, const Epi& E) {
;     ...
;     PG8_WAIT_V(0);
;     if constexpr (!ALIGN_EPI) { if (wr == 0) PG8_BAR; }
;     PG8_BAR;
; __device__ __forceinline__ void xcd_barrier(const XcdBarrier& b) {
;     asm volatile("s_waitcnt vmcnt(0)" ::: "memory");
;     __syncthreads();
;     if (threadIdx.x == 0) {
;         unsigned* bar = b.bar;
;         __builtin_amdgcn_s_waitcnt(0);
;         unsigned nloc = b.st[0], nx = b.st[1];
;         if (nloc == 0u) { xcd_barrier_complete(bar, b.x, nloc, nx); b.st[0] = nloc; b.st[1] = nx; }
.LBB0_1258:
	s_setprio 0
	s_waitcnt vmcnt(0)
	s_barrier
.LBB0_1259:
	s_waitcnt vmcnt(0)
	s_barrier
	s_mov_b64 s[0:1], exec
	v_readlane_b32 s2, v252, 4
	v_readlane_b32 s3, v252, 5
	s_and_b64 s[2:3], s[0:1], s[2:3]
	s_mov_b64 exec, s[2:3]
	s_cbranch_execz .LBB0_1311
	v_readlane_b32 s2, v254, 4
	s_waitcnt vmcnt(0) expcnt(0) lgkmcnt(0)
	s_nop 0
	v_mov_b32_e32 v0, s2
	ds_read_b32 v2, v0
	v_readlane_b32 s2, v254, 5
	s_waitcnt lgkmcnt(0)
	v_cmp_ne_u32_e32 vcc, 0, v2
	v_mov_b32_e32 v0, s2
	ds_read_b32 v0, v0
	s_cbranch_vccnz .LBB0_1275
	s_mov_b32 s8, 1
	s_branch .LBB0_1263
